# write-through (sc1) stores also in the up-projection, attention-output, final-norm and ph0 weight-transpose epilogues (none waits on its own stores); on top of v56
# speedup vs baseline: 1.0086x; 1.0023x over previous
.LBB0_35:
	s_lshl_b32 s7, s4, 1
	s_lshl_b32 s6, s3, 1
	v_or_b32_e32 v75, s7, v54
	s_add_i32 s27, s7, 4
	v_or_b32_e32 v73, s6, v17
	s_add_i32 s26, s6, 4
	s_add_i32 s72, s7, 8
	v_add_lshl_u32 v18, v75, s1, 11
	v_or_b32_e32 v79, s27, v54
	v_mov_b32_e32 v3, v19
	s_add_i32 s74, s7, 12
	v_add_lshl_u32 v2, v73, s2, 11
	v_or_b32_e32 v77, s26, v17
	v_or_b32_e32 v114, s72, v54
	v_lshl_add_u64 v[90:91], v[18:19], 2, v[0:1]
	v_add_lshl_u32 v18, v79, s1, 11
	v_mov_b32_e32 v5, v19
	s_add_i32 s71, s6, 8
	s_add_i32 s73, s6, 12
	s_add_i32 s76, s7, 16
	v_or_b32_e32 v116, s74, v54
	v_lshl_add_u64 v[2:3], v[2:3], 2, v[0:1]
	v_add_lshl_u32 v4, v77, s2, 11
	v_lshl_add_u64 v[112:113], v[18:19], 2, v[0:1]
	v_add_lshl_u32 v18, v114, s1, 11
	s_add_i32 s78, s7, 20
	v_or_b32_e32 v111, s71, v17
	v_or_b32_e32 v115, s73, v17
	v_or_b32_e32 v118, s76, v54
	v_lshl_add_u64 v[4:5], v[4:5], 2, v[0:1]
	global_load_dword v126, v[90:91], off nt
	global_load_dword v127, v[2:3], off nt
	global_load_dword v128, v[112:113], off nt
	global_load_dword v129, v[4:5], off nt
	v_lshl_add_u64 v[2:3], v[18:19], 2, v[0:1]
	v_add_lshl_u32 v18, v116, s1, 11
	v_mov_b32_e32 v7, v19
	v_mov_b32_e32 v9, v19
	s_add_i32 s75, s6, 16
	s_add_i32 s77, s6, 20
	s_add_i32 s80, s7, 24
	v_or_b32_e32 v120, s78, v54
	v_add_lshl_u32 v6, v111, s2, 11
	v_add_lshl_u32 v8, v115, s2, 11
	v_lshl_add_u64 v[4:5], v[18:19], 2, v[0:1]
	v_add_lshl_u32 v18, v118, s1, 11
	s_add_i32 s79, s6, 24
	s_add_i32 s6, s6, 28
	s_add_i32 s7, s7, 28
	v_or_b32_e32 v117, s75, v17
	v_or_b32_e32 v119, s77, v17
	v_or_b32_e32 v122, s80, v54
	v_lshl_add_u64 v[6:7], v[6:7], 2, v[0:1]
	v_lshl_add_u64 v[8:9], v[8:9], 2, v[0:1]
	global_load_dword v130, v[2:3], off nt
	global_load_dword v131, v[6:7], off nt
	global_load_dword v132, v[4:5], off nt
	global_load_dword v133, v[8:9], off nt
	v_lshl_add_u64 v[2:3], v[18:19], 2, v[0:1]
	v_add_lshl_u32 v18, v120, s1, 11
	v_mov_b32_e32 v11, v19
	v_mov_b32_e32 v13, v19
	v_or_b32_e32 v121, s79, v17
	v_or_b32_e32 v124, s6, v17
	v_or_b32_e32 v123, s7, v54
	v_add_lshl_u32 v10, v117, s2, 11
	v_add_lshl_u32 v12, v119, s2, 11
	v_lshl_add_u64 v[4:5], v[18:19], 2, v[0:1]
	v_add_lshl_u32 v18, v122, s1, 11
	v_mov_b32_e32 v15, v19
	v_mov_b32_e32 v89, v19
	v_add_lshl_u32 v14, v121, s2, 11
	v_add_lshl_u32 v88, v124, s2, 11
	v_lshl_add_u64 v[10:11], v[10:11], 2, v[0:1]
	v_lshl_add_u64 v[12:13], v[12:13], 2, v[0:1]
	global_load_dword v134, v[2:3], off nt
	global_load_dword v135, v[10:11], off nt
	global_load_dword v136, v[4:5], off nt
	global_load_dword v137, v[12:13], off nt
	v_lshl_add_u64 v[2:3], v[18:19], 2, v[0:1]
	v_add_lshl_u32 v18, v123, s1, 11
	v_lshl_add_u64 v[14:15], v[14:15], 2, v[0:1]
	v_lshl_add_u64 v[88:89], v[88:89], 2, v[0:1]
	v_lshl_add_u64 v[4:5], v[18:19], 2, v[0:1]
	global_load_dword v18, v[2:3], off nt
	global_load_dword v138, v[14:15], off nt
	global_load_dword v139, v[4:5], off nt
	global_load_dword v140, v[88:89], off nt
	s_add_i32 s4, s4, 16
	s_add_i32 s3, s3, 16
	s_add_i32 s5, s5, -16
	v_mad_u64_u32 v[2:3], s[6:7], v75, s49, v[56:57]
	s_cmp_lg_u32 s5, 0
	v_mad_u64_u32 v[4:5], s[6:7], v73, s49, v[56:57]
	v_mad_u64_u32 v[6:7], s[6:7], v79, s49, v[56:57]
	v_mad_u64_u32 v[8:9], s[6:7], v77, s49, v[56:57]
	v_mad_u64_u32 v[10:11], s[6:7], v114, s49, v[56:57]
	v_mad_u64_u32 v[12:13], s[6:7], v111, s49, v[56:57]
	v_mad_u64_u32 v[14:15], s[6:7], v116, s49, v[56:57]
	v_mad_u64_u32 v[88:89], s[6:7], v115, s49, v[56:57]
	v_mad_u64_u32 v[90:91], s[6:7], v118, s49, v[56:57]
	v_mad_u64_u32 v[112:113], s[6:7], v117, s49, v[56:57]
	v_mad_u64_u32 v[114:115], s[6:7], v120, s49, v[56:57]
	v_mad_u64_u32 v[116:117], s[6:7], v119, s49, v[56:57]
	v_mad_u64_u32 v[118:119], s[6:7], v122, s49, v[56:57]
	v_mad_u64_u32 v[120:121], s[6:7], v121, s49, v[56:57]
	v_mad_u64_u32 v[122:123], s[6:7], v123, s49, v[56:57]
	v_mad_u64_u32 v[124:125], s[6:7], v124, s49, v[56:57]
	s_waitcnt vmcnt(0)
	ds_write_b32 v2, v126
	ds_write_b32 v4, v127
	ds_write_b32 v6, v128
	ds_write_b32 v8, v129
	ds_write_b32 v10, v130
	ds_write_b32 v12, v131
	ds_write_b32 v14, v132
	ds_write_b32 v88, v133
	ds_write_b32 v90, v134
	ds_write_b32 v112, v135
	ds_write_b32 v114, v136
	ds_write_b32 v116, v137
	ds_write_b32 v118, v18
	ds_write_b32 v120, v138
	ds_write_b32 v122, v139
	ds_write_b32 v124, v140
	s_cbranch_scc1 .LBB0_35
	s_waitcnt lgkmcnt(0)
	ds_read2_b32 v[4:5], v94 offset1:8
	ds_read2_b32 v[8:9], v94 offset0:33 offset1:41
	ds_read2_b32 v[10:11], v94 offset0:66 offset1:74
	ds_read2_b32 v[12:13], v94 offset0:99 offset1:107
	ds_read2_b32 v[14:15], v94 offset0:132 offset1:140
	s_waitcnt lgkmcnt(0)
	v_bfe_u32 v0, v4, 16, 1
	v_add3_u32 v0, v4, v0, s65
	v_bfe_u32 v1, v8, 16, 1
	v_lshrrev_b32_e32 v0, 16, v0
	v_add3_u32 v1, v8, v1, s65
	ds_read2_b32 v[88:89], v94 offset0:165 offset1:173
	v_and_or_b32 v0, v1, s66, v0
	v_bfe_u32 v1, v10, 16, 1
	v_add3_u32 v1, v10, v1, s65
	v_bfe_u32 v2, v12, 16, 1
	ds_read2_b32 v[90:91], v94 offset0:198 offset1:206
	v_lshrrev_b32_e32 v1, 16, v1
	v_add3_u32 v2, v12, v2, s65
	ds_read2_b32 v[112:113], v94 offset0:231 offset1:239
	v_and_or_b32 v1, v2, s66, v1
	v_bfe_u32 v2, v14, 16, 1
	v_add3_u32 v2, v14, v2, s65
	s_waitcnt lgkmcnt(2)
	v_bfe_u32 v3, v88, 16, 1
	s_lshl_b64 s[2:3], s[24:25], 23
	v_lshrrev_b32_e32 v2, 16, v2
	v_add3_u32 v3, v88, v3, s65
	s_add_u32 s2, s36, s2
	v_and_or_b32 v2, v3, s66, v2
	s_waitcnt lgkmcnt(1)
	v_bfe_u32 v3, v90, 16, 1
	s_addc_u32 s3, s37, s3
	s_lshl_b32 s1, s1, 1
	v_add3_u32 v3, v90, v3, s65
	s_waitcnt lgkmcnt(0)
	v_bfe_u32 v4, v112, 16, 1
	s_add_u32 s2, s2, s1
	v_lshrrev_b32_e32 v3, 16, v3
	v_add3_u32 v4, v112, v4, s65
	s_addc_u32 s3, s3, 0
	v_lshlrev_b32_e32 v18, 1, v24
	v_and_or_b32 v3, v4, s66, v3
	v_or_b32_e32 v4, s0, v25
	v_lshl_add_u64 v[6:7], s[2:3], 0, v[18:19]
	v_lshlrev_b32_e32 v18, 12, v4
	v_lshl_add_u64 v[114:115], v[6:7], 0, v[18:19]
	global_store_dwordx4 v[114:115], v[0:3], off sc1
	v_bfe_u32 v4, v113, 16, 1
	v_or_b32_e32 v8, s0, v33
	v_bfe_u32 v0, v5, 16, 1
	v_add3_u32 v0, v5, v0, s65
	v_bfe_u32 v1, v9, 16, 1
	v_lshrrev_b32_e32 v0, 16, v0
	v_add3_u32 v1, v9, v1, s65
	v_and_or_b32 v0, v1, s66, v0
	v_bfe_u32 v1, v11, 16, 1
	v_add3_u32 v1, v11, v1, s65
	v_bfe_u32 v2, v13, 16, 1
	v_lshrrev_b32_e32 v1, 16, v1
	v_add3_u32 v2, v13, v2, s65
	v_and_or_b32 v1, v2, s66, v1
	v_bfe_u32 v2, v15, 16, 1
	v_add3_u32 v2, v15, v2, s65
	v_bfe_u32 v3, v89, 16, 1
	v_lshrrev_b32_e32 v2, 16, v2
	v_add3_u32 v3, v89, v3, s65
	v_and_or_b32 v2, v3, s66, v2
	v_bfe_u32 v3, v91, 16, 1
	v_add3_u32 v3, v91, v3, s65
	v_lshrrev_b32_e32 v3, 16, v3
	v_add3_u32 v4, v113, v4, s65
	v_lshlrev_b32_e32 v18, 12, v8
	v_and_or_b32 v3, v4, s66, v3
	ds_read2_b32 v[4:5], v94 offset0:16 offset1:24
	v_lshl_add_u64 v[8:9], v[6:7], 0, v[18:19]
	global_store_dwordx4 v[8:9], v[0:3], off sc1
	ds_read2_b32 v[8:9], v94 offset0:49 offset1:57
	ds_read2_b32 v[10:11], v94 offset0:82 offset1:90
	ds_read2_b32 v[12:13], v94 offset0:115 offset1:123
	s_waitcnt lgkmcnt(3)
	v_bfe_u32 v0, v4, 16, 1
	v_add3_u32 v0, v4, v0, s65
	s_waitcnt lgkmcnt(2)
	v_bfe_u32 v1, v8, 16, 1
	ds_read2_b32 v[14:15], v94 offset0:148 offset1:156
	v_lshrrev_b32_e32 v0, 16, v0
	v_add3_u32 v1, v8, v1, s65
	ds_read2_b32 v[88:89], v94 offset0:181 offset1:189
	v_and_or_b32 v0, v1, s66, v0
	s_waitcnt lgkmcnt(3)
	v_bfe_u32 v1, v10, 16, 1
	v_add3_u32 v1, v10, v1, s65
	s_waitcnt lgkmcnt(2)
	v_bfe_u32 v2, v12, 16, 1
	ds_read2_b32 v[90:91], v94 offset0:214 offset1:222
	v_lshrrev_b32_e32 v1, 16, v1
	v_add3_u32 v2, v12, v2, s65
	ds_read2_b32 v[112:113], v94 offset0:247 offset1:255
	v_and_or_b32 v1, v2, s66, v1
	s_waitcnt lgkmcnt(3)
	v_bfe_u32 v2, v14, 16, 1
	v_add3_u32 v2, v14, v2, s65
	s_waitcnt lgkmcnt(2)
	v_bfe_u32 v3, v88, 16, 1
	v_lshrrev_b32_e32 v2, 16, v2
	v_add3_u32 v3, v88, v3, s65
	v_and_or_b32 v2, v3, s66, v2
	s_waitcnt lgkmcnt(1)
	v_bfe_u32 v3, v90, 16, 1
	v_add3_u32 v3, v90, v3, s65
	s_waitcnt lgkmcnt(0)
	v_bfe_u32 v4, v112, 16, 1
	v_lshrrev_b32_e32 v3, 16, v3
	v_add3_u32 v4, v112, v4, s65
	v_and_or_b32 v3, v4, s66, v3
	v_or_b32_e32 v4, s0, v55
	v_lshlrev_b32_e32 v18, 12, v4
	v_lshl_add_u64 v[114:115], v[6:7], 0, v[18:19]
	global_store_dwordx4 v[114:115], v[0:3], off sc1
	v_bfe_u32 v4, v113, 16, 1
	v_add3_u32 v4, v113, v4, s65
	v_bfe_u32 v0, v5, 16, 1
	v_add3_u32 v0, v5, v0, s65
	v_bfe_u32 v1, v9, 16, 1
	v_lshrrev_b32_e32 v0, 16, v0
	v_add3_u32 v1, v9, v1, s65
	v_and_or_b32 v0, v1, s66, v0
	v_bfe_u32 v1, v11, 16, 1
	v_add3_u32 v1, v11, v1, s65
	v_bfe_u32 v2, v13, 16, 1
	v_lshrrev_b32_e32 v1, 16, v1
	v_add3_u32 v2, v13, v2, s65
	v_and_or_b32 v1, v2, s66, v1
	v_bfe_u32 v2, v15, 16, 1
	v_add3_u32 v2, v15, v2, s65
	v_bfe_u32 v3, v89, 16, 1
	v_lshrrev_b32_e32 v2, 16, v2
	v_add3_u32 v3, v89, v3, s65
	v_and_or_b32 v2, v3, s66, v2
	v_bfe_u32 v3, v91, 16, 1
	v_add3_u32 v3, v91, v3, s65
	v_lshrrev_b32_e32 v3, 16, v3
	v_and_or_b32 v3, v4, s66, v3
	v_or_b32_e32 v4, s0, v57
	v_lshlrev_b32_e32 v18, 12, v4
	v_lshl_add_u64 v[4:5], v[6:7], 0, v[18:19]
	global_store_dwordx4 v[4:5], v[0:3], off sc1
	s_waitcnt lgkmcnt(0)

.LBB0_61:
	s_waitcnt lgkmcnt(0)
	ds_read2_b32 v[4:5], v94 offset1:8
	ds_read2_b32 v[8:9], v94 offset0:33 offset1:41
	ds_read2_b32 v[10:11], v94 offset0:66 offset1:74
	ds_read2_b32 v[12:13], v94 offset0:99 offset1:107
	ds_read2_b32 v[14:15], v94 offset0:132 offset1:140
	s_waitcnt lgkmcnt(0)
	v_bfe_u32 v0, v4, 16, 1
	v_add3_u32 v0, v4, v0, s65
	v_bfe_u32 v1, v8, 16, 1
	v_lshrrev_b32_e32 v0, 16, v0
	v_add3_u32 v1, v8, v1, s65
	ds_read2_b32 v[88:89], v94 offset0:165 offset1:173
	v_and_or_b32 v0, v1, s66, v0
	v_bfe_u32 v1, v10, 16, 1
	s_and_b64 s[0:1], s[2:3], exec
	v_add3_u32 v1, v10, v1, s65
	v_bfe_u32 v2, v12, 16, 1
	ds_read2_b32 v[90:91], v94 offset0:198 offset1:206
	s_mov_b32 s0, 0x11d00000
	v_lshrrev_b32_e32 v1, 16, v1
	v_add3_u32 v2, v12, v2, s65
	ds_read2_b32 v[112:113], v94 offset0:231 offset1:239
	s_cselect_b32 s0, s0, 0x12400000
	v_and_or_b32 v1, v2, s66, v1
	v_bfe_u32 v2, v14, 16, 1
	s_cselect_b32 s1, 0x1000, 0
	s_add_u32 s0, s28, s0
	v_add3_u32 v2, v14, v2, s65
	s_waitcnt lgkmcnt(2)
	v_bfe_u32 v3, v88, 16, 1
	s_addc_u32 s2, s29, 0
	s_add_i32 s3, s6, s1
	s_lshl_b32 s1, s7, 1
	v_lshrrev_b32_e32 v2, 16, v2
	v_add3_u32 v3, v88, v3, s65
	s_add_u32 s0, s0, s1
	v_and_or_b32 v2, v3, s66, v2
	s_waitcnt lgkmcnt(1)
	v_bfe_u32 v3, v90, 16, 1
	s_addc_u32 s1, s2, 0
	v_lshlrev_b32_e32 v18, 1, v24
	v_add3_u32 v3, v90, v3, s65
	s_waitcnt lgkmcnt(0)
	v_bfe_u32 v4, v112, 16, 1
	v_lshl_add_u64 v[6:7], s[0:1], 0, v[18:19]
	v_lshrrev_b32_e32 v3, 16, v3
	v_add3_u32 v4, v112, v4, s65
	v_add_lshl_u32 v18, s3, v25, 10
	v_and_or_b32 v3, v4, s66, v3
	v_lshl_add_u64 v[114:115], v[6:7], 0, v[18:19]
	global_store_dwordx4 v[114:115], v[0:3], off sc1
	v_bfe_u32 v4, v113, 16, 1
	v_add3_u32 v4, v113, v4, s65
	v_bfe_u32 v0, v5, 16, 1
	v_add3_u32 v0, v5, v0, s65
	v_bfe_u32 v1, v9, 16, 1
	v_lshrrev_b32_e32 v0, 16, v0
	v_add3_u32 v1, v9, v1, s65
	v_and_or_b32 v0, v1, s66, v0
	v_bfe_u32 v1, v11, 16, 1
	v_add3_u32 v1, v11, v1, s65
	v_bfe_u32 v2, v13, 16, 1
	v_lshrrev_b32_e32 v1, 16, v1
	v_add3_u32 v2, v13, v2, s65
	v_and_or_b32 v1, v2, s66, v1
	v_bfe_u32 v2, v15, 16, 1
	v_add3_u32 v2, v15, v2, s65
	v_bfe_u32 v3, v89, 16, 1
	v_lshrrev_b32_e32 v2, 16, v2
	v_add3_u32 v3, v89, v3, s65
	v_and_or_b32 v2, v3, s66, v2
	v_bfe_u32 v3, v91, 16, 1
	v_add3_u32 v3, v91, v3, s65
	v_lshrrev_b32_e32 v3, 16, v3
	v_add_lshl_u32 v18, s3, v33, 10
	v_and_or_b32 v3, v4, s66, v3
	ds_read2_b32 v[4:5], v94 offset0:16 offset1:24
	v_lshl_add_u64 v[8:9], v[6:7], 0, v[18:19]
	global_store_dwordx4 v[8:9], v[0:3], off sc1
	ds_read2_b32 v[8:9], v94 offset0:49 offset1:57
	ds_read2_b32 v[10:11], v94 offset0:82 offset1:90
	ds_read2_b32 v[12:13], v94 offset0:115 offset1:123
	s_waitcnt lgkmcnt(3)
	v_bfe_u32 v0, v4, 16, 1
	v_add3_u32 v0, v4, v0, s65
	s_waitcnt lgkmcnt(2)
	v_bfe_u32 v1, v8, 16, 1
	ds_read2_b32 v[14:15], v94 offset0:148 offset1:156
	v_lshrrev_b32_e32 v0, 16, v0
	v_add3_u32 v1, v8, v1, s65
	ds_read2_b32 v[88:89], v94 offset0:181 offset1:189
	v_and_or_b32 v0, v1, s66, v0
	s_waitcnt lgkmcnt(3)
	v_bfe_u32 v1, v10, 16, 1
	v_add3_u32 v1, v10, v1, s65
	s_waitcnt lgkmcnt(2)
	v_bfe_u32 v2, v12, 16, 1
	ds_read2_b32 v[90:91], v94 offset0:214 offset1:222
	v_lshrrev_b32_e32 v1, 16, v1
	v_add3_u32 v2, v12, v2, s65
	ds_read2_b32 v[112:113], v94 offset0:247 offset1:255
	v_and_or_b32 v1, v2, s66, v1
	s_waitcnt lgkmcnt(3)
	v_bfe_u32 v2, v14, 16, 1
	v_add3_u32 v2, v14, v2, s65
	s_waitcnt lgkmcnt(2)
	v_bfe_u32 v3, v88, 16, 1
	v_lshrrev_b32_e32 v2, 16, v2
	v_add3_u32 v3, v88, v3, s65
	v_and_or_b32 v2, v3, s66, v2
	s_waitcnt lgkmcnt(1)
	v_bfe_u32 v3, v90, 16, 1
	v_add3_u32 v3, v90, v3, s65
	s_waitcnt lgkmcnt(0)
	v_bfe_u32 v4, v112, 16, 1
	v_lshrrev_b32_e32 v3, 16, v3
	v_add3_u32 v4, v112, v4, s65
	v_add_lshl_u32 v18, s3, v55, 10
	v_and_or_b32 v3, v4, s66, v3
	v_lshl_add_u64 v[114:115], v[6:7], 0, v[18:19]
	global_store_dwordx4 v[114:115], v[0:3], off sc1
	v_bfe_u32 v4, v113, 16, 1
	v_add3_u32 v4, v113, v4, s65
	v_bfe_u32 v0, v5, 16, 1
	v_add3_u32 v0, v5, v0, s65
	v_bfe_u32 v1, v9, 16, 1
	v_lshrrev_b32_e32 v0, 16, v0
	v_add3_u32 v1, v9, v1, s65
	v_and_or_b32 v0, v1, s66, v0
	v_bfe_u32 v1, v11, 16, 1
	v_add3_u32 v1, v11, v1, s65
	v_bfe_u32 v2, v13, 16, 1
	v_lshrrev_b32_e32 v1, 16, v1
	v_add3_u32 v2, v13, v2, s65
	v_and_or_b32 v1, v2, s66, v1
	v_bfe_u32 v2, v15, 16, 1
	v_add3_u32 v2, v15, v2, s65
	v_bfe_u32 v3, v89, 16, 1
	v_lshrrev_b32_e32 v2, 16, v2
	v_add3_u32 v3, v89, v3, s65
	v_and_or_b32 v2, v3, s66, v2
	v_bfe_u32 v3, v91, 16, 1
	v_add3_u32 v3, v91, v3, s65
	v_lshrrev_b32_e32 v3, 16, v3
	v_add_lshl_u32 v18, s3, v57, 10
	v_and_or_b32 v3, v4, s66, v3
	v_lshl_add_u64 v[4:5], v[6:7], 0, v[18:19]
	global_store_dwordx4 v[4:5], v[0:3], off sc1
	s_waitcnt lgkmcnt(0)

.LBB0_82:
	s_waitcnt lgkmcnt(0)
	ds_read2_b32 v[4:5], v94 offset1:8
	ds_read2_b32 v[8:9], v94 offset0:33 offset1:41
	ds_read2_b32 v[10:11], v94 offset0:66 offset1:74
	ds_read2_b32 v[12:13], v94 offset0:99 offset1:107
	ds_read2_b32 v[14:15], v94 offset0:132 offset1:140
	s_waitcnt lgkmcnt(0)
	v_bfe_u32 v0, v4, 16, 1
	v_add3_u32 v0, v4, v0, s65
	v_bfe_u32 v1, v8, 16, 1
	v_lshrrev_b32_e32 v0, 16, v0
	v_add3_u32 v1, v8, v1, s65
	ds_read2_b32 v[88:89], v94 offset0:165 offset1:173
	v_and_or_b32 v0, v1, s66, v0
	v_bfe_u32 v1, v10, 16, 1
	v_add3_u32 v1, v10, v1, s65
	v_bfe_u32 v2, v12, 16, 1
	ds_read2_b32 v[90:91], v94 offset0:198 offset1:206
	v_lshrrev_b32_e32 v1, 16, v1
	v_add3_u32 v2, v12, v2, s65
	ds_read2_b32 v[112:113], v94 offset0:231 offset1:239
	v_and_or_b32 v1, v2, s66, v1
	v_bfe_u32 v2, v14, 16, 1
	v_add3_u32 v2, v14, v2, s65
	s_waitcnt lgkmcnt(2)
	v_bfe_u32 v3, v88, 16, 1
	v_lshrrev_b32_e32 v2, 16, v2
	v_add3_u32 v3, v88, v3, s65
	s_lshl_b32 s1, s70, 5
	s_lshl_b32 s2, s22, 2
	v_and_or_b32 v2, v3, s66, v2
	s_waitcnt lgkmcnt(1)
	v_bfe_u32 v3, v90, 16, 1
	s_and_b32 s1, s1, 0x7e0
	s_and_b32 s2, s2, 0x7ffff800
	v_add3_u32 v3, v90, v3, s65
	s_waitcnt lgkmcnt(0)
	v_bfe_u32 v4, v112, 16, 1
	s_and_b32 s0, s22, 0x1c0
	s_or_b32 s1, s2, s1
	v_lshrrev_b32_e32 v3, 16, v3
	v_add3_u32 v4, v112, v4, s65
	s_lshl_b32 s24, s0, 1
	v_and_or_b32 v3, v4, s66, v3
	v_or_b32_e32 v4, s1, v25
	v_lshl_add_u64 v[6:7], v[26:27], 0, s[24:25]
	v_lshlrev_b32_e32 v18, 10, v4
	v_lshl_add_u64 v[114:115], v[6:7], 0, v[18:19]
	global_store_dwordx4 v[114:115], v[0:3], off sc1
	v_bfe_u32 v4, v113, 16, 1
	v_or_b32_e32 v8, s1, v33
	v_bfe_u32 v0, v5, 16, 1
	v_add3_u32 v0, v5, v0, s65
	v_bfe_u32 v1, v9, 16, 1
	v_lshrrev_b32_e32 v0, 16, v0
	v_add3_u32 v1, v9, v1, s65
	v_and_or_b32 v0, v1, s66, v0
	v_bfe_u32 v1, v11, 16, 1
	v_add3_u32 v1, v11, v1, s65
	v_bfe_u32 v2, v13, 16, 1
	v_lshrrev_b32_e32 v1, 16, v1
	v_add3_u32 v2, v13, v2, s65
	v_and_or_b32 v1, v2, s66, v1
	v_bfe_u32 v2, v15, 16, 1
	v_add3_u32 v2, v15, v2, s65
	v_bfe_u32 v3, v89, 16, 1
	v_lshrrev_b32_e32 v2, 16, v2
	v_add3_u32 v3, v89, v3, s65
	v_and_or_b32 v2, v3, s66, v2
	v_bfe_u32 v3, v91, 16, 1
	v_add3_u32 v3, v91, v3, s65
	v_lshrrev_b32_e32 v3, 16, v3
	v_add3_u32 v4, v113, v4, s65
	v_lshlrev_b32_e32 v18, 10, v8
	v_and_or_b32 v3, v4, s66, v3
	ds_read2_b32 v[4:5], v94 offset0:16 offset1:24
	v_lshl_add_u64 v[8:9], v[6:7], 0, v[18:19]
	global_store_dwordx4 v[8:9], v[0:3], off sc1
	ds_read2_b32 v[8:9], v94 offset0:49 offset1:57
	ds_read2_b32 v[10:11], v94 offset0:82 offset1:90
	ds_read2_b32 v[12:13], v94 offset0:115 offset1:123
	s_waitcnt lgkmcnt(3)
	v_bfe_u32 v0, v4, 16, 1
	v_add3_u32 v0, v4, v0, s65
	s_waitcnt lgkmcnt(2)
	v_bfe_u32 v1, v8, 16, 1
	ds_read2_b32 v[14:15], v94 offset0:148 offset1:156
	v_lshrrev_b32_e32 v0, 16, v0
	v_add3_u32 v1, v8, v1, s65
	ds_read2_b32 v[88:89], v94 offset0:181 offset1:189
	v_and_or_b32 v0, v1, s66, v0
	s_waitcnt lgkmcnt(3)
	v_bfe_u32 v1, v10, 16, 1
	v_add3_u32 v1, v10, v1, s65
	s_waitcnt lgkmcnt(2)
	v_bfe_u32 v2, v12, 16, 1
	ds_read2_b32 v[90:91], v94 offset0:214 offset1:222
	v_lshrrev_b32_e32 v1, 16, v1
	v_add3_u32 v2, v12, v2, s65
	ds_read2_b32 v[112:113], v94 offset0:247 offset1:255
	v_and_or_b32 v1, v2, s66, v1
	s_waitcnt lgkmcnt(3)
	v_bfe_u32 v2, v14, 16, 1
	v_add3_u32 v2, v14, v2, s65
	s_waitcnt lgkmcnt(2)
	v_bfe_u32 v3, v88, 16, 1
	v_lshrrev_b32_e32 v2, 16, v2
	v_add3_u32 v3, v88, v3, s65
	v_and_or_b32 v2, v3, s66, v2
	s_waitcnt lgkmcnt(1)
	v_bfe_u32 v3, v90, 16, 1
	v_add3_u32 v3, v90, v3, s65
	s_waitcnt lgkmcnt(0)
	v_bfe_u32 v4, v112, 16, 1
	v_lshrrev_b32_e32 v3, 16, v3
	v_add3_u32 v4, v112, v4, s65
	v_and_or_b32 v3, v4, s66, v3
	v_or_b32_e32 v4, s1, v55
	v_lshlrev_b32_e32 v18, 10, v4
	v_lshl_add_u64 v[114:115], v[6:7], 0, v[18:19]
	global_store_dwordx4 v[114:115], v[0:3], off sc1
	v_bfe_u32 v4, v113, 16, 1
	v_add3_u32 v4, v113, v4, s65
	v_bfe_u32 v0, v5, 16, 1
	v_add3_u32 v0, v5, v0, s65
	v_bfe_u32 v1, v9, 16, 1
	v_lshrrev_b32_e32 v0, 16, v0
	v_add3_u32 v1, v9, v1, s65
	v_and_or_b32 v0, v1, s66, v0
	v_bfe_u32 v1, v11, 16, 1
	v_add3_u32 v1, v11, v1, s65
	v_bfe_u32 v2, v13, 16, 1
	v_lshrrev_b32_e32 v1, 16, v1
	v_add3_u32 v2, v13, v2, s65
	v_and_or_b32 v1, v2, s66, v1
	v_bfe_u32 v2, v15, 16, 1
	v_add3_u32 v2, v15, v2, s65
	v_bfe_u32 v3, v89, 16, 1
	v_lshrrev_b32_e32 v2, 16, v2
	v_add3_u32 v3, v89, v3, s65
	v_and_or_b32 v2, v3, s66, v2
	v_bfe_u32 v3, v91, 16, 1
	v_add3_u32 v3, v91, v3, s65
	v_lshrrev_b32_e32 v3, 16, v3
	v_and_or_b32 v3, v4, s66, v3
	v_or_b32_e32 v4, s1, v57
	v_lshlrev_b32_e32 v18, 10, v4
	v_lshl_add_u64 v[4:5], v[6:7], 0, v[18:19]
	global_store_dwordx4 v[4:5], v[0:3], off sc1
	s_waitcnt lgkmcnt(0)

.LBB0_86:
	s_lshl_b32 s24, s5, 1
	s_lshl_b32 s7, s4, 1
	v_or_b32_e32 v75, s24, v54
	s_add_i32 s27, s24, 4
	v_or_b32_e32 v73, s7, v17
	s_add_i32 s26, s7, 4
	s_add_i32 s72, s24, 8
	v_add_lshl_u32 v18, v75, s0, 9
	v_or_b32_e32 v79, s27, v54
	v_mov_b32_e32 v3, v19
	s_add_i32 s74, s24, 12
	v_add_lshl_u32 v2, v73, s3, 9
	v_or_b32_e32 v77, s26, v17
	v_or_b32_e32 v114, s72, v54
	v_lshl_add_u64 v[90:91], v[18:19], 2, v[0:1]
	v_add_lshl_u32 v18, v79, s0, 9
	v_mov_b32_e32 v5, v19
	s_add_i32 s71, s7, 8
	s_add_i32 s73, s7, 12
	s_add_i32 s76, s24, 16
	v_or_b32_e32 v116, s74, v54
	v_lshl_add_u64 v[2:3], v[2:3], 2, v[0:1]
	v_add_lshl_u32 v4, v77, s3, 9
	v_lshl_add_u64 v[112:113], v[18:19], 2, v[0:1]
	v_add_lshl_u32 v18, v114, s0, 9
	s_add_i32 s78, s24, 20
	v_or_b32_e32 v111, s71, v17
	v_or_b32_e32 v115, s73, v17
	v_or_b32_e32 v118, s76, v54
	v_lshl_add_u64 v[4:5], v[4:5], 2, v[0:1]
	global_load_dword v126, v[90:91], off nt
	global_load_dword v127, v[2:3], off nt
	global_load_dword v128, v[112:113], off nt
	global_load_dword v129, v[4:5], off nt
	v_lshl_add_u64 v[2:3], v[18:19], 2, v[0:1]
	v_add_lshl_u32 v18, v116, s0, 9
	v_mov_b32_e32 v7, v19
	v_mov_b32_e32 v9, v19
	s_add_i32 s75, s7, 16
	s_add_i32 s77, s7, 20
	s_add_i32 s80, s24, 24
	v_or_b32_e32 v120, s78, v54
	v_add_lshl_u32 v6, v111, s3, 9
	v_add_lshl_u32 v8, v115, s3, 9
	v_lshl_add_u64 v[4:5], v[18:19], 2, v[0:1]
	v_add_lshl_u32 v18, v118, s0, 9
	s_add_i32 s79, s7, 24
	s_add_i32 s7, s7, 28
	s_add_i32 s24, s24, 28
	v_or_b32_e32 v117, s75, v17
	v_or_b32_e32 v119, s77, v17
	v_or_b32_e32 v122, s80, v54
	v_lshl_add_u64 v[6:7], v[6:7], 2, v[0:1]
	v_lshl_add_u64 v[8:9], v[8:9], 2, v[0:1]
	global_load_dword v130, v[2:3], off nt
	global_load_dword v131, v[6:7], off nt
	global_load_dword v132, v[4:5], off nt
	global_load_dword v133, v[8:9], off nt
	v_lshl_add_u64 v[2:3], v[18:19], 2, v[0:1]
	v_add_lshl_u32 v18, v120, s0, 9
	v_mov_b32_e32 v11, v19
	v_mov_b32_e32 v13, v19
	v_or_b32_e32 v121, s79, v17
	v_or_b32_e32 v124, s7, v17
	v_or_b32_e32 v123, s24, v54
	v_add_lshl_u32 v10, v117, s3, 9
	v_add_lshl_u32 v12, v119, s3, 9
	v_lshl_add_u64 v[4:5], v[18:19], 2, v[0:1]
	v_add_lshl_u32 v18, v122, s0, 9
	v_mov_b32_e32 v15, v19
	v_mov_b32_e32 v89, v19
	v_add_lshl_u32 v14, v121, s3, 9
	v_add_lshl_u32 v88, v124, s3, 9
	v_lshl_add_u64 v[10:11], v[10:11], 2, v[0:1]
	v_lshl_add_u64 v[12:13], v[12:13], 2, v[0:1]
	global_load_dword v134, v[2:3], off nt
	global_load_dword v135, v[10:11], off nt
	global_load_dword v136, v[4:5], off nt
	global_load_dword v137, v[12:13], off nt
	v_lshl_add_u64 v[2:3], v[18:19], 2, v[0:1]
	v_add_lshl_u32 v18, v123, s0, 9
	v_lshl_add_u64 v[14:15], v[14:15], 2, v[0:1]
	v_lshl_add_u64 v[88:89], v[88:89], 2, v[0:1]
	v_lshl_add_u64 v[4:5], v[18:19], 2, v[0:1]
	global_load_dword v18, v[2:3], off nt
	global_load_dword v138, v[14:15], off nt
	global_load_dword v139, v[4:5], off nt
	global_load_dword v140, v[88:89], off nt
	s_add_i32 s5, s5, 16
	s_add_i32 s4, s4, 16
	s_add_i32 s6, s6, -16
	v_mad_u64_u32 v[2:3], s[26:27], v75, s49, v[56:57]
	s_cmp_lg_u32 s6, 0
	v_mad_u64_u32 v[4:5], s[26:27], v73, s49, v[56:57]
	v_mad_u64_u32 v[6:7], s[26:27], v79, s49, v[56:57]
	v_mad_u64_u32 v[8:9], s[26:27], v77, s49, v[56:57]
	v_mad_u64_u32 v[10:11], s[26:27], v114, s49, v[56:57]
	v_mad_u64_u32 v[12:13], s[26:27], v111, s49, v[56:57]
	v_mad_u64_u32 v[14:15], s[26:27], v116, s49, v[56:57]
	v_mad_u64_u32 v[88:89], s[26:27], v115, s49, v[56:57]
	v_mad_u64_u32 v[90:91], s[26:27], v118, s49, v[56:57]
	v_mad_u64_u32 v[112:113], s[26:27], v117, s49, v[56:57]
	v_mad_u64_u32 v[114:115], s[26:27], v120, s49, v[56:57]
	v_mad_u64_u32 v[116:117], s[26:27], v119, s49, v[56:57]
	v_mad_u64_u32 v[118:119], s[26:27], v122, s49, v[56:57]
	v_mad_u64_u32 v[120:121], s[26:27], v121, s49, v[56:57]
	v_mad_u64_u32 v[122:123], s[26:27], v123, s49, v[56:57]
	v_mad_u64_u32 v[124:125], s[26:27], v124, s49, v[56:57]
	s_waitcnt vmcnt(0)
	ds_write_b32 v2, v126
	ds_write_b32 v4, v127
	ds_write_b32 v6, v128
	ds_write_b32 v8, v129
	ds_write_b32 v10, v130
	ds_write_b32 v12, v131
	ds_write_b32 v14, v132
	ds_write_b32 v88, v133
	ds_write_b32 v90, v134
	ds_write_b32 v112, v135
	ds_write_b32 v114, v136
	ds_write_b32 v116, v137
	ds_write_b32 v118, v18
	ds_write_b32 v120, v138
	ds_write_b32 v122, v139
	ds_write_b32 v124, v140
	s_cbranch_scc1 .LBB0_86
	s_waitcnt lgkmcnt(0)
	ds_read2_b32 v[4:5], v94 offset1:8
	ds_read2_b32 v[8:9], v94 offset0:33 offset1:41
	ds_read2_b32 v[10:11], v94 offset0:66 offset1:74
	ds_read2_b32 v[12:13], v94 offset0:99 offset1:107
	ds_read2_b32 v[14:15], v94 offset0:132 offset1:140
	s_waitcnt lgkmcnt(0)
	v_bfe_u32 v0, v4, 16, 1
	v_add3_u32 v0, v4, v0, s65
	v_bfe_u32 v1, v8, 16, 1
	v_lshrrev_b32_e32 v0, 16, v0
	v_add3_u32 v1, v8, v1, s65
	ds_read2_b32 v[88:89], v94 offset0:165 offset1:173
	v_and_or_b32 v0, v1, s66, v0
	v_bfe_u32 v1, v10, 16, 1
	v_add3_u32 v1, v10, v1, s65
	v_bfe_u32 v2, v12, 16, 1
	ds_read2_b32 v[90:91], v94 offset0:198 offset1:206
	s_cmpk_lt_u32 s1, 0x200
	v_lshrrev_b32_e32 v1, 16, v1
	v_add3_u32 v2, v12, v2, s65
	ds_read2_b32 v[112:113], v94 offset0:231 offset1:239
	s_cselect_b64 s[4:5], -1, 0
	v_and_or_b32 v1, v2, s66, v1
	v_bfe_u32 v2, v14, 16, 1
	s_and_b64 s[4:5], s[4:5], exec
	s_mov_b32 s1, 0x11600000
	v_add3_u32 v2, v14, v2, s65
	s_waitcnt lgkmcnt(2)
	v_bfe_u32 v3, v88, 16, 1
	s_cselect_b32 s1, s1, 0x11b00000
	v_lshrrev_b32_e32 v2, 16, v2
	v_add3_u32 v3, v88, v3, s65
	s_cselect_b32 s3, 0x300, 0
	s_add_u32 s1, s28, s1
	v_and_or_b32 v2, v3, s66, v2
	s_waitcnt lgkmcnt(1)
	v_bfe_u32 v3, v90, 16, 1
	s_addc_u32 s4, s29, 0
	s_add_i32 s3, s3, s2
	s_lshl_b32 s0, s0, 1
	v_add3_u32 v3, v90, v3, s65
	s_waitcnt lgkmcnt(0)
	v_bfe_u32 v4, v112, 16, 1
	s_add_u32 s0, s1, s0
	v_lshrrev_b32_e32 v3, 16, v3
	v_add3_u32 v4, v112, v4, s65
	s_addc_u32 s1, s4, 0
	v_lshlrev_b32_e32 v18, 1, v24
	v_and_or_b32 v3, v4, s66, v3
	v_or_b32_e32 v4, s3, v25
	v_lshl_add_u64 v[6:7], s[0:1], 0, v[18:19]
	v_lshlrev_b32_e32 v18, 12, v4
	v_lshl_add_u64 v[114:115], v[6:7], 0, v[18:19]
	global_store_dwordx4 v[114:115], v[0:3], off sc1
	v_bfe_u32 v4, v113, 16, 1
	v_or_b32_e32 v8, s3, v33
	v_bfe_u32 v0, v5, 16, 1
	v_add3_u32 v0, v5, v0, s65
	v_bfe_u32 v1, v9, 16, 1
	v_lshrrev_b32_e32 v0, 16, v0
	v_add3_u32 v1, v9, v1, s65
	v_and_or_b32 v0, v1, s66, v0
	v_bfe_u32 v1, v11, 16, 1
	v_add3_u32 v1, v11, v1, s65
	v_bfe_u32 v2, v13, 16, 1
	v_lshrrev_b32_e32 v1, 16, v1
	v_add3_u32 v2, v13, v2, s65
	v_and_or_b32 v1, v2, s66, v1
	v_bfe_u32 v2, v15, 16, 1
	v_add3_u32 v2, v15, v2, s65
	v_bfe_u32 v3, v89, 16, 1
	v_lshrrev_b32_e32 v2, 16, v2
	v_add3_u32 v3, v89, v3, s65
	v_and_or_b32 v2, v3, s66, v2
	v_bfe_u32 v3, v91, 16, 1
	v_add3_u32 v3, v91, v3, s65
	v_lshrrev_b32_e32 v3, 16, v3
	v_add3_u32 v4, v113, v4, s65
	v_lshlrev_b32_e32 v18, 12, v8
	v_and_or_b32 v3, v4, s66, v3
	ds_read2_b32 v[4:5], v94 offset0:16 offset1:24
	v_lshl_add_u64 v[8:9], v[6:7], 0, v[18:19]
	global_store_dwordx4 v[8:9], v[0:3], off sc1
	ds_read2_b32 v[8:9], v94 offset0:49 offset1:57
	ds_read2_b32 v[10:11], v94 offset0:82 offset1:90
	ds_read2_b32 v[12:13], v94 offset0:115 offset1:123
	s_waitcnt lgkmcnt(3)
	v_bfe_u32 v0, v4, 16, 1
	v_add3_u32 v0, v4, v0, s65
	s_waitcnt lgkmcnt(2)
	v_bfe_u32 v1, v8, 16, 1
	ds_read2_b32 v[14:15], v94 offset0:148 offset1:156
	v_lshrrev_b32_e32 v0, 16, v0
	v_add3_u32 v1, v8, v1, s65
	ds_read2_b32 v[88:89], v94 offset0:181 offset1:189
	v_and_or_b32 v0, v1, s66, v0
	s_waitcnt lgkmcnt(3)
	v_bfe_u32 v1, v10, 16, 1
	v_add3_u32 v1, v10, v1, s65
	s_waitcnt lgkmcnt(2)
	v_bfe_u32 v2, v12, 16, 1
	ds_read2_b32 v[90:91], v94 offset0:214 offset1:222
	v_lshrrev_b32_e32 v1, 16, v1
	v_add3_u32 v2, v12, v2, s65
	ds_read2_b32 v[112:113], v94 offset0:247 offset1:255
	v_and_or_b32 v1, v2, s66, v1
	s_waitcnt lgkmcnt(3)
	v_bfe_u32 v2, v14, 16, 1
	v_add3_u32 v2, v14, v2, s65
	s_waitcnt lgkmcnt(2)
	v_bfe_u32 v3, v88, 16, 1
	v_lshrrev_b32_e32 v2, 16, v2
	v_add3_u32 v3, v88, v3, s65
	v_and_or_b32 v2, v3, s66, v2
	s_waitcnt lgkmcnt(1)
	v_bfe_u32 v3, v90, 16, 1
	v_add3_u32 v3, v90, v3, s65
	s_waitcnt lgkmcnt(0)
	v_bfe_u32 v4, v112, 16, 1
	v_lshrrev_b32_e32 v3, 16, v3
	v_add3_u32 v4, v112, v4, s65
	v_and_or_b32 v3, v4, s66, v3
	v_or_b32_e32 v4, s3, v55
	v_lshlrev_b32_e32 v18, 12, v4
	v_lshl_add_u64 v[114:115], v[6:7], 0, v[18:19]
	global_store_dwordx4 v[114:115], v[0:3], off sc1
	v_bfe_u32 v4, v113, 16, 1
	v_add3_u32 v4, v113, v4, s65
	v_bfe_u32 v0, v5, 16, 1
	v_add3_u32 v0, v5, v0, s65
	v_bfe_u32 v1, v9, 16, 1
	v_lshrrev_b32_e32 v0, 16, v0
	v_add3_u32 v1, v9, v1, s65
	v_and_or_b32 v0, v1, s66, v0
	v_bfe_u32 v1, v11, 16, 1
	v_add3_u32 v1, v11, v1, s65
	v_bfe_u32 v2, v13, 16, 1
	v_lshrrev_b32_e32 v1, 16, v1
	v_add3_u32 v2, v13, v2, s65
	v_and_or_b32 v1, v2, s66, v1
	v_bfe_u32 v2, v15, 16, 1
	v_add3_u32 v2, v15, v2, s65
	v_bfe_u32 v3, v89, 16, 1
	v_lshrrev_b32_e32 v2, 16, v2
	v_add3_u32 v3, v89, v3, s65
	v_and_or_b32 v2, v3, s66, v2
	v_bfe_u32 v3, v91, 16, 1
	v_add3_u32 v3, v91, v3, s65
	v_lshrrev_b32_e32 v3, 16, v3
	v_and_or_b32 v3, v4, s66, v3
	v_or_b32_e32 v4, s3, v57
	v_lshlrev_b32_e32 v18, 12, v4
	v_lshl_add_u64 v[4:5], v[6:7], 0, v[18:19]
	global_store_dwordx4 v[4:5], v[0:3], off sc1
	s_waitcnt lgkmcnt(0)

.LBB0_91:
	s_lshl_b32 s6, s3, 1
	s_lshl_b32 s5, s2, 1
	v_or_b32_e32 v75, s6, v54
	s_add_i32 s24, s6, 4
	v_or_b32_e32 v73, s5, v17
	s_add_i32 s7, s5, 4
	s_add_i32 s27, s6, 8
	v_add_lshl_u32 v18, v75, s0, 6
	v_or_b32_e32 v79, s24, v54
	v_mov_b32_e32 v1, v19
	s_add_i32 s72, s6, 12
	v_add_lshl_u32 v0, v73, s1, 6
	v_or_b32_e32 v77, s7, v17
	v_or_b32_e32 v112, s27, v54
	v_lshl_add_u64 v[88:89], v[18:19], 2, v[30:31]
	v_add_lshl_u32 v18, v79, s0, 6
	v_mov_b32_e32 v3, v19
	s_add_i32 s26, s5, 8
	s_add_i32 s71, s5, 12
	s_add_i32 s74, s6, 16
	v_or_b32_e32 v114, s72, v54
	v_lshl_add_u64 v[0:1], v[0:1], 2, v[30:31]
	v_add_lshl_u32 v2, v77, s1, 6
	v_lshl_add_u64 v[90:91], v[18:19], 2, v[30:31]
	v_add_lshl_u32 v18, v112, s0, 6
	s_add_i32 s76, s6, 20
	v_or_b32_e32 v111, s26, v17
	v_or_b32_e32 v113, s71, v17
	v_or_b32_e32 v116, s74, v54
	v_lshl_add_u64 v[2:3], v[2:3], 2, v[30:31]
	global_load_dword v124, v[88:89], off nt
	global_load_dword v125, v[0:1], off nt
	global_load_dword v126, v[90:91], off nt
	global_load_dword v127, v[2:3], off nt
	v_lshl_add_u64 v[0:1], v[18:19], 2, v[30:31]
	v_add_lshl_u32 v18, v114, s0, 6
	v_mov_b32_e32 v5, v19
	v_mov_b32_e32 v7, v19
	s_add_i32 s73, s5, 16
	s_add_i32 s75, s5, 20
	s_add_i32 s78, s6, 24
	v_or_b32_e32 v118, s76, v54
	v_add_lshl_u32 v4, v111, s1, 6
	v_add_lshl_u32 v6, v113, s1, 6
	v_lshl_add_u64 v[2:3], v[18:19], 2, v[30:31]
	v_add_lshl_u32 v18, v116, s0, 6
	s_add_i32 s77, s5, 24
	s_add_i32 s5, s5, 28
	s_add_i32 s6, s6, 28
	v_or_b32_e32 v115, s73, v17
	v_or_b32_e32 v117, s75, v17
	v_or_b32_e32 v120, s78, v54
	v_lshl_add_u64 v[4:5], v[4:5], 2, v[30:31]
	v_lshl_add_u64 v[6:7], v[6:7], 2, v[30:31]
	global_load_dword v128, v[0:1], off nt
	global_load_dword v129, v[4:5], off nt
	global_load_dword v130, v[2:3], off nt
	global_load_dword v131, v[6:7], off nt
	v_lshl_add_u64 v[0:1], v[18:19], 2, v[30:31]
	v_add_lshl_u32 v18, v118, s0, 6
	v_mov_b32_e32 v9, v19
	v_mov_b32_e32 v11, v19
	v_or_b32_e32 v119, s77, v17
	v_or_b32_e32 v122, s5, v17
	v_or_b32_e32 v121, s6, v54
	v_add_lshl_u32 v8, v115, s1, 6
	v_add_lshl_u32 v10, v117, s1, 6
	v_lshl_add_u64 v[2:3], v[18:19], 2, v[30:31]
	v_add_lshl_u32 v18, v120, s0, 6
	v_mov_b32_e32 v13, v19
	v_mov_b32_e32 v15, v19
	v_add_lshl_u32 v12, v119, s1, 6
	v_add_lshl_u32 v14, v122, s1, 6
	v_lshl_add_u64 v[8:9], v[8:9], 2, v[30:31]
	v_lshl_add_u64 v[10:11], v[10:11], 2, v[30:31]
	global_load_dword v132, v[0:1], off nt
	global_load_dword v133, v[8:9], off nt
	global_load_dword v134, v[2:3], off nt
	global_load_dword v135, v[10:11], off nt
	v_lshl_add_u64 v[0:1], v[18:19], 2, v[30:31]
	v_add_lshl_u32 v18, v121, s0, 6
	v_lshl_add_u64 v[12:13], v[12:13], 2, v[30:31]
	v_lshl_add_u64 v[14:15], v[14:15], 2, v[30:31]
	v_lshl_add_u64 v[2:3], v[18:19], 2, v[30:31]
	global_load_dword v18, v[0:1], off nt
	global_load_dword v136, v[12:13], off nt
	global_load_dword v137, v[2:3], off nt
	global_load_dword v138, v[14:15], off nt
	s_add_i32 s3, s3, 16
	s_add_i32 s2, s2, 16
	s_add_i32 s4, s4, -16
	v_mad_u64_u32 v[0:1], s[6:7], v75, s49, v[56:57]
	s_cmp_lg_u32 s4, 0
	v_mad_u64_u32 v[2:3], s[6:7], v73, s49, v[56:57]
	v_mad_u64_u32 v[4:5], s[6:7], v79, s49, v[56:57]
	v_mad_u64_u32 v[6:7], s[6:7], v77, s49, v[56:57]
	v_mad_u64_u32 v[8:9], s[6:7], v112, s49, v[56:57]
	v_mad_u64_u32 v[10:11], s[6:7], v111, s49, v[56:57]
	v_mad_u64_u32 v[12:13], s[6:7], v114, s49, v[56:57]
	v_mad_u64_u32 v[14:15], s[6:7], v113, s49, v[56:57]
	v_mad_u64_u32 v[88:89], s[6:7], v116, s49, v[56:57]
	v_mad_u64_u32 v[90:91], s[6:7], v115, s49, v[56:57]
	v_mad_u64_u32 v[112:113], s[6:7], v118, s49, v[56:57]
	v_mad_u64_u32 v[114:115], s[6:7], v117, s49, v[56:57]
	v_mad_u64_u32 v[116:117], s[6:7], v120, s49, v[56:57]
	v_mad_u64_u32 v[118:119], s[6:7], v119, s49, v[56:57]
	v_mad_u64_u32 v[120:121], s[6:7], v121, s49, v[56:57]
	v_mad_u64_u32 v[122:123], s[6:7], v122, s49, v[56:57]
	s_waitcnt vmcnt(0)
	ds_write_b32 v0, v124
	ds_write_b32 v2, v125
	ds_write_b32 v4, v126
	ds_write_b32 v6, v127
	ds_write_b32 v8, v128
	ds_write_b32 v10, v129
	ds_write_b32 v12, v130
	ds_write_b32 v14, v131
	ds_write_b32 v88, v132
	ds_write_b32 v90, v133
	ds_write_b32 v112, v134
	ds_write_b32 v114, v135
	ds_write_b32 v116, v18
	ds_write_b32 v118, v136
	ds_write_b32 v120, v137
	ds_write_b32 v122, v138
	s_cbranch_scc1 .LBB0_91
	s_waitcnt lgkmcnt(0)
	ds_read2_b32 v[4:5], v94 offset1:8
	ds_read2_b32 v[8:9], v94 offset0:33 offset1:41
	ds_read2_b32 v[10:11], v94 offset0:66 offset1:74
	ds_read2_b32 v[12:13], v94 offset0:99 offset1:107
	ds_read2_b32 v[14:15], v94 offset0:132 offset1:140
	ds_read2_b32 v[88:89], v94 offset0:165 offset1:173
	s_waitcnt lgkmcnt(0)
	v_bfe_u32 v0, v4, 16, 1
	v_add3_u32 v0, v4, v0, s65
	v_bfe_u32 v1, v8, 16, 1
	v_lshrrev_b32_e32 v0, 16, v0
	v_add3_u32 v1, v8, v1, s65
	v_and_or_b32 v0, v1, s66, v0
	v_bfe_u32 v1, v10, 16, 1
	v_add3_u32 v1, v10, v1, s65
	v_bfe_u32 v2, v12, 16, 1
	ds_read2_b32 v[90:91], v94 offset0:198 offset1:206
	v_lshrrev_b32_e32 v1, 16, v1
	v_add3_u32 v2, v12, v2, s65
	ds_read2_b32 v[112:113], v94 offset0:231 offset1:239
	v_and_or_b32 v1, v2, s66, v1
	v_bfe_u32 v2, v14, 16, 1
	v_add3_u32 v2, v14, v2, s65
	v_bfe_u32 v3, v88, 16, 1
	v_lshrrev_b32_e32 v2, 16, v2
	v_add3_u32 v3, v88, v3, s65
	v_and_or_b32 v2, v3, s66, v2
	s_waitcnt lgkmcnt(1)
	v_bfe_u32 v3, v90, 16, 1
	s_mov_b32 s1, s25
	v_add3_u32 v3, v90, v3, s65
	s_waitcnt lgkmcnt(0)
	v_bfe_u32 v4, v112, 16, 1
	v_lshl_add_u64 v[6:7], s[0:1], 1, v[60:61]
	v_lshrrev_b32_e32 v3, 16, v3
	v_add3_u32 v4, v112, v4, s65
	v_mov_b32_e32 v73, v19
	v_and_or_b32 v3, v4, s66, v3
	v_lshl_add_u64 v[114:115], v[6:7], 0, v[72:73]
	global_store_dwordx4 v[114:115], v[0:3], off sc1
	v_bfe_u32 v4, v113, 16, 1
	v_add3_u32 v4, v113, v4, s65
	v_bfe_u32 v0, v5, 16, 1
	v_add3_u32 v0, v5, v0, s65
	v_bfe_u32 v1, v9, 16, 1
	v_lshrrev_b32_e32 v0, 16, v0
	v_add3_u32 v1, v9, v1, s65
	v_and_or_b32 v0, v1, s66, v0
	v_bfe_u32 v1, v11, 16, 1
	v_add3_u32 v1, v11, v1, s65
	v_bfe_u32 v2, v13, 16, 1
	v_lshrrev_b32_e32 v1, 16, v1
	v_add3_u32 v2, v13, v2, s65
	v_and_or_b32 v1, v2, s66, v1
	v_bfe_u32 v2, v15, 16, 1
	v_add3_u32 v2, v15, v2, s65
	v_bfe_u32 v3, v89, 16, 1
	v_lshrrev_b32_e32 v2, 16, v2
	v_add3_u32 v3, v89, v3, s65
	v_and_or_b32 v2, v3, s66, v2
	v_bfe_u32 v3, v91, 16, 1
	v_add3_u32 v3, v91, v3, s65
	v_lshrrev_b32_e32 v3, 16, v3
	v_mov_b32_e32 v75, v19
	v_and_or_b32 v3, v4, s66, v3
	ds_read2_b32 v[4:5], v94 offset0:16 offset1:24
	v_lshl_add_u64 v[8:9], v[6:7], 0, v[74:75]
	global_store_dwordx4 v[8:9], v[0:3], off sc1
	ds_read2_b32 v[8:9], v94 offset0:49 offset1:57
	ds_read2_b32 v[10:11], v94 offset0:82 offset1:90
	ds_read2_b32 v[12:13], v94 offset0:115 offset1:123
	s_waitcnt lgkmcnt(3)
	v_bfe_u32 v0, v4, 16, 1
	v_add3_u32 v0, v4, v0, s65
	s_waitcnt lgkmcnt(2)
	v_bfe_u32 v1, v8, 16, 1
	ds_read2_b32 v[14:15], v94 offset0:148 offset1:156
	v_lshrrev_b32_e32 v0, 16, v0
	v_add3_u32 v1, v8, v1, s65
	ds_read2_b32 v[88:89], v94 offset0:181 offset1:189
	v_and_or_b32 v0, v1, s66, v0
	s_waitcnt lgkmcnt(3)
	v_bfe_u32 v1, v10, 16, 1
	v_add3_u32 v1, v10, v1, s65
	s_waitcnt lgkmcnt(2)
	v_bfe_u32 v2, v12, 16, 1
	ds_read2_b32 v[90:91], v94 offset0:214 offset1:222
	v_lshrrev_b32_e32 v1, 16, v1
	v_add3_u32 v2, v12, v2, s65
	ds_read2_b32 v[112:113], v94 offset0:247 offset1:255
	v_and_or_b32 v1, v2, s66, v1
	s_waitcnt lgkmcnt(3)
	v_bfe_u32 v2, v14, 16, 1
	v_add3_u32 v2, v14, v2, s65
	s_waitcnt lgkmcnt(2)
	v_bfe_u32 v3, v88, 16, 1
	v_lshrrev_b32_e32 v2, 16, v2
	v_add3_u32 v3, v88, v3, s65
	v_and_or_b32 v2, v3, s66, v2
	s_waitcnt lgkmcnt(1)
	v_bfe_u32 v3, v90, 16, 1
	v_add3_u32 v3, v90, v3, s65
	s_waitcnt lgkmcnt(0)
	v_bfe_u32 v4, v112, 16, 1
	v_lshrrev_b32_e32 v3, 16, v3
	v_add3_u32 v4, v112, v4, s65
	v_mov_b32_e32 v77, v19
	v_and_or_b32 v3, v4, s66, v3
	v_lshl_add_u64 v[114:115], v[6:7], 0, v[76:77]
	global_store_dwordx4 v[114:115], v[0:3], off sc1
	v_bfe_u32 v4, v113, 16, 1
	v_add3_u32 v4, v113, v4, s65
	v_bfe_u32 v0, v5, 16, 1
	v_add3_u32 v0, v5, v0, s65
	v_bfe_u32 v1, v9, 16, 1
	v_lshrrev_b32_e32 v0, 16, v0
	v_add3_u32 v1, v9, v1, s65
	v_and_or_b32 v0, v1, s66, v0
	v_bfe_u32 v1, v11, 16, 1
	v_add3_u32 v1, v11, v1, s65
	v_bfe_u32 v2, v13, 16, 1
	v_lshrrev_b32_e32 v1, 16, v1
	v_add3_u32 v2, v13, v2, s65
	v_and_or_b32 v1, v2, s66, v1
	v_bfe_u32 v2, v15, 16, 1
	v_add3_u32 v2, v15, v2, s65
	v_bfe_u32 v3, v89, 16, 1
	v_lshrrev_b32_e32 v2, 16, v2
	v_add3_u32 v3, v89, v3, s65
	v_and_or_b32 v2, v3, s66, v2
	v_bfe_u32 v3, v91, 16, 1
	v_add3_u32 v3, v91, v3, s65
	v_lshrrev_b32_e32 v3, 16, v3
	v_mov_b32_e32 v79, v19
	v_and_or_b32 v3, v4, s66, v3
	v_lshl_add_u64 v[4:5], v[6:7], 0, v[78:79]
	global_store_dwordx4 v[4:5], v[0:3], off sc1
	s_waitcnt lgkmcnt(0)

.LBB0_96:
	s_lshl_b32 s7, s4, 1
	s_lshl_b32 s6, s3, 1
	v_or_b32_e32 v75, s7, v54
	s_add_i32 s26, s7, 4
	v_or_b32_e32 v73, s6, v17
	s_add_i32 s24, s6, 4
	s_add_i32 s71, s7, 8
	v_add_lshl_u32 v18, v75, s0, 9
	v_or_b32_e32 v79, s26, v54
	v_mov_b32_e32 v3, v19
	s_add_i32 s73, s7, 12
	v_add_lshl_u32 v2, v73, s1, 9
	v_or_b32_e32 v77, s24, v17
	v_or_b32_e32 v114, s71, v54
	v_lshl_add_u64 v[90:91], v[18:19], 2, v[0:1]
	v_add_lshl_u32 v18, v79, s0, 9
	v_mov_b32_e32 v5, v19
	s_add_i32 s27, s6, 8
	s_add_i32 s72, s6, 12
	s_add_i32 s75, s7, 16
	v_or_b32_e32 v116, s73, v54
	v_lshl_add_u64 v[2:3], v[2:3], 2, v[0:1]
	v_add_lshl_u32 v4, v77, s1, 9
	v_lshl_add_u64 v[112:113], v[18:19], 2, v[0:1]
	v_add_lshl_u32 v18, v114, s0, 9
	s_add_i32 s77, s7, 20
	v_or_b32_e32 v111, s27, v17
	v_or_b32_e32 v115, s72, v17
	v_or_b32_e32 v118, s75, v54
	v_lshl_add_u64 v[4:5], v[4:5], 2, v[0:1]
	global_load_dword v126, v[90:91], off nt
	global_load_dword v127, v[2:3], off nt
	global_load_dword v128, v[112:113], off nt
	global_load_dword v129, v[4:5], off nt
	v_lshl_add_u64 v[2:3], v[18:19], 2, v[0:1]
	v_add_lshl_u32 v18, v116, s0, 9
	v_mov_b32_e32 v7, v19
	v_mov_b32_e32 v9, v19
	s_add_i32 s74, s6, 16
	s_add_i32 s76, s6, 20
	s_add_i32 s79, s7, 24
	v_or_b32_e32 v120, s77, v54
	v_add_lshl_u32 v6, v111, s1, 9
	v_add_lshl_u32 v8, v115, s1, 9
	v_lshl_add_u64 v[4:5], v[18:19], 2, v[0:1]
	v_add_lshl_u32 v18, v118, s0, 9
	s_add_i32 s78, s6, 24
	s_add_i32 s6, s6, 28
	s_add_i32 s7, s7, 28
	v_or_b32_e32 v117, s74, v17
	v_or_b32_e32 v119, s76, v17
	v_or_b32_e32 v122, s79, v54
	v_lshl_add_u64 v[6:7], v[6:7], 2, v[0:1]
	v_lshl_add_u64 v[8:9], v[8:9], 2, v[0:1]
	global_load_dword v130, v[2:3], off nt
	global_load_dword v131, v[6:7], off nt
	global_load_dword v132, v[4:5], off nt
	global_load_dword v133, v[8:9], off nt
	v_lshl_add_u64 v[2:3], v[18:19], 2, v[0:1]
	v_add_lshl_u32 v18, v120, s0, 9
	v_mov_b32_e32 v11, v19
	v_mov_b32_e32 v13, v19
	v_or_b32_e32 v121, s78, v17
	v_or_b32_e32 v124, s6, v17
	v_or_b32_e32 v123, s7, v54
	v_add_lshl_u32 v10, v117, s1, 9
	v_add_lshl_u32 v12, v119, s1, 9
	v_lshl_add_u64 v[4:5], v[18:19], 2, v[0:1]
	v_add_lshl_u32 v18, v122, s0, 9
	v_mov_b32_e32 v15, v19
	v_mov_b32_e32 v89, v19
	v_add_lshl_u32 v14, v121, s1, 9
	v_add_lshl_u32 v88, v124, s1, 9
	v_lshl_add_u64 v[10:11], v[10:11], 2, v[0:1]
	v_lshl_add_u64 v[12:13], v[12:13], 2, v[0:1]
	global_load_dword v134, v[2:3], off nt
	global_load_dword v135, v[10:11], off nt
	global_load_dword v136, v[4:5], off nt
	global_load_dword v137, v[12:13], off nt
	v_lshl_add_u64 v[2:3], v[18:19], 2, v[0:1]
	v_add_lshl_u32 v18, v123, s0, 9
	v_lshl_add_u64 v[14:15], v[14:15], 2, v[0:1]
	v_lshl_add_u64 v[88:89], v[88:89], 2, v[0:1]
	v_lshl_add_u64 v[4:5], v[18:19], 2, v[0:1]
	global_load_dword v18, v[2:3], off nt
	global_load_dword v138, v[14:15], off nt
	global_load_dword v139, v[4:5], off nt
	global_load_dword v140, v[88:89], off nt
	s_add_i32 s4, s4, 16
	s_add_i32 s3, s3, 16
	s_add_i32 s5, s5, -16
	v_mad_u64_u32 v[2:3], s[6:7], v75, s49, v[56:57]
	s_cmp_lg_u32 s5, 0
	v_mad_u64_u32 v[4:5], s[6:7], v73, s49, v[56:57]
	v_mad_u64_u32 v[6:7], s[6:7], v79, s49, v[56:57]
	v_mad_u64_u32 v[8:9], s[6:7], v77, s49, v[56:57]
	v_mad_u64_u32 v[10:11], s[6:7], v114, s49, v[56:57]
	v_mad_u64_u32 v[12:13], s[6:7], v111, s49, v[56:57]
	v_mad_u64_u32 v[14:15], s[6:7], v116, s49, v[56:57]
	v_mad_u64_u32 v[88:89], s[6:7], v115, s49, v[56:57]
	v_mad_u64_u32 v[90:91], s[6:7], v118, s49, v[56:57]
	v_mad_u64_u32 v[112:113], s[6:7], v117, s49, v[56:57]
	v_mad_u64_u32 v[114:115], s[6:7], v120, s49, v[56:57]
	v_mad_u64_u32 v[116:117], s[6:7], v119, s49, v[56:57]
	v_mad_u64_u32 v[118:119], s[6:7], v122, s49, v[56:57]
	v_mad_u64_u32 v[120:121], s[6:7], v121, s49, v[56:57]
	v_mad_u64_u32 v[122:123], s[6:7], v123, s49, v[56:57]
	v_mad_u64_u32 v[124:125], s[6:7], v124, s49, v[56:57]
	s_waitcnt vmcnt(0)
	ds_write_b32 v2, v126
	ds_write_b32 v4, v127
	ds_write_b32 v6, v128
	ds_write_b32 v8, v129
	ds_write_b32 v10, v130
	ds_write_b32 v12, v131
	ds_write_b32 v14, v132
	ds_write_b32 v88, v133
	ds_write_b32 v90, v134
	ds_write_b32 v112, v135
	ds_write_b32 v114, v136
	ds_write_b32 v116, v137
	ds_write_b32 v118, v18
	ds_write_b32 v120, v138
	ds_write_b32 v122, v139
	ds_write_b32 v124, v140
	s_cbranch_scc1 .LBB0_96
	s_waitcnt lgkmcnt(0)
	ds_read2_b32 v[4:5], v94 offset1:8
	ds_read2_b32 v[8:9], v94 offset0:33 offset1:41
	ds_read2_b32 v[10:11], v94 offset0:66 offset1:74
	ds_read2_b32 v[12:13], v94 offset0:99 offset1:107
	ds_read2_b32 v[14:15], v94 offset0:132 offset1:140
	ds_read2_b32 v[88:89], v94 offset0:165 offset1:173
	s_waitcnt lgkmcnt(0)
	v_bfe_u32 v0, v4, 16, 1
	v_add3_u32 v0, v4, v0, s65
	v_bfe_u32 v1, v8, 16, 1
	v_lshrrev_b32_e32 v0, 16, v0
	v_add3_u32 v1, v8, v1, s65
	v_and_or_b32 v0, v1, s66, v0
	v_bfe_u32 v1, v10, 16, 1
	v_add3_u32 v1, v10, v1, s65
	v_bfe_u32 v2, v12, 16, 1
	ds_read2_b32 v[90:91], v94 offset0:198 offset1:206
	v_lshrrev_b32_e32 v1, 16, v1
	v_add3_u32 v2, v12, v2, s65
	ds_read2_b32 v[112:113], v94 offset0:231 offset1:239
	v_and_or_b32 v1, v2, s66, v1
	v_bfe_u32 v2, v14, 16, 1
	v_add3_u32 v2, v14, v2, s65
	v_bfe_u32 v3, v88, 16, 1
	v_lshrrev_b32_e32 v2, 16, v2
	v_add3_u32 v3, v88, v3, s65
	v_and_or_b32 v2, v3, s66, v2
	s_waitcnt lgkmcnt(1)
	v_bfe_u32 v3, v90, 16, 1
	v_add3_u32 v3, v90, v3, s65
	s_waitcnt lgkmcnt(0)
	v_bfe_u32 v4, v112, 16, 1
	v_lshrrev_b32_e32 v3, 16, v3
	v_add3_u32 v4, v112, v4, s65
	s_mov_b32 s1, s25
	v_and_or_b32 v3, v4, s66, v3
	v_or_b32_e32 v4, s2, v25
	v_lshl_add_u64 v[6:7], s[0:1], 1, v[60:61]
	v_lshlrev_b32_e32 v18, 12, v4
	v_lshl_add_u64 v[114:115], v[6:7], 0, v[18:19]
	global_store_dwordx4 v[114:115], v[0:3], off sc1
	v_bfe_u32 v4, v113, 16, 1
	v_or_b32_e32 v8, s2, v33
	v_bfe_u32 v0, v5, 16, 1
	v_add3_u32 v0, v5, v0, s65
	v_bfe_u32 v1, v9, 16, 1
	v_lshrrev_b32_e32 v0, 16, v0
	v_add3_u32 v1, v9, v1, s65
	v_and_or_b32 v0, v1, s66, v0
	v_bfe_u32 v1, v11, 16, 1
	v_add3_u32 v1, v11, v1, s65
	v_bfe_u32 v2, v13, 16, 1
	v_lshrrev_b32_e32 v1, 16, v1
	v_add3_u32 v2, v13, v2, s65
	v_and_or_b32 v1, v2, s66, v1
	v_bfe_u32 v2, v15, 16, 1
	v_add3_u32 v2, v15, v2, s65
	v_bfe_u32 v3, v89, 16, 1
	v_lshrrev_b32_e32 v2, 16, v2
	v_add3_u32 v3, v89, v3, s65
	v_and_or_b32 v2, v3, s66, v2
	v_bfe_u32 v3, v91, 16, 1
	v_add3_u32 v3, v91, v3, s65
	v_lshrrev_b32_e32 v3, 16, v3
	v_add3_u32 v4, v113, v4, s65
	v_lshlrev_b32_e32 v18, 12, v8
	v_and_or_b32 v3, v4, s66, v3
	ds_read2_b32 v[4:5], v94 offset0:16 offset1:24
	v_lshl_add_u64 v[8:9], v[6:7], 0, v[18:19]
	global_store_dwordx4 v[8:9], v[0:3], off sc1
	ds_read2_b32 v[8:9], v94 offset0:49 offset1:57
	ds_read2_b32 v[10:11], v94 offset0:82 offset1:90
	ds_read2_b32 v[12:13], v94 offset0:115 offset1:123
	s_waitcnt lgkmcnt(3)
	v_bfe_u32 v0, v4, 16, 1
	v_add3_u32 v0, v4, v0, s65
	s_waitcnt lgkmcnt(2)
	v_bfe_u32 v1, v8, 16, 1
	ds_read2_b32 v[14:15], v94 offset0:148 offset1:156
	v_lshrrev_b32_e32 v0, 16, v0
	v_add3_u32 v1, v8, v1, s65
	ds_read2_b32 v[88:89], v94 offset0:181 offset1:189
	v_and_or_b32 v0, v1, s66, v0
	s_waitcnt lgkmcnt(3)
	v_bfe_u32 v1, v10, 16, 1
	v_add3_u32 v1, v10, v1, s65
	s_waitcnt lgkmcnt(2)
	v_bfe_u32 v2, v12, 16, 1
	ds_read2_b32 v[90:91], v94 offset0:214 offset1:222
	v_lshrrev_b32_e32 v1, 16, v1
	v_add3_u32 v2, v12, v2, s65
	ds_read2_b32 v[112:113], v94 offset0:247 offset1:255
	v_and_or_b32 v1, v2, s66, v1
	s_waitcnt lgkmcnt(3)
	v_bfe_u32 v2, v14, 16, 1
	v_add3_u32 v2, v14, v2, s65
	s_waitcnt lgkmcnt(2)
	v_bfe_u32 v3, v88, 16, 1
	v_lshrrev_b32_e32 v2, 16, v2
	v_add3_u32 v3, v88, v3, s65
	v_and_or_b32 v2, v3, s66, v2
	s_waitcnt lgkmcnt(1)
	v_bfe_u32 v3, v90, 16, 1
	v_add3_u32 v3, v90, v3, s65
	s_waitcnt lgkmcnt(0)
	v_bfe_u32 v4, v112, 16, 1
	v_lshrrev_b32_e32 v3, 16, v3
	v_add3_u32 v4, v112, v4, s65
	v_and_or_b32 v3, v4, s66, v3
	v_or_b32_e32 v4, s2, v55
	v_lshlrev_b32_e32 v18, 12, v4
	v_lshl_add_u64 v[114:115], v[6:7], 0, v[18:19]
	global_store_dwordx4 v[114:115], v[0:3], off sc1
	v_bfe_u32 v4, v113, 16, 1
	v_add3_u32 v4, v113, v4, s65
	v_bfe_u32 v0, v5, 16, 1
	v_add3_u32 v0, v5, v0, s65
	v_bfe_u32 v1, v9, 16, 1
	v_lshrrev_b32_e32 v0, 16, v0
	v_add3_u32 v1, v9, v1, s65
	v_and_or_b32 v0, v1, s66, v0
	v_bfe_u32 v1, v11, 16, 1
	v_add3_u32 v1, v11, v1, s65
	v_bfe_u32 v2, v13, 16, 1
	v_lshrrev_b32_e32 v1, 16, v1
	v_add3_u32 v2, v13, v2, s65
	v_and_or_b32 v1, v2, s66, v1
	v_bfe_u32 v2, v15, 16, 1
	v_add3_u32 v2, v15, v2, s65
	v_bfe_u32 v3, v89, 16, 1
	v_lshrrev_b32_e32 v2, 16, v2
	v_add3_u32 v3, v89, v3, s65
	v_and_or_b32 v2, v3, s66, v2
	v_bfe_u32 v3, v91, 16, 1
	v_add3_u32 v3, v91, v3, s65
	v_lshrrev_b32_e32 v3, 16, v3
	v_and_or_b32 v3, v4, s66, v3
	v_or_b32_e32 v4, s2, v57
	v_lshlrev_b32_e32 v18, 12, v4
	v_lshl_add_u64 v[4:5], v[6:7], 0, v[18:19]
	global_store_dwordx4 v[4:5], v[0:3], off sc1
	s_waitcnt lgkmcnt(0)

.LBB0_101:
	s_lshl_b32 s26, s5, 1
	s_lshl_b32 s7, s4, 1
	v_or_b32_e32 v75, s26, v54
	s_add_i32 s71, s26, 4
	v_or_b32_e32 v73, s7, v17
	s_add_i32 s27, s7, 4
	s_add_i32 s73, s26, 8
	v_add_lshl_u32 v18, v75, s0, 9
	v_or_b32_e32 v79, s71, v54
	v_mov_b32_e32 v3, v19
	s_add_i32 s75, s26, 12
	v_add_lshl_u32 v2, v73, s3, 9
	v_or_b32_e32 v77, s27, v17
	v_or_b32_e32 v114, s73, v54
	v_lshl_add_u64 v[90:91], v[18:19], 2, v[0:1]
	v_add_lshl_u32 v18, v79, s0, 9
	v_mov_b32_e32 v5, v19
	s_add_i32 s72, s7, 8
	s_add_i32 s74, s7, 12
	s_add_i32 s77, s26, 16
	v_or_b32_e32 v116, s75, v54
	v_lshl_add_u64 v[2:3], v[2:3], 2, v[0:1]
	v_add_lshl_u32 v4, v77, s3, 9
	v_lshl_add_u64 v[112:113], v[18:19], 2, v[0:1]
	v_add_lshl_u32 v18, v114, s0, 9
	s_add_i32 s79, s26, 20
	v_or_b32_e32 v111, s72, v17
	v_or_b32_e32 v115, s74, v17
	v_or_b32_e32 v118, s77, v54
	v_lshl_add_u64 v[4:5], v[4:5], 2, v[0:1]
	global_load_dword v126, v[90:91], off nt
	global_load_dword v127, v[2:3], off nt
	global_load_dword v128, v[112:113], off nt
	global_load_dword v129, v[4:5], off nt
	v_lshl_add_u64 v[2:3], v[18:19], 2, v[0:1]
	v_add_lshl_u32 v18, v116, s0, 9
	v_mov_b32_e32 v7, v19
	v_mov_b32_e32 v9, v19
	s_add_i32 s76, s7, 16
	s_add_i32 s78, s7, 20
	s_add_i32 s81, s26, 24
	v_or_b32_e32 v120, s79, v54
	v_add_lshl_u32 v6, v111, s3, 9
	v_add_lshl_u32 v8, v115, s3, 9
	v_lshl_add_u64 v[4:5], v[18:19], 2, v[0:1]
	v_add_lshl_u32 v18, v118, s0, 9
	s_add_i32 s80, s7, 24
	s_add_i32 s7, s7, 28
	s_add_i32 s26, s26, 28
	v_or_b32_e32 v117, s76, v17
	v_or_b32_e32 v119, s78, v17
	v_or_b32_e32 v122, s81, v54
	v_lshl_add_u64 v[6:7], v[6:7], 2, v[0:1]
	v_lshl_add_u64 v[8:9], v[8:9], 2, v[0:1]
	global_load_dword v130, v[2:3], off nt
	global_load_dword v131, v[6:7], off nt
	global_load_dword v132, v[4:5], off nt
	global_load_dword v133, v[8:9], off nt
	v_lshl_add_u64 v[2:3], v[18:19], 2, v[0:1]
	v_add_lshl_u32 v18, v120, s0, 9
	v_mov_b32_e32 v11, v19
	v_mov_b32_e32 v13, v19
	v_or_b32_e32 v121, s80, v17
	v_or_b32_e32 v124, s7, v17
	v_or_b32_e32 v123, s26, v54
	v_add_lshl_u32 v10, v117, s3, 9
	v_add_lshl_u32 v12, v119, s3, 9
	v_lshl_add_u64 v[4:5], v[18:19], 2, v[0:1]
	v_add_lshl_u32 v18, v122, s0, 9
	v_mov_b32_e32 v15, v19
	v_mov_b32_e32 v89, v19
	v_add_lshl_u32 v14, v121, s3, 9
	v_add_lshl_u32 v88, v124, s3, 9
	v_lshl_add_u64 v[10:11], v[10:11], 2, v[0:1]
	v_lshl_add_u64 v[12:13], v[12:13], 2, v[0:1]
	global_load_dword v134, v[2:3], off nt
	global_load_dword v135, v[10:11], off nt
	global_load_dword v136, v[4:5], off nt
	global_load_dword v137, v[12:13], off nt
	v_lshl_add_u64 v[2:3], v[18:19], 2, v[0:1]
	v_add_lshl_u32 v18, v123, s0, 9
	v_lshl_add_u64 v[14:15], v[14:15], 2, v[0:1]
	v_lshl_add_u64 v[88:89], v[88:89], 2, v[0:1]
	v_lshl_add_u64 v[4:5], v[18:19], 2, v[0:1]
	global_load_dword v18, v[2:3], off nt
	global_load_dword v138, v[14:15], off nt
	global_load_dword v139, v[4:5], off nt
	global_load_dword v140, v[88:89], off nt
	s_add_i32 s5, s5, 16
	s_add_i32 s4, s4, 16
	s_add_i32 s6, s6, -16
	v_mad_u64_u32 v[2:3], s[26:27], v75, s49, v[56:57]
	s_cmp_lg_u32 s6, 0
	v_mad_u64_u32 v[4:5], s[26:27], v73, s49, v[56:57]
	v_mad_u64_u32 v[6:7], s[26:27], v79, s49, v[56:57]
	v_mad_u64_u32 v[8:9], s[26:27], v77, s49, v[56:57]
	v_mad_u64_u32 v[10:11], s[26:27], v114, s49, v[56:57]
	v_mad_u64_u32 v[12:13], s[26:27], v111, s49, v[56:57]
	v_mad_u64_u32 v[14:15], s[26:27], v116, s49, v[56:57]
	v_mad_u64_u32 v[88:89], s[26:27], v115, s49, v[56:57]
	v_mad_u64_u32 v[90:91], s[26:27], v118, s49, v[56:57]
	v_mad_u64_u32 v[112:113], s[26:27], v117, s49, v[56:57]
	v_mad_u64_u32 v[114:115], s[26:27], v120, s49, v[56:57]
	v_mad_u64_u32 v[116:117], s[26:27], v119, s49, v[56:57]
	v_mad_u64_u32 v[118:119], s[26:27], v122, s49, v[56:57]
	v_mad_u64_u32 v[120:121], s[26:27], v121, s49, v[56:57]
	v_mad_u64_u32 v[122:123], s[26:27], v123, s49, v[56:57]
	v_mad_u64_u32 v[124:125], s[26:27], v124, s49, v[56:57]
	s_waitcnt vmcnt(0)
	ds_write_b32 v2, v126
	ds_write_b32 v4, v127
	ds_write_b32 v6, v128
	ds_write_b32 v8, v129
	ds_write_b32 v10, v130
	ds_write_b32 v12, v131
	ds_write_b32 v14, v132
	ds_write_b32 v88, v133
	ds_write_b32 v90, v134
	ds_write_b32 v112, v135
	ds_write_b32 v114, v136
	ds_write_b32 v116, v137
	ds_write_b32 v118, v18
	ds_write_b32 v120, v138
	ds_write_b32 v122, v139
	ds_write_b32 v124, v140
	s_cbranch_scc1 .LBB0_101
	s_waitcnt lgkmcnt(0)
	ds_read2_b32 v[4:5], v94 offset1:8
	ds_read2_b32 v[8:9], v94 offset0:33 offset1:41
	ds_read2_b32 v[10:11], v94 offset0:66 offset1:74
	ds_read2_b32 v[12:13], v94 offset0:99 offset1:107
	ds_read2_b32 v[14:15], v94 offset0:132 offset1:140
	s_waitcnt lgkmcnt(0)
	v_bfe_u32 v0, v4, 16, 1
	v_add3_u32 v0, v4, v0, s65
	v_bfe_u32 v1, v8, 16, 1
	v_lshrrev_b32_e32 v0, 16, v0
	v_add3_u32 v1, v8, v1, s65
	ds_read2_b32 v[88:89], v94 offset0:165 offset1:173
	v_and_or_b32 v0, v1, s66, v0
	v_bfe_u32 v1, v10, 16, 1
	v_add3_u32 v1, v10, v1, s65
	v_bfe_u32 v2, v12, 16, 1
	ds_read2_b32 v[90:91], v94 offset0:198 offset1:206
	v_lshrrev_b32_e32 v1, 16, v1
	v_add3_u32 v2, v12, v2, s65
	ds_read2_b32 v[112:113], v94 offset0:231 offset1:239
	v_and_or_b32 v1, v2, s66, v1
	v_bfe_u32 v2, v14, 16, 1
	s_lshr_b32 s4, s1, 9
	s_mov_b32 s5, s25
	s_lshl_b32 s1, s24, 9
	v_add3_u32 v2, v14, v2, s65
	s_waitcnt lgkmcnt(2)
	v_bfe_u32 v3, v88, 16, 1
	s_lshl_b64 s[4:5], s[4:5], 21
	s_and_b32 s1, s1, 0x600
	v_lshrrev_b32_e32 v2, 16, v2
	v_add3_u32 v3, v88, v3, s65
	s_add_u32 s3, s40, s4
	v_and_or_b32 v2, v3, s66, v2
	s_waitcnt lgkmcnt(1)
	v_bfe_u32 v3, v90, 16, 1
	s_addc_u32 s4, s41, s5
	s_or_b32 s2, s1, s2
	s_lshl_b32 s0, s0, 1
	v_add3_u32 v3, v90, v3, s65
	s_waitcnt lgkmcnt(0)
	v_bfe_u32 v4, v112, 16, 1
	s_add_u32 s0, s3, s0
	v_lshrrev_b32_e32 v3, 16, v3
	v_add3_u32 v4, v112, v4, s65
	s_addc_u32 s1, s4, 0
	v_lshlrev_b32_e32 v18, 1, v24
	v_and_or_b32 v3, v4, s66, v3
	v_or_b32_e32 v4, s2, v25
	v_lshl_add_u64 v[6:7], s[0:1], 0, v[18:19]
	v_lshlrev_b32_e32 v18, 10, v4
	v_lshl_add_u64 v[114:115], v[6:7], 0, v[18:19]
	global_store_dwordx4 v[114:115], v[0:3], off sc1
	v_bfe_u32 v4, v113, 16, 1
	v_or_b32_e32 v8, s2, v33
	v_bfe_u32 v0, v5, 16, 1
	v_add3_u32 v0, v5, v0, s65
	v_bfe_u32 v1, v9, 16, 1
	v_lshrrev_b32_e32 v0, 16, v0
	v_add3_u32 v1, v9, v1, s65
	v_and_or_b32 v0, v1, s66, v0
	v_bfe_u32 v1, v11, 16, 1
	v_add3_u32 v1, v11, v1, s65
	v_bfe_u32 v2, v13, 16, 1
	v_lshrrev_b32_e32 v1, 16, v1
	v_add3_u32 v2, v13, v2, s65
	v_and_or_b32 v1, v2, s66, v1
	v_bfe_u32 v2, v15, 16, 1
	v_add3_u32 v2, v15, v2, s65
	v_bfe_u32 v3, v89, 16, 1
	v_lshrrev_b32_e32 v2, 16, v2
	v_add3_u32 v3, v89, v3, s65
	v_and_or_b32 v2, v3, s66, v2
	v_bfe_u32 v3, v91, 16, 1
	v_add3_u32 v3, v91, v3, s65
	v_lshrrev_b32_e32 v3, 16, v3
	v_add3_u32 v4, v113, v4, s65
	v_lshlrev_b32_e32 v18, 10, v8
	v_and_or_b32 v3, v4, s66, v3
	ds_read2_b32 v[4:5], v94 offset0:16 offset1:24
	v_lshl_add_u64 v[8:9], v[6:7], 0, v[18:19]
	global_store_dwordx4 v[8:9], v[0:3], off sc1
	ds_read2_b32 v[8:9], v94 offset0:49 offset1:57
	ds_read2_b32 v[10:11], v94 offset0:82 offset1:90
	ds_read2_b32 v[12:13], v94 offset0:115 offset1:123
	s_waitcnt lgkmcnt(3)
	v_bfe_u32 v0, v4, 16, 1
	v_add3_u32 v0, v4, v0, s65
	s_waitcnt lgkmcnt(2)
	v_bfe_u32 v1, v8, 16, 1
	ds_read2_b32 v[14:15], v94 offset0:148 offset1:156
	v_lshrrev_b32_e32 v0, 16, v0
	v_add3_u32 v1, v8, v1, s65
	ds_read2_b32 v[88:89], v94 offset0:181 offset1:189
	v_and_or_b32 v0, v1, s66, v0
	s_waitcnt lgkmcnt(3)
	v_bfe_u32 v1, v10, 16, 1
	v_add3_u32 v1, v10, v1, s65
	s_waitcnt lgkmcnt(2)
	v_bfe_u32 v2, v12, 16, 1
	ds_read2_b32 v[90:91], v94 offset0:214 offset1:222
	v_lshrrev_b32_e32 v1, 16, v1
	v_add3_u32 v2, v12, v2, s65
	ds_read2_b32 v[112:113], v94 offset0:247 offset1:255
	v_and_or_b32 v1, v2, s66, v1
	s_waitcnt lgkmcnt(3)
	v_bfe_u32 v2, v14, 16, 1
	v_add3_u32 v2, v14, v2, s65
	s_waitcnt lgkmcnt(2)
	v_bfe_u32 v3, v88, 16, 1
	v_lshrrev_b32_e32 v2, 16, v2
	v_add3_u32 v3, v88, v3, s65
	v_and_or_b32 v2, v3, s66, v2
	s_waitcnt lgkmcnt(1)
	v_bfe_u32 v3, v90, 16, 1
	v_add3_u32 v3, v90, v3, s65
	s_waitcnt lgkmcnt(0)
	v_bfe_u32 v4, v112, 16, 1
	v_lshrrev_b32_e32 v3, 16, v3
	v_add3_u32 v4, v112, v4, s65
	v_and_or_b32 v3, v4, s66, v3
	v_or_b32_e32 v4, s2, v55
	v_lshlrev_b32_e32 v18, 10, v4
	v_lshl_add_u64 v[114:115], v[6:7], 0, v[18:19]
	global_store_dwordx4 v[114:115], v[0:3], off sc1
	v_bfe_u32 v4, v113, 16, 1
	v_add3_u32 v4, v113, v4, s65
	v_bfe_u32 v0, v5, 16, 1
	v_add3_u32 v0, v5, v0, s65
	v_bfe_u32 v1, v9, 16, 1
	v_lshrrev_b32_e32 v0, 16, v0
	v_add3_u32 v1, v9, v1, s65
	v_and_or_b32 v0, v1, s66, v0
	v_bfe_u32 v1, v11, 16, 1
	v_add3_u32 v1, v11, v1, s65
	v_bfe_u32 v2, v13, 16, 1
	v_lshrrev_b32_e32 v1, 16, v1
	v_add3_u32 v2, v13, v2, s65
	v_and_or_b32 v1, v2, s66, v1
	v_bfe_u32 v2, v15, 16, 1
	v_add3_u32 v2, v15, v2, s65
	v_bfe_u32 v3, v89, 16, 1
	v_lshrrev_b32_e32 v2, 16, v2
	v_add3_u32 v3, v89, v3, s65
	v_and_or_b32 v2, v3, s66, v2
	v_bfe_u32 v3, v91, 16, 1
	v_add3_u32 v3, v91, v3, s65
	v_lshrrev_b32_e32 v3, 16, v3
	v_and_or_b32 v3, v4, s66, v3
	v_or_b32_e32 v4, s2, v57
	v_lshlrev_b32_e32 v18, 10, v4
	v_lshl_add_u64 v[4:5], v[6:7], 0, v[18:19]
	global_store_dwordx4 v[4:5], v[0:3], off sc1
	s_waitcnt lgkmcnt(0)

.LBB0_106:
	s_lshl_b32 s24, s5, 1
	s_lshl_b32 s7, s4, 1
	v_or_b32_e32 v75, s24, v54
	s_add_i32 s27, s24, 4
	v_or_b32_e32 v73, s7, v17
	s_add_i32 s26, s7, 4
	s_add_i32 s72, s24, 8
	v_add_lshl_u32 v18, v75, s1, 11
	v_or_b32_e32 v79, s27, v54
	v_mov_b32_e32 v3, v19
	s_add_i32 s74, s24, 12
	v_add_lshl_u32 v2, v73, s3, 11
	v_or_b32_e32 v77, s26, v17
	v_or_b32_e32 v114, s72, v54
	v_lshl_add_u64 v[90:91], v[18:19], 2, v[0:1]
	v_add_lshl_u32 v18, v79, s1, 11
	v_mov_b32_e32 v5, v19
	s_add_i32 s71, s7, 8
	s_add_i32 s73, s7, 12
	s_add_i32 s76, s24, 16
	v_or_b32_e32 v116, s74, v54
	v_lshl_add_u64 v[2:3], v[2:3], 2, v[0:1]
	v_add_lshl_u32 v4, v77, s3, 11
	v_lshl_add_u64 v[112:113], v[18:19], 2, v[0:1]
	v_add_lshl_u32 v18, v114, s1, 11
	s_add_i32 s78, s24, 20
	v_or_b32_e32 v111, s71, v17
	v_or_b32_e32 v115, s73, v17
	v_or_b32_e32 v118, s76, v54
	v_lshl_add_u64 v[4:5], v[4:5], 2, v[0:1]
	global_load_dword v126, v[90:91], off nt
	global_load_dword v127, v[2:3], off nt
	global_load_dword v128, v[112:113], off nt
	global_load_dword v129, v[4:5], off nt
	v_lshl_add_u64 v[2:3], v[18:19], 2, v[0:1]
	v_add_lshl_u32 v18, v116, s1, 11
	v_mov_b32_e32 v7, v19
	v_mov_b32_e32 v9, v19
	s_add_i32 s75, s7, 16
	s_add_i32 s77, s7, 20
	s_add_i32 s80, s24, 24
	v_or_b32_e32 v120, s78, v54
	v_add_lshl_u32 v6, v111, s3, 11
	v_add_lshl_u32 v8, v115, s3, 11
	v_lshl_add_u64 v[4:5], v[18:19], 2, v[0:1]
	v_add_lshl_u32 v18, v118, s1, 11
	s_add_i32 s79, s7, 24
	s_add_i32 s7, s7, 28
	s_add_i32 s24, s24, 28
	v_or_b32_e32 v117, s75, v17
	v_or_b32_e32 v119, s77, v17
	v_or_b32_e32 v122, s80, v54
	v_lshl_add_u64 v[6:7], v[6:7], 2, v[0:1]
	v_lshl_add_u64 v[8:9], v[8:9], 2, v[0:1]
	global_load_dword v130, v[2:3], off nt
	global_load_dword v131, v[6:7], off nt
	global_load_dword v132, v[4:5], off nt
	global_load_dword v133, v[8:9], off nt
	v_lshl_add_u64 v[2:3], v[18:19], 2, v[0:1]
	v_add_lshl_u32 v18, v120, s1, 11
	v_mov_b32_e32 v11, v19
	v_mov_b32_e32 v13, v19
	v_or_b32_e32 v121, s79, v17
	v_or_b32_e32 v124, s7, v17
	v_or_b32_e32 v123, s24, v54
	v_add_lshl_u32 v10, v117, s3, 11
	v_add_lshl_u32 v12, v119, s3, 11
	v_lshl_add_u64 v[4:5], v[18:19], 2, v[0:1]
	v_add_lshl_u32 v18, v122, s1, 11
	v_mov_b32_e32 v15, v19
	v_mov_b32_e32 v89, v19
	v_add_lshl_u32 v14, v121, s3, 11
	v_add_lshl_u32 v88, v124, s3, 11
	v_lshl_add_u64 v[10:11], v[10:11], 2, v[0:1]
	v_lshl_add_u64 v[12:13], v[12:13], 2, v[0:1]
	global_load_dword v134, v[2:3], off nt
	global_load_dword v135, v[10:11], off nt
	global_load_dword v136, v[4:5], off nt
	global_load_dword v137, v[12:13], off nt
	v_lshl_add_u64 v[2:3], v[18:19], 2, v[0:1]
	v_add_lshl_u32 v18, v123, s1, 11
	v_lshl_add_u64 v[14:15], v[14:15], 2, v[0:1]
	v_lshl_add_u64 v[88:89], v[88:89], 2, v[0:1]
	v_lshl_add_u64 v[4:5], v[18:19], 2, v[0:1]
	global_load_dword v18, v[2:3], off nt
	global_load_dword v138, v[14:15], off nt
	global_load_dword v139, v[4:5], off nt
	global_load_dword v140, v[88:89], off nt
	s_add_i32 s5, s5, 16
	s_add_i32 s4, s4, 16
	s_add_i32 s6, s6, -16
	v_mad_u64_u32 v[2:3], s[26:27], v75, s49, v[56:57]
	s_cmp_lg_u32 s6, 0
	v_mad_u64_u32 v[4:5], s[26:27], v73, s49, v[56:57]
	v_mad_u64_u32 v[6:7], s[26:27], v79, s49, v[56:57]
	v_mad_u64_u32 v[8:9], s[26:27], v77, s49, v[56:57]
	v_mad_u64_u32 v[10:11], s[26:27], v114, s49, v[56:57]
	v_mad_u64_u32 v[12:13], s[26:27], v111, s49, v[56:57]
	v_mad_u64_u32 v[14:15], s[26:27], v116, s49, v[56:57]
	v_mad_u64_u32 v[88:89], s[26:27], v115, s49, v[56:57]
	v_mad_u64_u32 v[90:91], s[26:27], v118, s49, v[56:57]
	v_mad_u64_u32 v[112:113], s[26:27], v117, s49, v[56:57]
	v_mad_u64_u32 v[114:115], s[26:27], v120, s49, v[56:57]
	v_mad_u64_u32 v[116:117], s[26:27], v119, s49, v[56:57]
	v_mad_u64_u32 v[118:119], s[26:27], v122, s49, v[56:57]
	v_mad_u64_u32 v[120:121], s[26:27], v121, s49, v[56:57]
	v_mad_u64_u32 v[122:123], s[26:27], v123, s49, v[56:57]
	v_mad_u64_u32 v[124:125], s[26:27], v124, s49, v[56:57]
	s_waitcnt vmcnt(0)
	ds_write_b32 v2, v126
	ds_write_b32 v4, v127
	ds_write_b32 v6, v128
	ds_write_b32 v8, v129
	ds_write_b32 v10, v130
	ds_write_b32 v12, v131
	ds_write_b32 v14, v132
	ds_write_b32 v88, v133
	ds_write_b32 v90, v134
	ds_write_b32 v112, v135
	ds_write_b32 v114, v136
	ds_write_b32 v116, v137
	ds_write_b32 v118, v18
	ds_write_b32 v120, v138
	ds_write_b32 v122, v139
	ds_write_b32 v124, v140
	s_cbranch_scc1 .LBB0_106
	s_waitcnt lgkmcnt(0)
	ds_read2_b32 v[4:5], v94 offset1:8
	ds_read2_b32 v[8:9], v94 offset0:33 offset1:41
	ds_read2_b32 v[10:11], v94 offset0:66 offset1:74
	ds_read2_b32 v[12:13], v94 offset0:99 offset1:107
	ds_read2_b32 v[14:15], v94 offset0:132 offset1:140
	s_waitcnt lgkmcnt(0)
	v_bfe_u32 v0, v4, 16, 1
	v_add3_u32 v0, v4, v0, s65
	v_bfe_u32 v1, v8, 16, 1
	v_lshrrev_b32_e32 v0, 16, v0
	v_add3_u32 v1, v8, v1, s65
	ds_read2_b32 v[88:89], v94 offset0:165 offset1:173
	v_and_or_b32 v0, v1, s66, v0
	v_bfe_u32 v1, v10, 16, 1
	v_add3_u32 v1, v10, v1, s65
	v_bfe_u32 v2, v12, 16, 1
	ds_read2_b32 v[90:91], v94 offset0:198 offset1:206
	v_lshrrev_b32_e32 v1, 16, v1
	v_add3_u32 v2, v12, v2, s65
	ds_read2_b32 v[112:113], v94 offset0:231 offset1:239
	v_and_or_b32 v1, v2, s66, v1
	v_bfe_u32 v2, v14, 16, 1
	v_add3_u32 v2, v14, v2, s65
	s_waitcnt lgkmcnt(2)
	v_bfe_u32 v3, v88, 16, 1
	v_lshrrev_b32_e32 v2, 16, v2
	v_add3_u32 v3, v88, v3, s65
	s_mul_i32 s2, s2, 0x1600000
	v_and_or_b32 v2, v3, s66, v2
	s_waitcnt lgkmcnt(1)
	v_bfe_u32 v3, v90, 16, 1
	s_add_u32 s2, s42, s2
	v_add3_u32 v3, v90, v3, s65
	s_waitcnt lgkmcnt(0)
	v_bfe_u32 v4, v112, 16, 1
	s_addc_u32 s3, s43, 0
	s_lshl_b32 s1, s1, 1
	v_lshrrev_b32_e32 v3, 16, v3
	v_add3_u32 v4, v112, v4, s65
	s_add_u32 s2, s2, s1
	v_and_or_b32 v3, v4, s66, v3
	v_or_b32_e32 v4, s0, v25
	s_addc_u32 s3, s3, 0
	v_lshlrev_b32_e32 v18, 1, v24
	v_mul_u32_u24_e32 v4, 0x1600, v4
	v_lshl_add_u64 v[6:7], s[2:3], 0, v[18:19]
	v_lshlrev_b32_e32 v18, 1, v4
	v_lshl_add_u64 v[114:115], v[6:7], 0, v[18:19]
	global_store_dwordx4 v[114:115], v[0:3], off sc1
	v_bfe_u32 v4, v113, 16, 1
	v_add3_u32 v4, v113, v4, s65
	v_bfe_u32 v0, v5, 16, 1
	v_add3_u32 v0, v5, v0, s65
	v_bfe_u32 v1, v9, 16, 1
	v_lshrrev_b32_e32 v0, 16, v0
	v_add3_u32 v1, v9, v1, s65
	v_and_or_b32 v0, v1, s66, v0
	v_bfe_u32 v1, v11, 16, 1
	v_add3_u32 v1, v11, v1, s65
	v_bfe_u32 v2, v13, 16, 1
	v_lshrrev_b32_e32 v1, 16, v1
	v_add3_u32 v2, v13, v2, s65
	v_and_or_b32 v1, v2, s66, v1
	v_bfe_u32 v2, v15, 16, 1
	v_add3_u32 v2, v15, v2, s65
	v_bfe_u32 v3, v89, 16, 1
	v_lshrrev_b32_e32 v2, 16, v2
	v_add3_u32 v3, v89, v3, s65
	v_and_or_b32 v2, v3, s66, v2
	v_bfe_u32 v3, v91, 16, 1
	v_add3_u32 v3, v91, v3, s65
	v_lshrrev_b32_e32 v3, 16, v3
	v_and_or_b32 v3, v4, s66, v3
	v_or_b32_e32 v4, s0, v33
	v_mul_u32_u24_e32 v8, 0x1600, v4
	v_lshlrev_b32_e32 v18, 1, v8
	ds_read2_b32 v[4:5], v94 offset0:16 offset1:24
	v_lshl_add_u64 v[8:9], v[6:7], 0, v[18:19]
	global_store_dwordx4 v[8:9], v[0:3], off sc1
	ds_read2_b32 v[8:9], v94 offset0:49 offset1:57
	ds_read2_b32 v[10:11], v94 offset0:82 offset1:90
	ds_read2_b32 v[12:13], v94 offset0:115 offset1:123
	s_waitcnt lgkmcnt(3)
	v_bfe_u32 v0, v4, 16, 1
	v_add3_u32 v0, v4, v0, s65
	s_waitcnt lgkmcnt(2)
	v_bfe_u32 v1, v8, 16, 1
	ds_read2_b32 v[14:15], v94 offset0:148 offset1:156
	v_lshrrev_b32_e32 v0, 16, v0
	v_add3_u32 v1, v8, v1, s65
	ds_read2_b32 v[88:89], v94 offset0:181 offset1:189
	v_and_or_b32 v0, v1, s66, v0
	s_waitcnt lgkmcnt(3)
	v_bfe_u32 v1, v10, 16, 1
	v_add3_u32 v1, v10, v1, s65
	s_waitcnt lgkmcnt(2)
	v_bfe_u32 v2, v12, 16, 1
	ds_read2_b32 v[90:91], v94 offset0:214 offset1:222
	v_lshrrev_b32_e32 v1, 16, v1
	v_add3_u32 v2, v12, v2, s65
	ds_read2_b32 v[112:113], v94 offset0:247 offset1:255
	v_and_or_b32 v1, v2, s66, v1
	s_waitcnt lgkmcnt(3)
	v_bfe_u32 v2, v14, 16, 1
	v_add3_u32 v2, v14, v2, s65
	s_waitcnt lgkmcnt(2)
	v_bfe_u32 v3, v88, 16, 1
	v_lshrrev_b32_e32 v2, 16, v2
	v_add3_u32 v3, v88, v3, s65
	v_and_or_b32 v2, v3, s66, v2
	s_waitcnt lgkmcnt(1)
	v_bfe_u32 v3, v90, 16, 1
	v_add3_u32 v3, v90, v3, s65
	s_waitcnt lgkmcnt(0)
	v_bfe_u32 v4, v112, 16, 1
	v_lshrrev_b32_e32 v3, 16, v3
	v_add3_u32 v4, v112, v4, s65
	v_and_or_b32 v3, v4, s66, v3
	v_or_b32_e32 v4, s0, v55
	v_mul_u32_u24_e32 v4, 0x1600, v4
	v_lshlrev_b32_e32 v18, 1, v4
	v_lshl_add_u64 v[114:115], v[6:7], 0, v[18:19]
	global_store_dwordx4 v[114:115], v[0:3], off sc1
	v_bfe_u32 v4, v113, 16, 1
	v_add3_u32 v4, v113, v4, s65
	v_bfe_u32 v0, v5, 16, 1
	v_add3_u32 v0, v5, v0, s65
	v_bfe_u32 v1, v9, 16, 1
	v_lshrrev_b32_e32 v0, 16, v0
	v_add3_u32 v1, v9, v1, s65
	v_and_or_b32 v0, v1, s66, v0
	v_bfe_u32 v1, v11, 16, 1
	v_add3_u32 v1, v11, v1, s65
	v_bfe_u32 v2, v13, 16, 1
	v_lshrrev_b32_e32 v1, 16, v1
	v_add3_u32 v2, v13, v2, s65
	v_and_or_b32 v1, v2, s66, v1
	v_bfe_u32 v2, v15, 16, 1
	v_add3_u32 v2, v15, v2, s65
	v_bfe_u32 v3, v89, 16, 1
	v_lshrrev_b32_e32 v2, 16, v2
	v_add3_u32 v3, v89, v3, s65
	v_and_or_b32 v2, v3, s66, v2
	v_bfe_u32 v3, v91, 16, 1
	v_add3_u32 v3, v91, v3, s65
	v_lshrrev_b32_e32 v3, 16, v3
	v_and_or_b32 v3, v4, s66, v3
	v_or_b32_e32 v4, s0, v57
	v_mul_u32_u24_e32 v4, 0x1600, v4
	v_lshlrev_b32_e32 v18, 1, v4
	v_lshl_add_u64 v[4:5], v[6:7], 0, v[18:19]
	global_store_dwordx4 v[4:5], v[0:3], off sc1
	s_waitcnt lgkmcnt(0)

.LBB0_111:
	s_lshl_b32 s24, s1, 1
	s_lshl_b32 s7, s5, 1
	v_or_b32_e32 v75, s24, v54
	s_add_i32 s27, s24, 4
	v_or_b32_e32 v73, s7, v17
	s_add_i32 s26, s7, 4
	s_add_i32 s71, s7, 8
	s_add_i32 s72, s24, 8
	s_add_i32 s73, s7, 12
	s_add_i32 s75, s7, 16
	s_add_i32 s77, s7, 20
	s_add_i32 s79, s7, 24
	s_add_i32 s7, s7, 28
	v_add_u32_e32 v4, s3, v75
	v_or_b32_e32 v79, s27, v54
	s_add_i32 s74, s24, 12
	v_add_u32_e32 v2, s4, v73
	v_or_b32_e32 v77, s26, v17
	v_or_b32_e32 v111, s71, v17
	v_or_b32_e32 v114, s72, v54
	v_or_b32_e32 v115, s73, v17
	v_or_b32_e32 v117, s75, v17
	v_or_b32_e32 v119, s77, v17
	v_or_b32_e32 v121, s79, v17
	v_or_b32_e32 v124, s7, v17
	v_mul_lo_u32 v18, v4, s68
	v_add_u32_e32 v6, s3, v79
	v_mov_b32_e32 v3, v19
	s_add_i32 s76, s24, 16
	v_or_b32_e32 v116, s74, v54
	v_mul_lo_u32 v2, v2, s68
	v_add_u32_e32 v4, s4, v77
	v_add_u32_e32 v125, s3, v114
	v_add_u32_e32 v8, s4, v111
	v_add_u32_e32 v10, s4, v115
	v_add_u32_e32 v12, s4, v117
	v_add_u32_e32 v14, s4, v119
	v_add_u32_e32 v88, s4, v121
	v_add_u32_e32 v112, s4, v124
	v_lshl_add_u64 v[90:91], v[18:19], 2, v[0:1]
	v_mul_lo_u32 v18, v6, s68
	v_mov_b32_e32 v5, v19
	s_add_i32 s78, s24, 20
	v_or_b32_e32 v118, s76, v54
	v_add_u32_e32 v126, s3, v116
	v_lshl_add_u64 v[2:3], v[2:3], 2, v[0:1]
	v_mul_lo_u32 v4, v4, s68
	v_mul_lo_u32 v6, v8, s68
	v_mul_lo_u32 v8, v10, s68
	v_mul_lo_u32 v10, v12, s68
	v_mul_lo_u32 v12, v14, s68
	v_mul_lo_u32 v14, v88, s68
	v_mul_lo_u32 v88, v112, s68
	v_lshl_add_u64 v[112:113], v[18:19], 2, v[0:1]
	v_mul_lo_u32 v18, v125, s68
	s_add_i32 s80, s24, 24
	v_or_b32_e32 v120, s78, v54
	v_add_u32_e32 v127, s3, v118
	v_lshl_add_u64 v[4:5], v[4:5], 2, v[0:1]
	global_load_dword v131, v[90:91], off nt
	global_load_dword v132, v[2:3], off nt
	global_load_dword v133, v[112:113], off nt
	global_load_dword v134, v[4:5], off nt
	v_lshl_add_u64 v[2:3], v[18:19], 2, v[0:1]
	v_mul_lo_u32 v18, v126, s68
	v_mov_b32_e32 v7, v19
	v_mov_b32_e32 v9, v19
	s_add_i32 s24, s24, 28
	v_or_b32_e32 v122, s80, v54
	v_add_u32_e32 v128, s3, v120
	v_lshl_add_u64 v[4:5], v[18:19], 2, v[0:1]
	v_mul_lo_u32 v18, v127, s68
	v_or_b32_e32 v123, s24, v54
	v_add_u32_e32 v129, s3, v122
	v_lshl_add_u64 v[6:7], v[6:7], 2, v[0:1]
	v_lshl_add_u64 v[8:9], v[8:9], 2, v[0:1]
	global_load_dword v126, v[2:3], off nt
	global_load_dword v127, v[6:7], off nt
	global_load_dword v135, v[4:5], off nt
	global_load_dword v136, v[8:9], off nt
	v_lshl_add_u64 v[2:3], v[18:19], 2, v[0:1]
	v_mul_lo_u32 v18, v128, s68
	v_mov_b32_e32 v11, v19
	v_mov_b32_e32 v13, v19
	v_add_u32_e32 v130, s3, v123
	v_lshl_add_u64 v[4:5], v[18:19], 2, v[0:1]
	v_mul_lo_u32 v18, v129, s68
	v_mov_b32_e32 v15, v19
	v_mov_b32_e32 v89, v19
	v_lshl_add_u64 v[10:11], v[10:11], 2, v[0:1]
	v_lshl_add_u64 v[12:13], v[12:13], 2, v[0:1]
	global_load_dword v128, v[2:3], off nt
	global_load_dword v129, v[10:11], off nt
	global_load_dword v137, v[4:5], off nt
	global_load_dword v138, v[12:13], off nt
	v_lshl_add_u64 v[2:3], v[18:19], 2, v[0:1]
	v_mul_lo_u32 v18, v130, s68
	v_lshl_add_u64 v[14:15], v[14:15], 2, v[0:1]
	v_lshl_add_u64 v[88:89], v[88:89], 2, v[0:1]
	v_lshl_add_u64 v[4:5], v[18:19], 2, v[0:1]
	global_load_dword v18, v[2:3], off nt
	global_load_dword v130, v[14:15], off nt
	global_load_dword v139, v[4:5], off nt
	global_load_dword v140, v[88:89], off nt
	s_add_i32 s1, s1, 16
	s_add_i32 s5, s5, 16
	s_add_i32 s6, s6, -16
	v_mad_u64_u32 v[2:3], s[26:27], v75, s49, v[56:57]
	s_cmp_lg_u32 s6, 0
	v_mad_u64_u32 v[4:5], s[26:27], v73, s49, v[56:57]
	v_mad_u64_u32 v[6:7], s[26:27], v79, s49, v[56:57]
	v_mad_u64_u32 v[8:9], s[26:27], v77, s49, v[56:57]
	v_mad_u64_u32 v[10:11], s[26:27], v114, s49, v[56:57]
	v_mad_u64_u32 v[12:13], s[26:27], v111, s49, v[56:57]
	v_mad_u64_u32 v[14:15], s[26:27], v116, s49, v[56:57]
	v_mad_u64_u32 v[88:89], s[26:27], v115, s49, v[56:57]
	v_mad_u64_u32 v[90:91], s[26:27], v118, s49, v[56:57]
	v_mad_u64_u32 v[112:113], s[26:27], v117, s49, v[56:57]
	v_mad_u64_u32 v[114:115], s[26:27], v120, s49, v[56:57]
	v_mad_u64_u32 v[116:117], s[26:27], v119, s49, v[56:57]
	v_mad_u64_u32 v[118:119], s[26:27], v122, s49, v[56:57]
	v_mad_u64_u32 v[120:121], s[26:27], v121, s49, v[56:57]
	v_mad_u64_u32 v[122:123], s[26:27], v123, s49, v[56:57]
	v_mad_u64_u32 v[124:125], s[26:27], v124, s49, v[56:57]
	s_waitcnt vmcnt(0)
	ds_write_b32 v2, v131
	ds_write_b32 v4, v132
	ds_write_b32 v6, v133
	ds_write_b32 v8, v134
	ds_write_b32 v10, v126
	ds_write_b32 v12, v127
	ds_write_b32 v14, v135
	ds_write_b32 v88, v136
	ds_write_b32 v90, v128
	ds_write_b32 v112, v129
	ds_write_b32 v114, v137
	ds_write_b32 v116, v138
	ds_write_b32 v118, v18
	ds_write_b32 v120, v130
	ds_write_b32 v122, v139
	ds_write_b32 v124, v140
	s_cbranch_scc1 .LBB0_111
	s_waitcnt lgkmcnt(0)
	ds_read2_b32 v[4:5], v94 offset1:8
	ds_read2_b32 v[8:9], v94 offset0:33 offset1:41
	ds_read2_b32 v[10:11], v94 offset0:66 offset1:74
	ds_read2_b32 v[12:13], v94 offset0:99 offset1:107
	ds_read2_b32 v[14:15], v94 offset0:132 offset1:140
	s_waitcnt lgkmcnt(0)
	v_bfe_u32 v0, v4, 16, 1
	v_add3_u32 v0, v4, v0, s65
	v_bfe_u32 v1, v8, 16, 1
	v_lshrrev_b32_e32 v0, 16, v0
	v_add3_u32 v1, v8, v1, s65
	ds_read2_b32 v[88:89], v94 offset0:165 offset1:173
	v_and_or_b32 v0, v1, s66, v0
	v_bfe_u32 v1, v10, 16, 1
	v_add3_u32 v1, v10, v1, s65
	v_bfe_u32 v2, v12, 16, 1
	ds_read2_b32 v[90:91], v94 offset0:198 offset1:206
	v_lshrrev_b32_e32 v1, 16, v1
	v_add3_u32 v2, v12, v2, s65
	ds_read2_b32 v[112:113], v94 offset0:231 offset1:239
	v_and_or_b32 v1, v2, s66, v1
	v_bfe_u32 v2, v14, 16, 1
	v_add3_u32 v2, v14, v2, s65
	s_waitcnt lgkmcnt(2)
	v_bfe_u32 v3, v88, 16, 1
	s_add_u32 s1, s44, s2
	v_lshrrev_b32_e32 v2, 16, v2
	v_add3_u32 v3, v88, v3, s65
	s_addc_u32 s4, s45, 0
	s_and_b32 s2, 0xffff, s3
	v_and_or_b32 v2, v3, s66, v2
	s_waitcnt lgkmcnt(1)
	v_bfe_u32 v3, v90, 16, 1
	s_lshl_b32 s2, s2, 1
	v_add3_u32 v3, v90, v3, s65
	s_waitcnt lgkmcnt(0)
	v_bfe_u32 v4, v112, 16, 1
	s_add_u32 s2, s1, s2
	v_lshrrev_b32_e32 v3, 16, v3
	v_add3_u32 v4, v112, v4, s65
	s_addc_u32 s3, s4, 0
	v_lshlrev_b32_e32 v18, 1, v24
	v_and_or_b32 v3, v4, s66, v3
	v_or_b32_e32 v4, s0, v25
	v_lshl_add_u64 v[6:7], s[2:3], 0, v[18:19]
	v_lshlrev_b32_e32 v18, 12, v4
	v_lshl_add_u64 v[114:115], v[6:7], 0, v[18:19]
	global_store_dwordx4 v[114:115], v[0:3], off sc1
	v_bfe_u32 v4, v113, 16, 1
	v_or_b32_e32 v8, s0, v33
	v_bfe_u32 v0, v5, 16, 1
	v_add3_u32 v0, v5, v0, s65
	v_bfe_u32 v1, v9, 16, 1
	v_lshrrev_b32_e32 v0, 16, v0
	v_add3_u32 v1, v9, v1, s65
	v_and_or_b32 v0, v1, s66, v0
	v_bfe_u32 v1, v11, 16, 1
	v_add3_u32 v1, v11, v1, s65
	v_bfe_u32 v2, v13, 16, 1
	v_lshrrev_b32_e32 v1, 16, v1
	v_add3_u32 v2, v13, v2, s65
	v_and_or_b32 v1, v2, s66, v1
	v_bfe_u32 v2, v15, 16, 1
	v_add3_u32 v2, v15, v2, s65
	v_bfe_u32 v3, v89, 16, 1
	v_lshrrev_b32_e32 v2, 16, v2
	v_add3_u32 v3, v89, v3, s65
	v_and_or_b32 v2, v3, s66, v2
	v_bfe_u32 v3, v91, 16, 1
	v_add3_u32 v3, v91, v3, s65
	v_lshrrev_b32_e32 v3, 16, v3
	v_add3_u32 v4, v113, v4, s65
	v_lshlrev_b32_e32 v18, 12, v8
	v_and_or_b32 v3, v4, s66, v3
	ds_read2_b32 v[4:5], v94 offset0:16 offset1:24
	v_lshl_add_u64 v[8:9], v[6:7], 0, v[18:19]
	global_store_dwordx4 v[8:9], v[0:3], off sc1
	ds_read2_b32 v[8:9], v94 offset0:49 offset1:57
	ds_read2_b32 v[10:11], v94 offset0:82 offset1:90
	ds_read2_b32 v[12:13], v94 offset0:115 offset1:123
	s_waitcnt lgkmcnt(3)
	v_bfe_u32 v0, v4, 16, 1
	v_add3_u32 v0, v4, v0, s65
	s_waitcnt lgkmcnt(2)
	v_bfe_u32 v1, v8, 16, 1
	ds_read2_b32 v[14:15], v94 offset0:148 offset1:156
	v_lshrrev_b32_e32 v0, 16, v0
	v_add3_u32 v1, v8, v1, s65
	ds_read2_b32 v[88:89], v94 offset0:181 offset1:189
	v_and_or_b32 v0, v1, s66, v0
	s_waitcnt lgkmcnt(3)
	v_bfe_u32 v1, v10, 16, 1
	v_add3_u32 v1, v10, v1, s65
	s_waitcnt lgkmcnt(2)
	v_bfe_u32 v2, v12, 16, 1
	ds_read2_b32 v[90:91], v94 offset0:214 offset1:222
	v_lshrrev_b32_e32 v1, 16, v1
	v_add3_u32 v2, v12, v2, s65
	ds_read2_b32 v[112:113], v94 offset0:247 offset1:255
	v_and_or_b32 v1, v2, s66, v1
	s_waitcnt lgkmcnt(3)
	v_bfe_u32 v2, v14, 16, 1
	v_add3_u32 v2, v14, v2, s65
	s_waitcnt lgkmcnt(2)
	v_bfe_u32 v3, v88, 16, 1
	v_lshrrev_b32_e32 v2, 16, v2
	v_add3_u32 v3, v88, v3, s65
	v_and_or_b32 v2, v3, s66, v2
	s_waitcnt lgkmcnt(1)
	v_bfe_u32 v3, v90, 16, 1
	v_add3_u32 v3, v90, v3, s65
	s_waitcnt lgkmcnt(0)
	v_bfe_u32 v4, v112, 16, 1
	v_lshrrev_b32_e32 v3, 16, v3
	v_add3_u32 v4, v112, v4, s65
	v_and_or_b32 v3, v4, s66, v3
	v_or_b32_e32 v4, s0, v55
	v_lshlrev_b32_e32 v18, 12, v4
	v_lshl_add_u64 v[114:115], v[6:7], 0, v[18:19]
	global_store_dwordx4 v[114:115], v[0:3], off sc1
	v_bfe_u32 v4, v113, 16, 1
	v_add3_u32 v4, v113, v4, s65
	v_bfe_u32 v0, v5, 16, 1
	v_add3_u32 v0, v5, v0, s65
	v_bfe_u32 v1, v9, 16, 1
	v_lshrrev_b32_e32 v0, 16, v0
	v_add3_u32 v1, v9, v1, s65
	v_and_or_b32 v0, v1, s66, v0
	v_bfe_u32 v1, v11, 16, 1
	v_add3_u32 v1, v11, v1, s65
	v_bfe_u32 v2, v13, 16, 1
	v_lshrrev_b32_e32 v1, 16, v1
	v_add3_u32 v2, v13, v2, s65
	v_and_or_b32 v1, v2, s66, v1
	v_bfe_u32 v2, v15, 16, 1
	v_add3_u32 v2, v15, v2, s65
	v_bfe_u32 v3, v89, 16, 1
	v_lshrrev_b32_e32 v2, 16, v2
	v_add3_u32 v3, v89, v3, s65
	v_and_or_b32 v2, v3, s66, v2
	v_bfe_u32 v3, v91, 16, 1
	v_add3_u32 v3, v91, v3, s65
	v_lshrrev_b32_e32 v3, 16, v3
	v_and_or_b32 v3, v4, s66, v3
	v_or_b32_e32 v4, s0, v57
	v_lshlrev_b32_e32 v18, 12, v4
	v_lshl_add_u64 v[4:5], v[6:7], 0, v[18:19]
	global_store_dwordx4 v[4:5], v[0:3], off sc1
	s_waitcnt lgkmcnt(0)

.LBB0_551:
	s_lshl_b32 s0, s22, 8
	s_add_i32 s0, s0, s72
	s_cmp_ge_i32 s20, s41
	s_cselect_b64 s[24:25], -1, 0
	v_mbcnt_lo_u32_b32 v0, -1, 0
	v_mbcnt_hi_u32_b32 v0, -1, v0
	s_nop 0
	v_and_or_b32 v130, v0, 15, s0
	s_and_b64 s[0:1], s[24:25], exec
	s_cselect_b32 s0, s41, 0
	s_cselect_b32 s1, s40, 0x18000
	s_sub_i32 s0, s20, s0
	s_lshl_b32 s1, s1, 3
	s_add_u32 s22, s56, s1
	s_addc_u32 s23, s57, 0
	s_cmp_gt_i32 s0, 7
	s_cselect_b64 s[26:27], -1, 0
	s_and_b64 s[28:29], s[24:25], s[26:27]
	v_or_b32_e32 v138, 16, v130
	v_or_b32_e32 v136, 32, v130
	v_or_b32_e32 v134, 48, v130
	v_bfe_u32 v144, v0, 4, 2
	s_mov_b64 s[26:27], -1
	s_and_b64 vcc, exec, s[28:29]
	v_ashrrev_i32_e32 v131, 31, v130
	v_ashrrev_i32_e32 v139, 31, v138
	v_ashrrev_i32_e32 v137, 31, v136
	v_ashrrev_i32_e32 v135, 31, v134
	s_cbranch_vccnz .LBB0_554
	v_lshl_add_u64 v[132:133], v[130:131], 3, s[22:23]
	global_load_dwordx2 v[140:141], v[132:133], off
	s_cmp_lt_i32 s0, 8
	s_mov_b32 s1, 0x1b700000
	s_cselect_b32 s1, s1, 0x1f700000
	s_and_b64 s[24:25], s[24:25], exec
	s_cselect_b32 s1, 0x25900000, s1
	s_add_u32 s24, s6, s1
	s_addc_u32 s25, s7, 0
	s_lshl_b32 s1, s20, 8
	s_and_b32 s1, s1, 0x700
	v_lshl_or_b32 v0, v144, 3, s1
	v_readlane_b32 s1, v255, 26
	s_mov_b64 s[20:21], 0x80000
	s_nop 0
	v_or_b32_e32 v0, s1, v0
	v_lshlrev_b32_e32 v0, 1, v0
	v_lshl_add_u64 v[142:143], s[24:25], 0, v[0:1]
	s_mov_b32 s1, 0x80000
	s_waitcnt vmcnt(0)
	v_xor_b32_e32 v0, v140, v141
	v_ashrrev_i32_e32 v0, 31, v0
	v_ffbh_i32_e32 v145, v141
	v_add_u32_e32 v0, 32, v0
	v_add_u32_e32 v145, -1, v145
	v_min_u32_e32 v0, v145, v0
	v_lshlrev_b64 v[140:141], v0, v[140:141]
	v_min_u32_e32 v140, 1, v140
	v_or_b32_e32 v140, v141, v140
	v_cvt_f32_i32_e32 v140, v140
	v_sub_u32_e32 v0, 32, v0
	v_ldexp_f32 v0, v140, v0
	v_mul_f32_e32 v0, 0x35800000, v0
	v_fmamk_f32 v0, v0, 0x3b000000, v180
	v_cmp_gt_f32_e32 vcc, s73, v0
	v_mul_f32_e32 v140, 0x4b800000, v0
	s_nop 0
	v_cndmask_b32_e32 v0, v0, v140, vcc
	v_rsq_f32_e32 v0, v0
	s_nop 0
	v_mul_f32_e32 v140, 0x45800000, v0
	v_cndmask_b32_e32 v0, v0, v140, vcc
	v_lshlrev_b64 v[140:141], 12, v[130:131]
	v_pk_mul_f32 v[154:155], v[124:125], v[0:1] op_sel_hi:[1,0]
	v_pk_mul_f32 v[152:153], v[122:123], v[0:1] op_sel_hi:[1,0]
	v_lshl_add_u64 v[140:141], v[142:143], 0, v[140:141]
	v_pk_mul_f32 v[156:157], v[116:117], v[0:1] op_sel_hi:[1,0]
	v_pk_mul_f32 v[158:159], v[114:115], v[0:1] op_sel_hi:[1,0]
	v_cvt_pk_bf16_f32 v152, v152, v153
	v_cvt_pk_bf16_f32 v153, v154, v155
	s_nop 0
	v_cvt_pk_bf16_f32 v154, v158, v159
	v_cvt_pk_bf16_f32 v155, v156, v157
	flat_store_dwordx4 v[140:141], v[152:155] sc1
	v_pk_mul_f32 v[156:157], v[120:121], v[0:1] op_sel_hi:[1,0]
	v_pk_mul_f32 v[158:159], v[118:119], v[0:1] op_sel_hi:[1,0]
	v_pk_mul_f32 v[154:155], v[128:129], v[0:1] op_sel_hi:[1,0]
	v_pk_mul_f32 v[152:153], v[126:127], v[0:1] op_sel_hi:[1,0]
	s_nop 0
	v_cvt_pk_bf16_f32 v152, v152, v153
	v_cvt_pk_bf16_f32 v153, v154, v155
	v_cvt_pk_bf16_f32 v154, v158, v159
	v_cvt_pk_bf16_f32 v155, v156, v157
	flat_store_dwordx4 v[140:141], v[152:155] offset:256 sc1
	global_load_dwordx2 v[152:153], v[132:133], off offset:128
	s_waitcnt vmcnt(0)
	v_xor_b32_e32 v0, v152, v153
	v_ashrrev_i32_e32 v0, 31, v0
	v_ffbh_i32_e32 v145, v153
	v_add_u32_e32 v0, 32, v0
	v_add_u32_e32 v145, -1, v145
	v_min_u32_e32 v0, v145, v0
	v_lshlrev_b64 v[152:153], v0, v[152:153]
	v_min_u32_e32 v145, 1, v152
	v_or_b32_e32 v145, v153, v145
	v_cvt_f32_i32_e32 v145, v145
	v_sub_u32_e32 v0, 32, v0
	v_lshlrev_b64 v[152:153], 12, v[138:139]
	v_lshl_add_u64 v[156:157], v[142:143], 0, v[152:153]
	v_ldexp_f32 v0, v145, v0
	v_mul_f32_e32 v0, 0x35800000, v0
	v_fmamk_f32 v0, v0, 0x3b000000, v180
	v_cmp_gt_f32_e32 vcc, s73, v0
	v_mul_f32_e32 v145, 0x4b800000, v0
	s_nop 0
	v_cndmask_b32_e32 v0, v0, v145, vcc
	v_rsq_f32_e32 v0, v0
	s_nop 0
	v_mul_f32_e32 v145, 0x45800000, v0
	v_cndmask_b32_e32 v0, v0, v145, vcc
	v_pk_mul_f32 v[154:155], v[108:109], v[0:1] op_sel_hi:[1,0]
	v_pk_mul_f32 v[152:153], v[106:107], v[0:1] op_sel_hi:[1,0]
	v_pk_mul_f32 v[158:159], v[100:101], v[0:1] op_sel_hi:[1,0]
	v_pk_mul_f32 v[160:161], v[98:99], v[0:1] op_sel_hi:[1,0]
	v_cvt_pk_bf16_f32 v152, v152, v153
	v_cvt_pk_bf16_f32 v153, v154, v155
	s_nop 0
	v_cvt_pk_bf16_f32 v154, v160, v161
	v_cvt_pk_bf16_f32 v155, v158, v159
	flat_store_dwordx4 v[156:157], v[152:155] sc1
	v_pk_mul_f32 v[158:159], v[104:105], v[0:1] op_sel_hi:[1,0]
	v_pk_mul_f32 v[160:161], v[102:103], v[0:1] op_sel_hi:[1,0]
	v_pk_mul_f32 v[154:155], v[112:113], v[0:1] op_sel_hi:[1,0]
	v_pk_mul_f32 v[152:153], v[110:111], v[0:1] op_sel_hi:[1,0]
	s_nop 0
	v_cvt_pk_bf16_f32 v152, v152, v153
	v_cvt_pk_bf16_f32 v153, v154, v155
	v_cvt_pk_bf16_f32 v154, v160, v161
	v_cvt_pk_bf16_f32 v155, v158, v159
	flat_store_dwordx4 v[156:157], v[152:155] offset:256 sc1
	global_load_dwordx2 v[152:153], v[132:133], off offset:256
	s_waitcnt vmcnt(0)
	v_xor_b32_e32 v0, v152, v153
	v_ashrrev_i32_e32 v0, 31, v0
	v_ffbh_i32_e32 v145, v153
	v_add_u32_e32 v0, 32, v0
	v_add_u32_e32 v145, -1, v145
	v_min_u32_e32 v0, v145, v0
	v_lshlrev_b64 v[152:153], v0, v[152:153]
	v_min_u32_e32 v145, 1, v152
	v_or_b32_e32 v145, v153, v145
	v_cvt_f32_i32_e32 v145, v145
	v_sub_u32_e32 v0, 32, v0
	v_lshlrev_b64 v[152:153], 12, v[136:137]
	v_lshl_add_u64 v[156:157], v[142:143], 0, v[152:153]
	v_ldexp_f32 v0, v145, v0
	v_mul_f32_e32 v0, 0x35800000, v0
	v_fmamk_f32 v0, v0, 0x3b000000, v180
	v_cmp_gt_f32_e32 vcc, s73, v0
	v_mul_f32_e32 v145, 0x4b800000, v0
	s_nop 0
	v_cndmask_b32_e32 v0, v0, v145, vcc
	v_rsq_f32_e32 v0, v0
	s_nop 0
	v_mul_f32_e32 v145, 0x45800000, v0
	v_cndmask_b32_e32 v0, v0, v145, vcc
	v_pk_mul_f32 v[154:155], v[92:93], v[0:1] op_sel_hi:[1,0]
	v_pk_mul_f32 v[152:153], v[90:91], v[0:1] op_sel_hi:[1,0]
	v_pk_mul_f32 v[158:159], v[84:85], v[0:1] op_sel_hi:[1,0]
	v_pk_mul_f32 v[160:161], v[82:83], v[0:1] op_sel_hi:[1,0]
	v_cvt_pk_bf16_f32 v152, v152, v153
	v_cvt_pk_bf16_f32 v153, v154, v155
	s_nop 0
	v_cvt_pk_bf16_f32 v154, v160, v161
	v_cvt_pk_bf16_f32 v155, v158, v159
	flat_store_dwordx4 v[156:157], v[152:155] sc1
	v_pk_mul_f32 v[158:159], v[88:89], v[0:1] op_sel_hi:[1,0]
	v_pk_mul_f32 v[160:161], v[86:87], v[0:1] op_sel_hi:[1,0]
	v_pk_mul_f32 v[154:155], v[96:97], v[0:1] op_sel_hi:[1,0]
	v_pk_mul_f32 v[152:153], v[94:95], v[0:1] op_sel_hi:[1,0]
	s_nop 0
	v_cvt_pk_bf16_f32 v152, v152, v153
	v_cvt_pk_bf16_f32 v153, v154, v155
	v_cvt_pk_bf16_f32 v154, v160, v161
	v_cvt_pk_bf16_f32 v155, v158, v159
	flat_store_dwordx4 v[156:157], v[152:155] offset:256 sc1
	global_load_dwordx2 v[152:153], v[132:133], off offset:384
	s_waitcnt vmcnt(0)
	v_xor_b32_e32 v0, v152, v153
	v_ashrrev_i32_e32 v0, 31, v0
	v_ffbh_i32_e32 v145, v153
	v_add_u32_e32 v0, 32, v0
	v_add_u32_e32 v145, -1, v145
	v_min_u32_e32 v0, v145, v0
	v_lshlrev_b64 v[152:153], v0, v[152:153]
	v_min_u32_e32 v145, 1, v152
	v_or_b32_e32 v145, v153, v145
	v_cvt_f32_i32_e32 v145, v145
	v_sub_u32_e32 v0, 32, v0
	v_lshlrev_b64 v[152:153], 12, v[134:135]
	v_lshl_add_u64 v[142:143], v[142:143], 0, v[152:153]
	v_ldexp_f32 v0, v145, v0
	v_mul_f32_e32 v0, 0x35800000, v0
	v_fmamk_f32 v0, v0, 0x3b000000, v180
	v_cmp_gt_f32_e32 vcc, s73, v0
	v_mul_f32_e32 v145, 0x4b800000, v0
	s_nop 0
	v_cndmask_b32_e32 v0, v0, v145, vcc
	v_rsq_f32_e32 v0, v0
	s_nop 0
	v_mul_f32_e32 v145, 0x45800000, v0
	v_cndmask_b32_e32 v0, v0, v145, vcc
	v_pk_mul_f32 v[154:155], v[76:77], v[0:1] op_sel_hi:[1,0]
	v_pk_mul_f32 v[152:153], v[74:75], v[0:1] op_sel_hi:[1,0]
	v_pk_mul_f32 v[156:157], v[68:69], v[0:1] op_sel_hi:[1,0]
	v_pk_mul_f32 v[158:159], v[66:67], v[0:1] op_sel_hi:[1,0]
	v_cvt_pk_bf16_f32 v152, v152, v153
	v_cvt_pk_bf16_f32 v153, v154, v155
	s_nop 0
	v_cvt_pk_bf16_f32 v154, v158, v159
	v_cvt_pk_bf16_f32 v155, v156, v157
	flat_store_dwordx4 v[142:143], v[152:155] sc1
	v_pk_mul_f32 v[156:157], v[72:73], v[0:1] op_sel_hi:[1,0]
	v_pk_mul_f32 v[158:159], v[70:71], v[0:1] op_sel_hi:[1,0]
	v_pk_mul_f32 v[154:155], v[80:81], v[0:1] op_sel_hi:[1,0]
	v_pk_mul_f32 v[152:153], v[78:79], v[0:1] op_sel_hi:[1,0]
	s_nop 0
	v_cvt_pk_bf16_f32 v152, v152, v153
	v_cvt_pk_bf16_f32 v153, v154, v155
	v_cvt_pk_bf16_f32 v154, v158, v159
	v_cvt_pk_bf16_f32 v155, v156, v157
	flat_store_dwordx4 v[142:143], v[152:155] offset:256 sc1
	global_load_dwordx2 v[142:143], v[132:133], off offset:1024
	s_waitcnt vmcnt(0)
	v_xor_b32_e32 v0, v142, v143
	v_ashrrev_i32_e32 v0, 31, v0
	v_ffbh_i32_e32 v145, v143
	v_add_u32_e32 v0, 32, v0
	v_add_u32_e32 v145, -1, v145
	v_min_u32_e32 v0, v145, v0
	v_lshlrev_b64 v[142:143], v0, v[142:143]
	v_min_u32_e32 v142, 1, v142
	v_or_b32_e32 v142, v143, v142
	v_cvt_f32_i32_e32 v142, v142
	v_sub_u32_e32 v0, 32, v0
	v_ldexp_f32 v0, v142, v0
	v_mul_f32_e32 v0, 0x35800000, v0
	v_fmamk_f32 v0, v0, 0x3b000000, v180
	v_cmp_gt_f32_e32 vcc, s73, v0
	v_mul_f32_e32 v142, 0x4b800000, v0
	s_nop 0
	v_cndmask_b32_e32 v0, v0, v142, vcc
	v_rsq_f32_e32 v0, v0
	s_nop 0
	v_mul_f32_e32 v142, 0x45800000, v0
	v_cndmask_b32_e32 v0, v0, v142, vcc
	v_pk_mul_f32 v[154:155], v[60:61], v[0:1] op_sel_hi:[1,0]
	v_pk_mul_f32 v[152:153], v[58:59], v[0:1] op_sel_hi:[1,0]
	v_pk_mul_f32 v[156:157], v[52:53], v[0:1] op_sel_hi:[1,0]
	v_pk_mul_f32 v[158:159], v[50:51], v[0:1] op_sel_hi:[1,0]
	v_cvt_pk_bf16_f32 v152, v152, v153
	v_cvt_pk_bf16_f32 v153, v154, v155
	v_lshl_add_u64 v[142:143], v[140:141], 0, s[20:21]
	v_cvt_pk_bf16_f32 v154, v158, v159
	v_cvt_pk_bf16_f32 v155, v156, v157
	v_add_co_u32_e32 v156, vcc, s1, v140
	v_pk_mul_f32 v[158:159], v[54:55], v[0:1] op_sel_hi:[1,0]
	s_nop 0
	v_addc_co_u32_e32 v157, vcc, 0, v141, vcc
	flat_store_dwordx4 v[156:157], v[152:155] sc1
	v_pk_mul_f32 v[156:157], v[56:57], v[0:1] op_sel_hi:[1,0]
	s_mov_b32 s1, 0x90000
	v_pk_mul_f32 v[154:155], v[64:65], v[0:1] op_sel_hi:[1,0]
	v_pk_mul_f32 v[152:153], v[62:63], v[0:1] op_sel_hi:[1,0]
	s_mov_b64 s[20:21], 0x90000
	v_cvt_pk_bf16_f32 v152, v152, v153
	v_cvt_pk_bf16_f32 v153, v154, v155
	v_cvt_pk_bf16_f32 v154, v158, v159
	v_cvt_pk_bf16_f32 v155, v156, v157
	flat_store_dwordx4 v[142:143], v[152:155] offset:256 sc1
	global_load_dwordx2 v[142:143], v[132:133], off offset:1152
	s_waitcnt vmcnt(0)
	v_xor_b32_e32 v0, v142, v143
	v_ashrrev_i32_e32 v0, 31, v0
	v_ffbh_i32_e32 v145, v143
	v_add_u32_e32 v0, 32, v0
	v_add_u32_e32 v145, -1, v145
	v_min_u32_e32 v0, v145, v0
	v_lshlrev_b64 v[142:143], v0, v[142:143]
	v_min_u32_e32 v142, 1, v142
	v_or_b32_e32 v142, v143, v142
	v_cvt_f32_i32_e32 v142, v142
	v_sub_u32_e32 v0, 32, v0
	v_ldexp_f32 v0, v142, v0
	v_mul_f32_e32 v0, 0x35800000, v0
	v_fmamk_f32 v0, v0, 0x3b000000, v180
	v_cmp_gt_f32_e32 vcc, s73, v0
	v_mul_f32_e32 v142, 0x4b800000, v0
	s_nop 0
	v_cndmask_b32_e32 v0, v0, v142, vcc
	v_rsq_f32_e32 v0, v0
	s_nop 0
	v_mul_f32_e32 v142, 0x45800000, v0
	v_cndmask_b32_e32 v0, v0, v142, vcc
	v_pk_mul_f32 v[154:155], v[44:45], v[0:1] op_sel_hi:[1,0]
	v_pk_mul_f32 v[152:153], v[42:43], v[0:1] op_sel_hi:[1,0]
	v_pk_mul_f32 v[156:157], v[36:37], v[0:1] op_sel_hi:[1,0]
	v_pk_mul_f32 v[158:159], v[34:35], v[0:1] op_sel_hi:[1,0]
	v_cvt_pk_bf16_f32 v152, v152, v153
	v_cvt_pk_bf16_f32 v153, v154, v155
	v_lshl_add_u64 v[142:143], v[140:141], 0, s[20:21]
	v_cvt_pk_bf16_f32 v154, v158, v159
	v_cvt_pk_bf16_f32 v155, v156, v157
	v_add_co_u32_e32 v156, vcc, s1, v140
	v_pk_mul_f32 v[158:159], v[38:39], v[0:1] op_sel_hi:[1,0]
	s_nop 0
	v_addc_co_u32_e32 v157, vcc, 0, v141, vcc
	flat_store_dwordx4 v[156:157], v[152:155] sc1
	v_pk_mul_f32 v[156:157], v[40:41], v[0:1] op_sel_hi:[1,0]
	s_mov_b32 s1, 0xa0000
	v_pk_mul_f32 v[154:155], v[48:49], v[0:1] op_sel_hi:[1,0]
	v_pk_mul_f32 v[152:153], v[46:47], v[0:1] op_sel_hi:[1,0]
	s_mov_b64 s[20:21], 0xa0000
	v_cvt_pk_bf16_f32 v152, v152, v153
	v_cvt_pk_bf16_f32 v153, v154, v155
	v_cvt_pk_bf16_f32 v154, v158, v159
	v_cvt_pk_bf16_f32 v155, v156, v157
	flat_store_dwordx4 v[142:143], v[152:155] offset:256 sc1
	global_load_dwordx2 v[142:143], v[132:133], off offset:1280
	s_waitcnt vmcnt(0)
	v_xor_b32_e32 v0, v142, v143
	v_ashrrev_i32_e32 v0, 31, v0
	v_ffbh_i32_e32 v145, v143
	v_add_u32_e32 v0, 32, v0
	v_add_u32_e32 v145, -1, v145
	v_min_u32_e32 v0, v145, v0
	v_lshlrev_b64 v[142:143], v0, v[142:143]
	v_min_u32_e32 v142, 1, v142
	v_or_b32_e32 v142, v143, v142
	v_cvt_f32_i32_e32 v142, v142
	v_sub_u32_e32 v0, 32, v0
	v_ldexp_f32 v0, v142, v0
	v_mul_f32_e32 v0, 0x35800000, v0
	v_fmamk_f32 v0, v0, 0x3b000000, v180
	v_cmp_gt_f32_e32 vcc, s73, v0
	v_mul_f32_e32 v142, 0x4b800000, v0
	s_nop 0
	v_cndmask_b32_e32 v0, v0, v142, vcc
	v_rsq_f32_e32 v0, v0
	s_nop 0
	v_mul_f32_e32 v142, 0x45800000, v0
	v_cndmask_b32_e32 v0, v0, v142, vcc
	v_pk_mul_f32 v[154:155], v[28:29], v[0:1] op_sel_hi:[1,0]
	v_pk_mul_f32 v[152:153], v[26:27], v[0:1] op_sel_hi:[1,0]
	v_pk_mul_f32 v[156:157], v[20:21], v[0:1] op_sel_hi:[1,0]
	v_pk_mul_f32 v[158:159], v[18:19], v[0:1] op_sel_hi:[1,0]
	v_cvt_pk_bf16_f32 v152, v152, v153
	v_cvt_pk_bf16_f32 v153, v154, v155
	v_lshl_add_u64 v[142:143], v[140:141], 0, s[20:21]
	v_cvt_pk_bf16_f32 v154, v158, v159
	v_cvt_pk_bf16_f32 v155, v156, v157
	v_add_co_u32_e32 v156, vcc, s1, v140
	v_pk_mul_f32 v[158:159], v[22:23], v[0:1] op_sel_hi:[1,0]
	s_nop 0
	v_addc_co_u32_e32 v157, vcc, 0, v141, vcc
	flat_store_dwordx4 v[156:157], v[152:155] sc1
	v_pk_mul_f32 v[156:157], v[24:25], v[0:1] op_sel_hi:[1,0]
	s_mov_b64 s[20:21], 0xb0000
	v_pk_mul_f32 v[154:155], v[32:33], v[0:1] op_sel_hi:[1,0]
	v_pk_mul_f32 v[152:153], v[30:31], v[0:1] op_sel_hi:[1,0]
	s_mov_b32 s1, 0xb0000
	v_cvt_pk_bf16_f32 v152, v152, v153
	v_cvt_pk_bf16_f32 v153, v154, v155
	v_cvt_pk_bf16_f32 v154, v158, v159
	v_cvt_pk_bf16_f32 v155, v156, v157
	flat_store_dwordx4 v[142:143], v[152:155] offset:256 sc1
	global_load_dwordx2 v[132:133], v[132:133], off offset:1408
	s_waitcnt vmcnt(0)
	v_xor_b32_e32 v0, v132, v133
	v_ashrrev_i32_e32 v0, 31, v0
	v_ffbh_i32_e32 v142, v133
	v_add_u32_e32 v0, 32, v0
	v_add_u32_e32 v142, -1, v142
	v_min_u32_e32 v0, v142, v0
	v_lshlrev_b64 v[132:133], v0, v[132:133]
	v_min_u32_e32 v132, 1, v132
	v_or_b32_e32 v132, v133, v132
	v_cvt_f32_i32_e32 v132, v132
	v_sub_u32_e32 v0, 32, v0
	v_ldexp_f32 v0, v132, v0
	v_mul_f32_e32 v0, 0x35800000, v0
	v_fmamk_f32 v0, v0, 0x3b000000, v180
	v_cmp_gt_f32_e32 vcc, s73, v0
	v_mul_f32_e32 v132, 0x4b800000, v0
	s_nop 0
	v_cndmask_b32_e32 v0, v0, v132, vcc
	v_rsq_f32_e32 v0, v0
	s_nop 0
	v_mul_f32_e32 v132, 0x45800000, v0
	v_cndmask_b32_e32 v0, v0, v132, vcc
	v_lshl_add_u64 v[132:133], v[140:141], 0, s[20:21]
	v_add_co_u32_e32 v140, vcc, s1, v140
	v_pk_mul_f32 v[142:143], v[12:13], v[0:1] op_sel_hi:[1,0]
	v_pk_mul_f32 v[152:153], v[10:11], v[0:1] op_sel_hi:[1,0]
	v_pk_mul_f32 v[154:155], v[2:3], v[0:1] op_sel_hi:[1,0]
	v_addc_co_u32_e32 v141, vcc, 0, v141, vcc
	v_pk_mul_f32 v[156:157], v[4:5], v[0:1] op_sel_hi:[1,0]
	v_cvt_pk_bf16_f32 v152, v152, v153
	v_cvt_pk_bf16_f32 v153, v142, v143
	v_cvt_pk_bf16_f32 v154, v154, v155
	v_pk_mul_f32 v[142:143], v[16:17], v[0:1] op_sel_hi:[1,0]
	v_cvt_pk_bf16_f32 v155, v156, v157
	flat_store_dwordx4 v[140:141], v[152:155] sc1
	v_pk_mul_f32 v[140:141], v[14:15], v[0:1] op_sel_hi:[1,0]
	s_nop 0
	v_pk_mul_f32 v[152:153], v[8:9], v[0:1] op_sel_hi:[1,0]
	v_pk_mul_f32 v[154:155], v[6:7], v[0:1] op_sel_hi:[1,0]
	v_cvt_pk_bf16_f32 v140, v140, v141
	v_cvt_pk_bf16_f32 v141, v142, v143
	s_nop 0
	v_cvt_pk_bf16_f32 v142, v154, v155
	v_cvt_pk_bf16_f32 v143, v152, v153
	flat_store_dwordx4 v[132:133], v[140:143] offset:256 sc1
	s_cbranch_execz .LBB0_555

.LBB0_555:
	v_lshl_add_u64 v[132:133], v[130:131], 3, s[22:23]
	global_load_dwordx2 v[140:141], v[132:133], off
	s_lshl_b32 s0, s0, 8
	v_readlane_b32 s1, v254, 57
	s_add_i32 s94, s1, s0
	s_lshl_b64 s[0:1], s[94:95], 1
	s_add_u32 s20, s58, s0
	s_addc_u32 s21, s59, s1
	s_waitcnt vmcnt(0)
	v_xor_b32_e32 v0, v140, v141
	v_ashrrev_i32_e32 v0, 31, v0
	v_ffbh_i32_e32 v142, v141
	v_add_u32_e32 v0, 32, v0
	v_add_u32_e32 v142, -1, v142
	v_min_u32_e32 v0, v142, v0
	v_lshlrev_b64 v[140:141], v0, v[140:141]
	v_min_u32_e32 v140, 1, v140
	v_or_b32_e32 v140, v141, v140
	v_cvt_f32_i32_e32 v140, v140
	v_sub_u32_e32 v0, 32, v0
	v_lshlrev_b64 v[142:143], 8, v[130:131]
	v_lshl_add_u64 v[142:143], s[10:11], 0, v[142:143]
	v_ldexp_f32 v0, v140, v0
	v_mul_f32_e32 v0, 0x35800000, v0
	v_fmamk_f32 v0, v0, 0x3b000000, v180
	v_cmp_gt_f32_e32 vcc, s73, v0
	v_mul_f32_e32 v140, 0x4b800000, v0
	s_nop 0
	v_cndmask_b32_e32 v0, v0, v140, vcc
	v_rsq_f32_e32 v0, v0
	s_nop 0
	v_mul_f32_e32 v140, 0x45800000, v0
	v_cndmask_b32_e32 v140, v0, v140, vcc
	v_lshlrev_b32_e32 v0, 6, v144
	v_lshl_add_u64 v[160:161], v[142:143], 0, v[0:1]
	flat_load_dwordx4 v[152:155], v[160:161]
	v_mov_b32_e32 v142, v122
	v_mov_b32_e32 v143, v126
	v_pk_mul_f32 v[142:143], v[142:143], v[140:141] op_sel_hi:[1,0]
	v_mov_b32_e32 v126, v123
	s_waitcnt vmcnt(0) lgkmcnt(0)
	v_pk_mul_f32 v[156:157], v[152:153], v[142:143]
	s_nop 0
	v_sub_f32_e32 v141, v156, v157
	flat_load_dwordx4 v[156:159], v[160:161] offset:32
	v_pk_mul_f32 v[142:143], v[152:153], v[142:143] op_sel:[0,1] op_sel_hi:[1,0]
	s_nop 0
	v_add_f32_e32 v122, v142, v143
	v_mov_b32_e32 v142, v114
	v_mov_b32_e32 v143, v118
	v_pk_mul_f32 v[152:153], v[142:143], v[140:141] op_sel_hi:[1,0]
	v_mov_b32_e32 v118, v115
	v_pk_mul_f32 v[114:115], v[118:119], v[140:141] op_sel_hi:[1,0]
	s_waitcnt vmcnt(0) lgkmcnt(0)
	v_pk_mul_f32 v[142:143], v[156:157], v[152:153]
	v_pk_mul_f32 v[152:153], v[156:157], v[152:153] op_sel:[0,1] op_sel_hi:[1,0]
	v_sub_f32_e32 v143, v142, v143
	v_add_f32_e32 v142, v152, v153
	v_pk_mul_f32 v[152:153], v[126:127], v[140:141] op_sel_hi:[1,0]
	v_pk_mul_f32 v[118:119], v[158:159], v[114:115]
	v_pk_mul_f32 v[126:127], v[154:155], v[152:153]
	v_pk_mul_f32 v[152:153], v[154:155], v[152:153] op_sel:[0,1] op_sel_hi:[1,0]
	v_pk_mul_f32 v[114:115], v[158:159], v[114:115] op_sel:[0,1] op_sel_hi:[1,0]
	v_add_f32_e32 v123, v152, v153
	flat_load_dwordx4 v[152:155], v[160:161] offset:16
	v_sub_f32_e32 v119, v118, v119
	v_add_f32_e32 v118, v114, v115
	v_mov_b32_e32 v114, v124
	v_mov_b32_e32 v115, v128
	v_pk_mul_f32 v[114:115], v[114:115], v[140:141] op_sel_hi:[1,0]
	v_sub_f32_e32 v126, v126, v127
	v_mov_b32_e32 v128, v125
	s_waitcnt vmcnt(0) lgkmcnt(0)
	v_pk_mul_f32 v[156:157], v[152:153], v[114:115]
	s_nop 0
	v_sub_f32_e32 v127, v156, v157
	flat_load_dwordx4 v[156:159], v[160:161] offset:48
	v_pk_mul_f32 v[114:115], v[114:115], v[152:153] op_sel:[1,0] op_sel_hi:[0,1]
	v_add_f32_e32 v145, v114, v115
	v_mov_b32_e32 v114, v116
	v_mov_b32_e32 v115, v120
	v_pk_mul_f32 v[114:115], v[114:115], v[140:141] op_sel_hi:[1,0]
	v_mov_b32_e32 v120, v117
	s_waitcnt vmcnt(0) lgkmcnt(0)
	v_pk_mul_f32 v[152:153], v[114:115], v[156:157]
	v_pk_mul_f32 v[114:115], v[114:115], v[156:157] op_sel:[1,0] op_sel_hi:[0,1]
	v_sub_f32_e32 v152, v152, v153
	v_add_f32_e32 v153, v114, v115
	v_pk_mul_f32 v[114:115], v[128:129], v[140:141] op_sel_hi:[1,0]
	s_nop 0
	v_pk_mul_f32 v[124:125], v[114:115], v[154:155]
	v_pk_mul_f32 v[114:115], v[114:115], v[154:155] op_sel:[1,0] op_sel_hi:[0,1]
	v_add_f32_e32 v128, v114, v115
	v_pk_mul_f32 v[114:115], v[120:121], v[140:141] op_sel_hi:[1,0]
	v_sub_f32_e32 v125, v124, v125
	v_pk_mul_f32 v[116:117], v[114:115], v[158:159]
	v_pk_mul_f32 v[114:115], v[114:115], v[158:159] op_sel:[1,0] op_sel_hi:[0,1]
	v_add_f32_e32 v140, v114, v115
	v_lshlrev_b64 v[114:115], 11, v[130:131]
	v_sub_f32_e32 v129, v116, v117
	v_lshl_add_u64 v[116:117], s[20:21], 0, v[114:115]
	v_lshlrev_b32_e32 v114, 4, v144
	v_mov_b32_e32 v115, v1
	v_lshl_add_u64 v[120:121], v[116:117], 0, v[114:115]
	v_cvt_pk_bf16_f32 v124, v141, v126
	v_cvt_pk_bf16_f32 v125, v127, v125
	v_cvt_pk_bf16_f32 v126, v143, v119
	v_cvt_pk_bf16_f32 v127, v152, v129
	flat_store_dwordx4 v[120:121], v[124:127] sc1
	v_cvt_pk_bf16_f32 v116, v122, v123
	v_cvt_pk_bf16_f32 v117, v145, v128
	v_cvt_pk_bf16_f32 v118, v142, v118
	v_cvt_pk_bf16_f32 v119, v153, v140
	flat_store_dwordx4 v[120:121], v[116:119] offset:64 sc1
	global_load_dwordx2 v[116:117], v[132:133], off offset:128
	v_mov_b32_e32 v122, v106
	v_mov_b32_e32 v123, v110
	v_mov_b32_e32 v110, v107
	s_waitcnt vmcnt(0)
	v_xor_b32_e32 v118, v116, v117
	v_ashrrev_i32_e32 v118, 31, v118
	v_ffbh_i32_e32 v119, v117
	v_add_u32_e32 v118, 32, v118
	v_add_u32_e32 v119, -1, v119
	v_min_u32_e32 v118, v119, v118
	v_lshlrev_b64 v[116:117], v118, v[116:117]
	v_min_u32_e32 v116, 1, v116
	v_or_b32_e32 v116, v117, v116
	v_sub_u32_e32 v117, 32, v118
	v_lshlrev_b64 v[118:119], 8, v[138:139]
	v_lshl_add_u64 v[118:119], s[10:11], 0, v[118:119]
	v_lshl_add_u64 v[126:127], v[118:119], 0, v[0:1]
	flat_load_dwordx4 v[118:121], v[126:127]
	v_cvt_f32_i32_e32 v116, v116
	v_ldexp_f32 v116, v116, v117
	v_mul_f32_e32 v116, 0x35800000, v116
	v_fmamk_f32 v116, v116, 0x3b000000, v180
	v_cmp_gt_f32_e32 vcc, s73, v116
	v_mul_f32_e32 v117, 0x4b800000, v116
	s_nop 0
	v_cndmask_b32_e32 v116, v116, v117, vcc
	v_rsq_f32_e32 v116, v116
	s_nop 0
	v_mul_f32_e32 v117, 0x45800000, v116
	v_cndmask_b32_e32 v116, v116, v117, vcc
	v_pk_mul_f32 v[122:123], v[122:123], v[116:117] op_sel_hi:[1,0]
	s_waitcnt vmcnt(0) lgkmcnt(0)
	v_pk_mul_f32 v[124:125], v[118:119], v[122:123]
	s_nop 0
	v_sub_f32_e32 v117, v124, v125
	v_pk_mul_f32 v[118:119], v[118:119], v[122:123] op_sel:[0,1] op_sel_hi:[1,0]
	flat_load_dwordx4 v[122:125], v[126:127] offset:32
	v_add_f32_e32 v106, v118, v119
	v_mov_b32_e32 v118, v98
	v_mov_b32_e32 v119, v102
	v_pk_mul_f32 v[128:129], v[118:119], v[116:117] op_sel_hi:[1,0]
	v_pk_mul_f32 v[110:111], v[110:111], v[116:117] op_sel_hi:[1,0]
	v_mov_b32_e32 v102, v99
	v_pk_mul_f32 v[102:103], v[102:103], v[116:117] op_sel_hi:[1,0]
	s_waitcnt vmcnt(0) lgkmcnt(0)
	v_pk_mul_f32 v[118:119], v[122:123], v[128:129]
	v_pk_mul_f32 v[122:123], v[122:123], v[128:129] op_sel:[0,1] op_sel_hi:[1,0]
	v_sub_f32_e32 v118, v118, v119
	v_add_f32_e32 v98, v122, v123
	v_pk_mul_f32 v[122:123], v[120:121], v[110:111]
	v_pk_mul_f32 v[110:111], v[120:121], v[110:111] op_sel:[0,1] op_sel_hi:[1,0]
	v_sub_f32_e32 v107, v122, v123
	flat_load_dwordx4 v[120:123], v[126:127] offset:16
	v_add_f32_e32 v119, v110, v111
	v_pk_mul_f32 v[110:111], v[124:125], v[102:103]
	v_pk_mul_f32 v[102:103], v[124:125], v[102:103] op_sel:[0,1] op_sel_hi:[1,0]
	flat_load_dwordx4 v[124:127], v[126:127] offset:48
	v_add_f32_e32 v128, v102, v103
	v_mov_b32_e32 v102, v108
	v_mov_b32_e32 v103, v112
	v_pk_mul_f32 v[102:103], v[102:103], v[116:117] op_sel_hi:[1,0]
	v_sub_f32_e32 v99, v110, v111
	v_mov_b32_e32 v112, v109
	s_waitcnt vmcnt(0) lgkmcnt(0)
	v_pk_mul_f32 v[110:111], v[120:121], v[102:103]
	v_pk_mul_f32 v[102:103], v[102:103], v[120:121] op_sel:[1,0] op_sel_hi:[0,1]
	v_add_f32_e32 v120, v102, v103
	v_mov_b32_e32 v102, v100
	v_mov_b32_e32 v103, v104
	v_pk_mul_f32 v[102:103], v[102:103], v[116:117] op_sel_hi:[1,0]
	v_sub_f32_e32 v129, v110, v111
	v_pk_mul_f32 v[110:111], v[102:103], v[124:125]
	v_pk_mul_f32 v[102:103], v[102:103], v[124:125] op_sel:[1,0] op_sel_hi:[0,1]
	v_sub_f32_e32 v110, v110, v111
	v_add_f32_e32 v111, v102, v103
	v_pk_mul_f32 v[102:103], v[112:113], v[116:117] op_sel_hi:[1,0]
	v_mov_b32_e32 v104, v101
	v_pk_mul_f32 v[108:109], v[102:103], v[122:123]
	v_pk_mul_f32 v[102:103], v[102:103], v[122:123] op_sel:[1,0] op_sel_hi:[0,1]
	v_pk_mul_f32 v[100:101], v[104:105], v[116:117] op_sel_hi:[1,0]
	v_sub_f32_e32 v108, v108, v109
	v_add_f32_e32 v109, v102, v103
	v_pk_mul_f32 v[102:103], v[100:101], v[126:127]
	v_pk_mul_f32 v[100:101], v[100:101], v[126:127] op_sel:[1,0] op_sel_hi:[0,1]
	v_add_f32_e32 v112, v100, v101
	v_lshlrev_b64 v[100:101], 11, v[138:139]
	v_sub_f32_e32 v103, v102, v103
	v_lshl_add_u64 v[100:101], s[20:21], 0, v[100:101]
	v_lshl_add_u64 v[104:105], v[100:101], 0, v[114:115]
	v_cvt_pk_bf16_f32 v100, v117, v107
	v_cvt_pk_bf16_f32 v101, v129, v108
	v_cvt_pk_bf16_f32 v102, v118, v99
	v_cvt_pk_bf16_f32 v103, v110, v103
	flat_store_dwordx4 v[104:105], v[100:103] sc1
	s_nop 1
	v_cvt_pk_bf16_f32 v100, v106, v119
	v_cvt_pk_bf16_f32 v101, v120, v109
	v_cvt_pk_bf16_f32 v102, v98, v128
	v_cvt_pk_bf16_f32 v103, v111, v112
	flat_store_dwordx4 v[104:105], v[100:103] offset:64 sc1
	global_load_dwordx2 v[98:99], v[132:133], off offset:256
	v_mov_b32_e32 v104, v90
	v_mov_b32_e32 v105, v94
	v_mov_b32_e32 v94, v91
	s_waitcnt vmcnt(0)
	v_xor_b32_e32 v100, v98, v99
	v_ashrrev_i32_e32 v100, 31, v100
	v_ffbh_i32_e32 v101, v99
	v_add_u32_e32 v100, 32, v100
	v_add_u32_e32 v101, -1, v101
	v_min_u32_e32 v100, v101, v100
	v_lshlrev_b64 v[98:99], v100, v[98:99]
	v_min_u32_e32 v98, 1, v98
	v_or_b32_e32 v98, v99, v98
	v_sub_u32_e32 v99, 32, v100
	v_lshlrev_b64 v[100:101], 8, v[136:137]
	v_lshl_add_u64 v[100:101], s[10:11], 0, v[100:101]
	v_lshl_add_u64 v[108:109], v[100:101], 0, v[0:1]
	flat_load_dwordx4 v[100:103], v[108:109]
	v_cvt_f32_i32_e32 v98, v98
	v_ldexp_f32 v98, v98, v99
	v_mul_f32_e32 v98, 0x35800000, v98
	v_fmamk_f32 v98, v98, 0x3b000000, v180
	v_cmp_gt_f32_e32 vcc, s73, v98
	v_mul_f32_e32 v99, 0x4b800000, v98
	s_nop 0
	v_cndmask_b32_e32 v98, v98, v99, vcc
	v_rsq_f32_e32 v98, v98
	s_nop 0
	v_mul_f32_e32 v99, 0x45800000, v98
	v_cndmask_b32_e32 v98, v98, v99, vcc
	v_pk_mul_f32 v[104:105], v[104:105], v[98:99] op_sel_hi:[1,0]
	s_waitcnt vmcnt(0) lgkmcnt(0)
	v_pk_mul_f32 v[106:107], v[100:101], v[104:105]
	s_nop 0
	v_sub_f32_e32 v99, v106, v107
	v_pk_mul_f32 v[100:101], v[100:101], v[104:105] op_sel:[0,1] op_sel_hi:[1,0]
	flat_load_dwordx4 v[104:107], v[108:109] offset:32
	v_add_f32_e32 v90, v100, v101
	v_mov_b32_e32 v100, v82
	v_mov_b32_e32 v101, v86
	v_pk_mul_f32 v[110:111], v[100:101], v[98:99] op_sel_hi:[1,0]
	v_pk_mul_f32 v[94:95], v[94:95], v[98:99] op_sel_hi:[1,0]
	v_mov_b32_e32 v86, v83
	v_pk_mul_f32 v[86:87], v[86:87], v[98:99] op_sel_hi:[1,0]
	s_waitcnt vmcnt(0) lgkmcnt(0)
	v_pk_mul_f32 v[100:101], v[104:105], v[110:111]
	v_pk_mul_f32 v[104:105], v[104:105], v[110:111] op_sel:[0,1] op_sel_hi:[1,0]
	v_sub_f32_e32 v100, v100, v101
	v_add_f32_e32 v82, v104, v105
	v_pk_mul_f32 v[104:105], v[102:103], v[94:95]
	v_pk_mul_f32 v[94:95], v[102:103], v[94:95] op_sel:[0,1] op_sel_hi:[1,0]
	v_sub_f32_e32 v91, v104, v105
	flat_load_dwordx4 v[102:105], v[108:109] offset:16
	v_add_f32_e32 v101, v94, v95
	v_pk_mul_f32 v[94:95], v[106:107], v[86:87]
	v_pk_mul_f32 v[86:87], v[106:107], v[86:87] op_sel:[0,1] op_sel_hi:[1,0]
	flat_load_dwordx4 v[106:109], v[108:109] offset:48
	v_add_f32_e32 v110, v86, v87
	v_mov_b32_e32 v86, v92
	v_mov_b32_e32 v87, v96
	v_pk_mul_f32 v[86:87], v[86:87], v[98:99] op_sel_hi:[1,0]
	v_sub_f32_e32 v83, v94, v95
	v_mov_b32_e32 v96, v93
	s_waitcnt vmcnt(0) lgkmcnt(0)
	v_pk_mul_f32 v[94:95], v[102:103], v[86:87]
	v_pk_mul_f32 v[86:87], v[86:87], v[102:103] op_sel:[1,0] op_sel_hi:[0,1]
	v_add_f32_e32 v102, v86, v87
	v_mov_b32_e32 v86, v84
	v_mov_b32_e32 v87, v88
	v_pk_mul_f32 v[86:87], v[86:87], v[98:99] op_sel_hi:[1,0]
	v_sub_f32_e32 v111, v94, v95
	v_pk_mul_f32 v[94:95], v[86:87], v[106:107]
	v_pk_mul_f32 v[86:87], v[86:87], v[106:107] op_sel:[1,0] op_sel_hi:[0,1]
	v_sub_f32_e32 v94, v94, v95
	v_add_f32_e32 v95, v86, v87
	v_pk_mul_f32 v[86:87], v[96:97], v[98:99] op_sel_hi:[1,0]
	v_mov_b32_e32 v88, v85
	v_pk_mul_f32 v[92:93], v[86:87], v[104:105]
	v_pk_mul_f32 v[86:87], v[86:87], v[104:105] op_sel:[1,0] op_sel_hi:[0,1]
	v_pk_mul_f32 v[84:85], v[88:89], v[98:99] op_sel_hi:[1,0]
	v_sub_f32_e32 v92, v92, v93
	v_add_f32_e32 v93, v86, v87
	v_pk_mul_f32 v[86:87], v[84:85], v[108:109]
	v_pk_mul_f32 v[84:85], v[84:85], v[108:109] op_sel:[1,0] op_sel_hi:[0,1]
	v_add_f32_e32 v96, v84, v85
	v_lshlrev_b64 v[84:85], 11, v[136:137]
	v_sub_f32_e32 v87, v86, v87
	v_lshl_add_u64 v[84:85], s[20:21], 0, v[84:85]
	v_lshl_add_u64 v[88:89], v[84:85], 0, v[114:115]
	v_cvt_pk_bf16_f32 v84, v99, v91
	v_cvt_pk_bf16_f32 v85, v111, v92
	v_cvt_pk_bf16_f32 v86, v100, v83
	v_cvt_pk_bf16_f32 v87, v94, v87
	flat_store_dwordx4 v[88:89], v[84:87] sc1
	s_nop 1
	v_cvt_pk_bf16_f32 v84, v90, v101
	v_cvt_pk_bf16_f32 v85, v102, v93
	v_cvt_pk_bf16_f32 v86, v82, v110
	v_cvt_pk_bf16_f32 v87, v95, v96
	flat_store_dwordx4 v[88:89], v[84:87] offset:64 sc1
	global_load_dwordx2 v[82:83], v[132:133], off offset:384
	v_mov_b32_e32 v88, v74
	v_mov_b32_e32 v89, v78
	v_mov_b32_e32 v78, v75
	s_waitcnt vmcnt(0)
	v_xor_b32_e32 v84, v82, v83
	v_ashrrev_i32_e32 v84, 31, v84
	v_ffbh_i32_e32 v85, v83
	v_add_u32_e32 v84, 32, v84
	v_add_u32_e32 v85, -1, v85
	v_min_u32_e32 v84, v85, v84
	v_lshlrev_b64 v[82:83], v84, v[82:83]
	v_min_u32_e32 v82, 1, v82
	v_or_b32_e32 v82, v83, v82
	v_sub_u32_e32 v83, 32, v84
	v_lshlrev_b64 v[84:85], 8, v[134:135]
	v_lshl_add_u64 v[84:85], s[10:11], 0, v[84:85]
	v_lshl_add_u64 v[92:93], v[84:85], 0, v[0:1]
	flat_load_dwordx4 v[84:87], v[92:93]
	v_cvt_f32_i32_e32 v82, v82
	v_ldexp_f32 v82, v82, v83
	v_mul_f32_e32 v82, 0x35800000, v82
	v_fmamk_f32 v82, v82, 0x3b000000, v180
	v_cmp_gt_f32_e32 vcc, s73, v82
	v_mul_f32_e32 v83, 0x4b800000, v82
	s_nop 0
	v_cndmask_b32_e32 v82, v82, v83, vcc
	v_rsq_f32_e32 v82, v82
	s_nop 0
	v_mul_f32_e32 v83, 0x45800000, v82
	v_cndmask_b32_e32 v82, v82, v83, vcc
	v_pk_mul_f32 v[88:89], v[88:89], v[82:83] op_sel_hi:[1,0]
	s_waitcnt vmcnt(0) lgkmcnt(0)
	v_pk_mul_f32 v[90:91], v[84:85], v[88:89]
	s_nop 0
	v_sub_f32_e32 v83, v90, v91
	v_pk_mul_f32 v[84:85], v[84:85], v[88:89] op_sel:[0,1] op_sel_hi:[1,0]
	flat_load_dwordx4 v[88:91], v[92:93] offset:32
	v_add_f32_e32 v74, v84, v85
	v_mov_b32_e32 v84, v66
	v_mov_b32_e32 v85, v70
	v_pk_mul_f32 v[94:95], v[84:85], v[82:83] op_sel_hi:[1,0]
	v_pk_mul_f32 v[78:79], v[78:79], v[82:83] op_sel_hi:[1,0]
	v_mov_b32_e32 v70, v67
	v_pk_mul_f32 v[70:71], v[70:71], v[82:83] op_sel_hi:[1,0]
	s_waitcnt vmcnt(0) lgkmcnt(0)
	v_pk_mul_f32 v[84:85], v[88:89], v[94:95]
	v_pk_mul_f32 v[88:89], v[88:89], v[94:95] op_sel:[0,1] op_sel_hi:[1,0]
	v_sub_f32_e32 v84, v84, v85
	v_add_f32_e32 v66, v88, v89
	v_pk_mul_f32 v[88:89], v[86:87], v[78:79]
	v_pk_mul_f32 v[78:79], v[86:87], v[78:79] op_sel:[0,1] op_sel_hi:[1,0]
	v_sub_f32_e32 v75, v88, v89
	flat_load_dwordx4 v[86:89], v[92:93] offset:16
	v_add_f32_e32 v85, v78, v79
	v_pk_mul_f32 v[78:79], v[90:91], v[70:71]
	v_pk_mul_f32 v[70:71], v[90:91], v[70:71] op_sel:[0,1] op_sel_hi:[1,0]
	flat_load_dwordx4 v[90:93], v[92:93] offset:48
	v_add_f32_e32 v94, v70, v71
	v_mov_b32_e32 v70, v76
	v_mov_b32_e32 v71, v80
	v_pk_mul_f32 v[70:71], v[70:71], v[82:83] op_sel_hi:[1,0]
	v_sub_f32_e32 v67, v78, v79
	v_mov_b32_e32 v80, v77
	s_waitcnt vmcnt(0) lgkmcnt(0)
	v_pk_mul_f32 v[78:79], v[86:87], v[70:71]
	v_pk_mul_f32 v[70:71], v[70:71], v[86:87] op_sel:[1,0] op_sel_hi:[0,1]
	v_add_f32_e32 v86, v70, v71
	v_mov_b32_e32 v70, v68
	v_mov_b32_e32 v71, v72
	v_pk_mul_f32 v[70:71], v[70:71], v[82:83] op_sel_hi:[1,0]
	v_sub_f32_e32 v95, v78, v79
	v_pk_mul_f32 v[78:79], v[70:71], v[90:91]
	v_pk_mul_f32 v[70:71], v[70:71], v[90:91] op_sel:[1,0] op_sel_hi:[0,1]
	v_sub_f32_e32 v78, v78, v79
	v_add_f32_e32 v79, v70, v71
	v_pk_mul_f32 v[70:71], v[80:81], v[82:83] op_sel_hi:[1,0]
	v_mov_b32_e32 v72, v69
	v_pk_mul_f32 v[76:77], v[70:71], v[88:89]
	v_pk_mul_f32 v[70:71], v[70:71], v[88:89] op_sel:[1,0] op_sel_hi:[0,1]
	v_pk_mul_f32 v[68:69], v[72:73], v[82:83] op_sel_hi:[1,0]
	v_sub_f32_e32 v76, v76, v77
	v_add_f32_e32 v77, v70, v71
	v_pk_mul_f32 v[70:71], v[68:69], v[92:93]
	v_pk_mul_f32 v[68:69], v[68:69], v[92:93] op_sel:[1,0] op_sel_hi:[0,1]
	v_add_f32_e32 v80, v68, v69
	v_lshlrev_b64 v[68:69], 11, v[134:135]
	v_sub_f32_e32 v71, v70, v71
	v_lshl_add_u64 v[68:69], s[20:21], 0, v[68:69]
	v_lshl_add_u64 v[72:73], v[68:69], 0, v[114:115]
	v_cvt_pk_bf16_f32 v68, v83, v75
	v_cvt_pk_bf16_f32 v69, v95, v76
	v_cvt_pk_bf16_f32 v70, v84, v67
	v_cvt_pk_bf16_f32 v71, v78, v71
	flat_store_dwordx4 v[72:73], v[68:71] sc1
	v_mov_b32_e32 v75, v62
	v_mov_b32_e32 v62, v59
	v_cvt_pk_bf16_f32 v68, v74, v85
	v_cvt_pk_bf16_f32 v69, v86, v77
	v_cvt_pk_bf16_f32 v70, v66, v94
	v_cvt_pk_bf16_f32 v71, v79, v80
	flat_store_dwordx4 v[72:73], v[68:71] offset:64 sc1
	global_load_dwordx2 v[68:69], v[132:133], off offset:1024
	v_add_u32_e32 v66, 0x80, v130
	v_ashrrev_i32_e32 v67, 31, v66
	v_mov_b32_e32 v74, v58
	s_waitcnt vmcnt(0)
	v_xor_b32_e32 v70, v68, v69
	v_ashrrev_i32_e32 v70, 31, v70
	v_ffbh_i32_e32 v71, v69
	v_add_u32_e32 v70, 32, v70
	v_add_u32_e32 v71, -1, v71
	v_min_u32_e32 v70, v71, v70
	v_lshlrev_b64 v[68:69], v70, v[68:69]
	v_min_u32_e32 v68, 1, v68
	v_or_b32_e32 v68, v69, v68
	v_sub_u32_e32 v69, 32, v70
	v_lshlrev_b64 v[70:71], 8, v[66:67]
	v_lshl_add_u64 v[70:71], s[10:11], 0, v[70:71]
	v_lshl_add_u64 v[78:79], v[70:71], 0, v[0:1]
	flat_load_dwordx4 v[70:73], v[78:79]
	v_cvt_f32_i32_e32 v68, v68
	v_ldexp_f32 v68, v68, v69
	v_mul_f32_e32 v68, 0x35800000, v68
	v_fmamk_f32 v68, v68, 0x3b000000, v180
	v_cmp_gt_f32_e32 vcc, s73, v68
	v_mul_f32_e32 v69, 0x4b800000, v68
	s_nop 0
	v_cndmask_b32_e32 v68, v68, v69, vcc
	v_rsq_f32_e32 v68, v68
	s_nop 0
	v_mul_f32_e32 v69, 0x45800000, v68
	v_cndmask_b32_e32 v68, v68, v69, vcc
	v_pk_mul_f32 v[74:75], v[74:75], v[68:69] op_sel_hi:[1,0]
	s_waitcnt vmcnt(0) lgkmcnt(0)
	v_pk_mul_f32 v[76:77], v[70:71], v[74:75]
	s_nop 0
	v_sub_f32_e32 v69, v76, v77
	v_pk_mul_f32 v[70:71], v[70:71], v[74:75] op_sel:[0,1] op_sel_hi:[1,0]
	flat_load_dwordx4 v[74:77], v[78:79] offset:32
	v_add_f32_e32 v58, v70, v71
	v_mov_b32_e32 v70, v50
	v_mov_b32_e32 v71, v54
	v_pk_mul_f32 v[80:81], v[70:71], v[68:69] op_sel_hi:[1,0]
	v_pk_mul_f32 v[62:63], v[62:63], v[68:69] op_sel_hi:[1,0]
	v_mov_b32_e32 v54, v51
	v_pk_mul_f32 v[54:55], v[54:55], v[68:69] op_sel_hi:[1,0]
	s_waitcnt vmcnt(0) lgkmcnt(0)
	v_pk_mul_f32 v[70:71], v[74:75], v[80:81]
	v_pk_mul_f32 v[74:75], v[74:75], v[80:81] op_sel:[0,1] op_sel_hi:[1,0]
	v_sub_f32_e32 v70, v70, v71
	v_add_f32_e32 v50, v74, v75
	v_pk_mul_f32 v[74:75], v[72:73], v[62:63]
	v_pk_mul_f32 v[62:63], v[72:73], v[62:63] op_sel:[0,1] op_sel_hi:[1,0]
	v_sub_f32_e32 v59, v74, v75
	flat_load_dwordx4 v[72:75], v[78:79] offset:16
	v_add_f32_e32 v71, v62, v63
	v_pk_mul_f32 v[62:63], v[76:77], v[54:55]
	v_pk_mul_f32 v[54:55], v[76:77], v[54:55] op_sel:[0,1] op_sel_hi:[1,0]
	flat_load_dwordx4 v[76:79], v[78:79] offset:48
	v_add_f32_e32 v80, v54, v55
	v_mov_b32_e32 v54, v60
	v_mov_b32_e32 v55, v64
	v_pk_mul_f32 v[54:55], v[54:55], v[68:69] op_sel_hi:[1,0]
	v_sub_f32_e32 v51, v62, v63
	v_mov_b32_e32 v64, v61
	s_waitcnt vmcnt(0) lgkmcnt(0)
	v_pk_mul_f32 v[62:63], v[72:73], v[54:55]
	v_pk_mul_f32 v[54:55], v[54:55], v[72:73] op_sel:[1,0] op_sel_hi:[0,1]
	v_add_f32_e32 v72, v54, v55
	v_mov_b32_e32 v54, v52
	v_mov_b32_e32 v55, v56
	v_pk_mul_f32 v[54:55], v[54:55], v[68:69] op_sel_hi:[1,0]
	v_sub_f32_e32 v81, v62, v63
	v_pk_mul_f32 v[62:63], v[54:55], v[76:77]
	v_pk_mul_f32 v[54:55], v[54:55], v[76:77] op_sel:[1,0] op_sel_hi:[0,1]
	v_sub_f32_e32 v62, v62, v63
	v_add_f32_e32 v63, v54, v55
	v_pk_mul_f32 v[54:55], v[64:65], v[68:69] op_sel_hi:[1,0]
	v_mov_b32_e32 v56, v53
	v_pk_mul_f32 v[60:61], v[54:55], v[74:75]
	v_pk_mul_f32 v[54:55], v[54:55], v[74:75] op_sel:[1,0] op_sel_hi:[0,1]
	v_pk_mul_f32 v[52:53], v[56:57], v[68:69] op_sel_hi:[1,0]
	v_sub_f32_e32 v60, v60, v61
	v_add_f32_e32 v61, v54, v55
	v_pk_mul_f32 v[54:55], v[52:53], v[78:79]
	v_pk_mul_f32 v[52:53], v[52:53], v[78:79] op_sel:[1,0] op_sel_hi:[0,1]
	v_add_f32_e32 v64, v52, v53
	v_lshlrev_b64 v[52:53], 11, v[66:67]
	v_sub_f32_e32 v55, v54, v55
	v_lshl_add_u64 v[52:53], s[20:21], 0, v[52:53]
	v_lshl_add_u64 v[56:57], v[52:53], 0, v[114:115]
	v_cvt_pk_bf16_f32 v52, v69, v59
	v_cvt_pk_bf16_f32 v53, v81, v60
	v_cvt_pk_bf16_f32 v54, v70, v51
	v_cvt_pk_bf16_f32 v55, v62, v55
	flat_store_dwordx4 v[56:57], v[52:55] sc1
	v_mov_b32_e32 v59, v46
	v_mov_b32_e32 v46, v43
	v_cvt_pk_bf16_f32 v52, v58, v71
	v_cvt_pk_bf16_f32 v53, v72, v61
	v_cvt_pk_bf16_f32 v54, v50, v80
	v_cvt_pk_bf16_f32 v55, v63, v64
	flat_store_dwordx4 v[56:57], v[52:55] offset:64 sc1
	global_load_dwordx2 v[52:53], v[132:133], off offset:1152
	v_add_u32_e32 v50, 0x90, v130
	v_ashrrev_i32_e32 v51, 31, v50
	v_mov_b32_e32 v58, v42
	s_waitcnt vmcnt(0)
	v_xor_b32_e32 v54, v52, v53
	v_ashrrev_i32_e32 v54, 31, v54
	v_ffbh_i32_e32 v55, v53
	v_add_u32_e32 v54, 32, v54
	v_add_u32_e32 v55, -1, v55
	v_min_u32_e32 v54, v55, v54
	v_lshlrev_b64 v[52:53], v54, v[52:53]
	v_min_u32_e32 v52, 1, v52
	v_or_b32_e32 v52, v53, v52
	v_sub_u32_e32 v53, 32, v54
	v_lshlrev_b64 v[54:55], 8, v[50:51]
	v_lshl_add_u64 v[54:55], s[10:11], 0, v[54:55]
	v_lshl_add_u64 v[62:63], v[54:55], 0, v[0:1]
	flat_load_dwordx4 v[54:57], v[62:63]
	v_cvt_f32_i32_e32 v52, v52
	v_ldexp_f32 v52, v52, v53
	v_mul_f32_e32 v52, 0x35800000, v52
	v_fmamk_f32 v52, v52, 0x3b000000, v180
	v_cmp_gt_f32_e32 vcc, s73, v52
	v_mul_f32_e32 v53, 0x4b800000, v52
	s_nop 0
	v_cndmask_b32_e32 v52, v52, v53, vcc
	v_rsq_f32_e32 v52, v52
	s_nop 0
	v_mul_f32_e32 v53, 0x45800000, v52
	v_cndmask_b32_e32 v52, v52, v53, vcc
	v_pk_mul_f32 v[58:59], v[58:59], v[52:53] op_sel_hi:[1,0]
	s_waitcnt vmcnt(0) lgkmcnt(0)
	v_pk_mul_f32 v[60:61], v[54:55], v[58:59]
	s_nop 0
	v_sub_f32_e32 v53, v60, v61
	v_pk_mul_f32 v[54:55], v[54:55], v[58:59] op_sel:[0,1] op_sel_hi:[1,0]
	flat_load_dwordx4 v[58:61], v[62:63] offset:32
	v_add_f32_e32 v42, v54, v55
	v_mov_b32_e32 v54, v34
	v_mov_b32_e32 v55, v38
	v_pk_mul_f32 v[64:65], v[54:55], v[52:53] op_sel_hi:[1,0]
	v_pk_mul_f32 v[46:47], v[46:47], v[52:53] op_sel_hi:[1,0]
	v_mov_b32_e32 v38, v35
	v_pk_mul_f32 v[38:39], v[38:39], v[52:53] op_sel_hi:[1,0]
	s_waitcnt vmcnt(0) lgkmcnt(0)
	v_pk_mul_f32 v[54:55], v[58:59], v[64:65]
	v_pk_mul_f32 v[58:59], v[58:59], v[64:65] op_sel:[0,1] op_sel_hi:[1,0]
	v_sub_f32_e32 v54, v54, v55
	v_add_f32_e32 v34, v58, v59
	v_pk_mul_f32 v[58:59], v[56:57], v[46:47]
	v_pk_mul_f32 v[46:47], v[56:57], v[46:47] op_sel:[0,1] op_sel_hi:[1,0]
	v_sub_f32_e32 v43, v58, v59
	flat_load_dwordx4 v[56:59], v[62:63] offset:16
	v_add_f32_e32 v55, v46, v47
	v_pk_mul_f32 v[46:47], v[60:61], v[38:39]
	v_pk_mul_f32 v[38:39], v[60:61], v[38:39] op_sel:[0,1] op_sel_hi:[1,0]
	flat_load_dwordx4 v[60:63], v[62:63] offset:48
	v_add_f32_e32 v64, v38, v39
	v_mov_b32_e32 v38, v44
	v_mov_b32_e32 v39, v48
	v_pk_mul_f32 v[38:39], v[38:39], v[52:53] op_sel_hi:[1,0]
	v_sub_f32_e32 v35, v46, v47
	v_mov_b32_e32 v48, v45
	s_waitcnt vmcnt(0) lgkmcnt(0)
	v_pk_mul_f32 v[46:47], v[56:57], v[38:39]
	v_pk_mul_f32 v[38:39], v[38:39], v[56:57] op_sel:[1,0] op_sel_hi:[0,1]
	v_add_f32_e32 v56, v38, v39
	v_mov_b32_e32 v38, v36
	v_mov_b32_e32 v39, v40
	v_pk_mul_f32 v[38:39], v[38:39], v[52:53] op_sel_hi:[1,0]
	v_sub_f32_e32 v65, v46, v47
	v_pk_mul_f32 v[46:47], v[38:39], v[60:61]
	v_pk_mul_f32 v[38:39], v[38:39], v[60:61] op_sel:[1,0] op_sel_hi:[0,1]
	v_sub_f32_e32 v46, v46, v47
	v_add_f32_e32 v47, v38, v39
	v_pk_mul_f32 v[38:39], v[48:49], v[52:53] op_sel_hi:[1,0]
	v_mov_b32_e32 v40, v37
	v_pk_mul_f32 v[44:45], v[38:39], v[58:59]
	v_pk_mul_f32 v[38:39], v[38:39], v[58:59] op_sel:[1,0] op_sel_hi:[0,1]
	v_pk_mul_f32 v[36:37], v[40:41], v[52:53] op_sel_hi:[1,0]
	v_sub_f32_e32 v44, v44, v45
	v_add_f32_e32 v45, v38, v39
	v_pk_mul_f32 v[38:39], v[36:37], v[62:63]
	v_pk_mul_f32 v[36:37], v[36:37], v[62:63] op_sel:[1,0] op_sel_hi:[0,1]
	v_add_f32_e32 v48, v36, v37
	v_lshlrev_b64 v[36:37], 11, v[50:51]
	v_sub_f32_e32 v39, v38, v39
	v_lshl_add_u64 v[36:37], s[20:21], 0, v[36:37]
	v_lshl_add_u64 v[40:41], v[36:37], 0, v[114:115]
	v_cvt_pk_bf16_f32 v36, v53, v43
	v_cvt_pk_bf16_f32 v37, v65, v44
	v_cvt_pk_bf16_f32 v38, v54, v35
	v_cvt_pk_bf16_f32 v39, v46, v39
	flat_store_dwordx4 v[40:41], v[36:39] sc1
	v_mov_b32_e32 v43, v30
	v_mov_b32_e32 v30, v27
	v_cvt_pk_bf16_f32 v36, v42, v55
	v_cvt_pk_bf16_f32 v37, v56, v45
	v_cvt_pk_bf16_f32 v38, v34, v64
	v_cvt_pk_bf16_f32 v39, v47, v48
	flat_store_dwordx4 v[40:41], v[36:39] offset:64 sc1
	global_load_dwordx2 v[36:37], v[132:133], off offset:1280
	v_add_u32_e32 v34, 0xa0, v130
	v_ashrrev_i32_e32 v35, 31, v34
	v_mov_b32_e32 v42, v26
	s_waitcnt vmcnt(0)
	v_xor_b32_e32 v38, v36, v37
	v_ashrrev_i32_e32 v38, 31, v38
	v_ffbh_i32_e32 v39, v37
	v_add_u32_e32 v38, 32, v38
	v_add_u32_e32 v39, -1, v39
	v_min_u32_e32 v38, v39, v38
	v_lshlrev_b64 v[36:37], v38, v[36:37]
	v_min_u32_e32 v36, 1, v36
	v_or_b32_e32 v36, v37, v36
	v_sub_u32_e32 v37, 32, v38
	v_lshlrev_b64 v[38:39], 8, v[34:35]
	v_lshl_add_u64 v[38:39], s[10:11], 0, v[38:39]
	v_lshl_add_u64 v[46:47], v[38:39], 0, v[0:1]
	flat_load_dwordx4 v[38:41], v[46:47]
	v_cvt_f32_i32_e32 v36, v36
	v_ldexp_f32 v36, v36, v37
	v_mul_f32_e32 v36, 0x35800000, v36
	v_fmamk_f32 v36, v36, 0x3b000000, v180
	v_cmp_gt_f32_e32 vcc, s73, v36
	v_mul_f32_e32 v37, 0x4b800000, v36
	s_nop 0
	v_cndmask_b32_e32 v36, v36, v37, vcc
	v_rsq_f32_e32 v36, v36
	s_nop 0
	v_mul_f32_e32 v37, 0x45800000, v36
	v_cndmask_b32_e32 v36, v36, v37, vcc
	v_pk_mul_f32 v[42:43], v[42:43], v[36:37] op_sel_hi:[1,0]
	s_waitcnt vmcnt(0) lgkmcnt(0)
	v_pk_mul_f32 v[44:45], v[38:39], v[42:43]
	s_nop 0
	v_sub_f32_e32 v37, v44, v45
	v_pk_mul_f32 v[38:39], v[38:39], v[42:43] op_sel:[0,1] op_sel_hi:[1,0]
	flat_load_dwordx4 v[42:45], v[46:47] offset:32
	v_add_f32_e32 v26, v38, v39
	v_mov_b32_e32 v38, v18
	v_mov_b32_e32 v39, v22
	v_pk_mul_f32 v[48:49], v[38:39], v[36:37] op_sel_hi:[1,0]
	v_pk_mul_f32 v[30:31], v[30:31], v[36:37] op_sel_hi:[1,0]
	v_mov_b32_e32 v22, v19
	v_pk_mul_f32 v[22:23], v[22:23], v[36:37] op_sel_hi:[1,0]
	s_waitcnt vmcnt(0) lgkmcnt(0)
	v_pk_mul_f32 v[38:39], v[42:43], v[48:49]
	v_pk_mul_f32 v[42:43], v[42:43], v[48:49] op_sel:[0,1] op_sel_hi:[1,0]
	v_sub_f32_e32 v38, v38, v39
	v_add_f32_e32 v18, v42, v43
	v_pk_mul_f32 v[42:43], v[40:41], v[30:31]
	v_pk_mul_f32 v[30:31], v[40:41], v[30:31] op_sel:[0,1] op_sel_hi:[1,0]
	v_sub_f32_e32 v27, v42, v43
	flat_load_dwordx4 v[40:43], v[46:47] offset:16
	v_add_f32_e32 v39, v30, v31
	v_pk_mul_f32 v[30:31], v[44:45], v[22:23]
	v_pk_mul_f32 v[22:23], v[44:45], v[22:23] op_sel:[0,1] op_sel_hi:[1,0]
	flat_load_dwordx4 v[44:47], v[46:47] offset:48
	v_add_f32_e32 v48, v22, v23
	v_mov_b32_e32 v22, v28
	v_mov_b32_e32 v23, v32
	v_pk_mul_f32 v[22:23], v[22:23], v[36:37] op_sel_hi:[1,0]
	v_sub_f32_e32 v19, v30, v31
	v_mov_b32_e32 v32, v29
	s_waitcnt vmcnt(0) lgkmcnt(0)
	v_pk_mul_f32 v[30:31], v[40:41], v[22:23]
	v_pk_mul_f32 v[22:23], v[22:23], v[40:41] op_sel:[1,0] op_sel_hi:[0,1]
	v_add_f32_e32 v40, v22, v23
	v_mov_b32_e32 v22, v20
	v_mov_b32_e32 v23, v24
	v_pk_mul_f32 v[22:23], v[22:23], v[36:37] op_sel_hi:[1,0]
	v_sub_f32_e32 v49, v30, v31
	v_pk_mul_f32 v[30:31], v[22:23], v[44:45]
	v_pk_mul_f32 v[22:23], v[22:23], v[44:45] op_sel:[1,0] op_sel_hi:[0,1]
	v_sub_f32_e32 v30, v30, v31
	v_add_f32_e32 v31, v22, v23
	v_pk_mul_f32 v[22:23], v[32:33], v[36:37] op_sel_hi:[1,0]
	v_mov_b32_e32 v24, v21
	v_pk_mul_f32 v[28:29], v[22:23], v[42:43]
	v_pk_mul_f32 v[22:23], v[22:23], v[42:43] op_sel:[1,0] op_sel_hi:[0,1]
	v_pk_mul_f32 v[20:21], v[24:25], v[36:37] op_sel_hi:[1,0]
	v_sub_f32_e32 v28, v28, v29
	v_add_f32_e32 v29, v22, v23
	v_pk_mul_f32 v[22:23], v[20:21], v[46:47]
	v_pk_mul_f32 v[20:21], v[20:21], v[46:47] op_sel:[1,0] op_sel_hi:[0,1]
	v_add_f32_e32 v32, v20, v21
	v_lshlrev_b64 v[20:21], 11, v[34:35]
	v_sub_f32_e32 v23, v22, v23
	v_lshl_add_u64 v[20:21], s[20:21], 0, v[20:21]
	v_lshl_add_u64 v[24:25], v[20:21], 0, v[114:115]
	v_cvt_pk_bf16_f32 v20, v37, v27
	v_cvt_pk_bf16_f32 v21, v49, v28
	v_cvt_pk_bf16_f32 v22, v38, v19
	v_cvt_pk_bf16_f32 v23, v30, v23
	flat_store_dwordx4 v[24:25], v[20:23] sc1
	v_mov_b32_e32 v27, v14
	v_mov_b32_e32 v14, v11
	v_cvt_pk_bf16_f32 v20, v26, v39
	v_cvt_pk_bf16_f32 v21, v40, v29
	v_cvt_pk_bf16_f32 v22, v18, v48
	v_cvt_pk_bf16_f32 v23, v31, v32
	flat_store_dwordx4 v[24:25], v[20:23] offset:64 sc1
	global_load_dwordx2 v[20:21], v[132:133], off offset:1408
	v_add_u32_e32 v18, 0xb0, v130
	v_ashrrev_i32_e32 v19, 31, v18
	v_mov_b32_e32 v26, v10
	s_waitcnt vmcnt(0)
	v_xor_b32_e32 v22, v20, v21
	v_ashrrev_i32_e32 v22, 31, v22
	v_ffbh_i32_e32 v23, v21
	v_add_u32_e32 v22, 32, v22
	v_add_u32_e32 v23, -1, v23
	v_min_u32_e32 v22, v23, v22
	v_lshlrev_b64 v[20:21], v22, v[20:21]
	v_min_u32_e32 v20, 1, v20
	v_or_b32_e32 v20, v21, v20
	v_sub_u32_e32 v21, 32, v22
	v_lshlrev_b64 v[22:23], 8, v[18:19]
	v_lshl_add_u64 v[22:23], s[10:11], 0, v[22:23]
	v_lshl_add_u64 v[30:31], v[22:23], 0, v[0:1]
	flat_load_dwordx4 v[22:25], v[30:31]
	v_cvt_f32_i32_e32 v20, v20
	v_ldexp_f32 v20, v20, v21
	v_mul_f32_e32 v20, 0x35800000, v20
	v_fmamk_f32 v20, v20, 0x3b000000, v180
	v_cmp_gt_f32_e32 vcc, s73, v20
	v_mul_f32_e32 v21, 0x4b800000, v20
	s_nop 0
	v_cndmask_b32_e32 v20, v20, v21, vcc
	v_rsq_f32_e32 v20, v20
	s_nop 0
	v_mul_f32_e32 v21, 0x45800000, v20
	v_cndmask_b32_e32 v20, v20, v21, vcc
	v_pk_mul_f32 v[26:27], v[26:27], v[20:21] op_sel_hi:[1,0]
	s_waitcnt vmcnt(0) lgkmcnt(0)
	v_pk_mul_f32 v[28:29], v[22:23], v[26:27]
	s_nop 0
	v_sub_f32_e32 v10, v28, v29
	v_pk_mul_f32 v[22:23], v[22:23], v[26:27] op_sel:[0,1] op_sel_hi:[1,0]
	flat_load_dwordx4 v[26:29], v[30:31] offset:32
	v_add_f32_e32 v0, v22, v23
	v_mov_b32_e32 v22, v2
	v_mov_b32_e32 v23, v6
	v_pk_mul_f32 v[22:23], v[22:23], v[20:21] op_sel_hi:[1,0]
	v_mov_b32_e32 v6, v3
	s_waitcnt vmcnt(0) lgkmcnt(0)
	v_pk_mul_f32 v[32:33], v[26:27], v[22:23]
	s_nop 0
	v_sub_f32_e32 v21, v32, v33
	v_pk_mul_f32 v[22:23], v[26:27], v[22:23] op_sel:[0,1] op_sel_hi:[1,0]
	v_pk_mul_f32 v[14:15], v[14:15], v[20:21] op_sel_hi:[1,0]
	v_add_f32_e32 v2, v22, v23
	v_pk_mul_f32 v[22:23], v[24:25], v[14:15]
	v_pk_mul_f32 v[14:15], v[24:25], v[14:15] op_sel:[0,1] op_sel_hi:[1,0]
	v_sub_f32_e32 v11, v22, v23
	flat_load_dwordx4 v[22:25], v[30:31] offset:16
	v_pk_mul_f32 v[6:7], v[6:7], v[20:21] op_sel_hi:[1,0]
	v_add_f32_e32 v32, v14, v15
	v_pk_mul_f32 v[14:15], v[28:29], v[6:7]
	v_pk_mul_f32 v[6:7], v[28:29], v[6:7] op_sel:[0,1] op_sel_hi:[1,0]
	flat_load_dwordx4 v[26:29], v[30:31] offset:48
	v_add_f32_e32 v33, v6, v7
	v_mov_b32_e32 v6, v12
	v_mov_b32_e32 v7, v16
	v_pk_mul_f32 v[6:7], v[6:7], v[20:21] op_sel_hi:[1,0]
	v_sub_f32_e32 v3, v14, v15
	v_mov_b32_e32 v16, v13
	s_waitcnt vmcnt(0) lgkmcnt(0)
	v_pk_mul_f32 v[14:15], v[22:23], v[6:7]
	v_pk_mul_f32 v[6:7], v[6:7], v[22:23] op_sel:[1,0] op_sel_hi:[0,1]
	v_add_f32_e32 v22, v6, v7
	v_mov_b32_e32 v6, v4
	v_mov_b32_e32 v7, v8
	v_pk_mul_f32 v[6:7], v[6:7], v[20:21] op_sel_hi:[1,0]
	v_sub_f32_e32 v34, v14, v15
	v_pk_mul_f32 v[14:15], v[6:7], v[26:27]
	v_pk_mul_f32 v[6:7], v[6:7], v[26:27] op_sel:[1,0] op_sel_hi:[0,1]
	v_sub_f32_e32 v14, v14, v15
	v_add_f32_e32 v15, v6, v7
	v_pk_mul_f32 v[6:7], v[16:17], v[20:21] op_sel_hi:[1,0]
	v_mov_b32_e32 v8, v5
	v_pk_mul_f32 v[12:13], v[6:7], v[24:25]
	v_pk_mul_f32 v[6:7], v[6:7], v[24:25] op_sel:[1,0] op_sel_hi:[0,1]
	v_pk_mul_f32 v[4:5], v[8:9], v[20:21] op_sel_hi:[1,0]
	v_sub_f32_e32 v12, v12, v13
	v_add_f32_e32 v13, v6, v7
	v_pk_mul_f32 v[6:7], v[4:5], v[28:29]
	v_pk_mul_f32 v[4:5], v[4:5], v[28:29] op_sel:[1,0] op_sel_hi:[0,1]
	v_add_f32_e32 v16, v4, v5
	v_lshlrev_b64 v[4:5], 11, v[18:19]
	v_sub_f32_e32 v7, v6, v7
	v_lshl_add_u64 v[4:5], s[20:21], 0, v[4:5]
	v_lshl_add_u64 v[8:9], v[4:5], 0, v[114:115]
	v_cvt_pk_bf16_f32 v4, v10, v11
	v_cvt_pk_bf16_f32 v5, v34, v12
	v_cvt_pk_bf16_f32 v6, v21, v3
	v_cvt_pk_bf16_f32 v7, v14, v7
	flat_store_dwordx4 v[8:9], v[4:7] sc1
	s_nop 1
	v_cvt_pk_bf16_f32 v4, v0, v32
	v_cvt_pk_bf16_f32 v5, v22, v13
	v_cvt_pk_bf16_f32 v6, v2, v33
	v_cvt_pk_bf16_f32 v7, v15, v16
	flat_store_dwordx4 v[8:9], v[4:7] offset:64 sc1
	s_andn2_b64 vcc, exec, s[4:5]
	s_mov_b64 s[4:5], -1
	s_cbranch_vccnz .LBB0_538

.LBB0_611:
	s_or_b64 exec, exec, s[2:3]
	s_waitcnt lgkmcnt(0)
	ds_read_b128 v[10:13], v146
	v_add_co_u32_e32 v8, vcc, 0x10000, v8
	s_nop 1
	v_addc_co_u32_e32 v9, vcc, 0, v9, vcc
	s_waitcnt lgkmcnt(0)
	flat_store_dwordx4 v[8:9], v[10:13] sc1
	ds_read_b128 v[8:11], v20
	v_add_co_u32_e32 v6, vcc, 0x10000, v6
	s_nop 1
	v_addc_co_u32_e32 v7, vcc, 0, v7, vcc
	s_waitcnt lgkmcnt(0)
	flat_store_dwordx4 v[6:7], v[8:11] sc1
	ds_read_b128 v[6:9], v19
	v_add_co_u32_e32 v2, vcc, 0x10000, v2
	s_nop 1
	v_addc_co_u32_e32 v3, vcc, 0, v3, vcc
	s_waitcnt lgkmcnt(0)
	flat_store_dwordx4 v[2:3], v[6:9] sc1
	ds_read_b128 v[6:9], v18
	v_add_co_u32_e32 v2, vcc, 0x10000, v4
	s_nop 1
	v_addc_co_u32_e32 v3, vcc, 0, v5, vcc
	s_waitcnt lgkmcnt(0)
	flat_store_dwordx4 v[2:3], v[6:9] sc1
	s_waitcnt lgkmcnt(0)
	s_setprio 0
	s_waitcnt lgkmcnt(0)
	s_barrier

.LBB0_731:
	s_or_b64 exec, exec, s[2:3]
	v_readlane_b32 s0, v252, 51
	s_waitcnt lgkmcnt(0)
	s_add_u32 s0, s0, s76
	v_readlane_b32 s1, v252, 54
	v_lshlrev_b32_e32 v0, 4, v190
	ds_read_b128 v[10:13], v188
	s_addc_u32 s1, s1, s77
	v_and_b32_e32 v0, 0xf0, v0
	v_lshl_add_u64 v[22:23], s[0:1], 0, v[0:1]
	v_lshlrev_b32_e32 v0, 8, v189
	v_and_b32_e32 v0, 0x3000, v0
	v_lshl_add_u64 v[16:17], v[22:23], 0, v[0:1]
	v_or_b32_e32 v0, 64, v189
	s_waitcnt lgkmcnt(0)
	flat_store_dwordx4 v[16:17], v[10:13] sc1
	v_rcp_f32_e32 v6, v6
	s_nop 0
	v_lshlrev_b32_e32 v10, 4, v0
	v_add_u32_e32 v20, s70, v10
	ds_read_b128 v[10:13], v20
	v_lshlrev_b32_e32 v0, 8, v0
	v_and_b32_e32 v0, 0x7000, v0
	v_lshl_add_u64 v[14:15], v[22:23], 0, v[0:1]
	v_or_b32_e32 v0, 0x80, v189
	s_waitcnt lgkmcnt(0)
	flat_store_dwordx4 v[14:15], v[10:13] sc1
	s_nop 1
	v_lshlrev_b32_e32 v10, 4, v0
	v_add_u32_e32 v19, s70, v10
	ds_read_b128 v[32:35], v19
	v_lshlrev_b32_e32 v0, 8, v0
	v_and_b32_e32 v0, 0xb000, v0
	v_lshl_add_u64 v[10:11], v[22:23], 0, v[0:1]
	v_or_b32_e32 v0, 0xc0, v189
	v_lshlrev_b32_e32 v12, 4, v0
	s_waitcnt lgkmcnt(0)
	flat_store_dwordx4 v[10:11], v[32:35] sc1
	v_add_u32_e32 v18, s70, v12
	ds_read_b128 v[32:35], v18
	v_lshlrev_b32_e32 v0, 8, v0
	v_and_b32_e32 v0, 0xf000, v0
	v_lshl_add_u64 v[12:13], v[22:23], 0, v[0:1]
	v_mul_f32_e32 v0, v72, v6
	s_waitcnt lgkmcnt(0)
	flat_store_dwordx4 v[12:13], v[32:35] sc1
	s_waitcnt lgkmcnt(0)
	v_mov_b32_dpp v21, v0 quad_perm:[1,0,3,2] row_mask:0xf bank_mask:0xf bound_ctrl:1
	s_and_saveexec_b64 s[2:3], vcc
	s_cbranch_execz .LBB0_733
	v_cvt_pk_bf16_f32 v0, v0, v21
	ds_write_b32 v80, v0

.LBB0_795:
	s_or_b64 exec, exec, s[2:3]
	s_waitcnt lgkmcnt(0)
	ds_read_b128 v[2:5], v188
	v_add_co_u32_e32 v6, vcc, 0x10000, v16
	s_nop 1
	v_addc_co_u32_e32 v7, vcc, 0, v17, vcc
	s_waitcnt lgkmcnt(0)
	flat_store_dwordx4 v[6:7], v[2:5] sc1
	ds_read_b128 v[2:5], v20
	v_add_co_u32_e32 v6, vcc, 0x10000, v14
	s_nop 1
	v_addc_co_u32_e32 v7, vcc, 0, v15, vcc
	s_waitcnt lgkmcnt(0)
	flat_store_dwordx4 v[6:7], v[2:5] sc1
	ds_read_b128 v[2:5], v19
	v_add_co_u32_e32 v6, vcc, 0x10000, v10
	s_nop 1
	v_addc_co_u32_e32 v7, vcc, 0, v11, vcc
	s_waitcnt lgkmcnt(0)
	flat_store_dwordx4 v[6:7], v[2:5] sc1
	ds_read_b128 v[2:5], v18
	v_add_co_u32_e32 v6, vcc, 0x10000, v12
	s_nop 1
	v_addc_co_u32_e32 v7, vcc, 0, v13, vcc
	s_waitcnt lgkmcnt(0)
	flat_store_dwordx4 v[6:7], v[2:5] sc1
	s_waitcnt lgkmcnt(0)
	s_setprio 0
	s_mov_b64 s[2:3], 0
	s_waitcnt lgkmcnt(0)
	s_barrier

.LBB0_914:
	s_or_b64 exec, exec, s[2:3]
	v_readlane_b32 s0, v252, 51
	s_waitcnt lgkmcnt(0)
	s_add_u32 s0, s0, s66
	v_readlane_b32 s1, v252, 54
	v_lshlrev_b32_e32 v0, 4, v147
	ds_read_b128 v[2:5], v146
	s_addc_u32 s1, s1, s67
	v_and_b32_e32 v0, 0xf0, v0
	v_lshl_add_u64 v[34:35], s[0:1], 0, v[0:1]
	v_lshlrev_b32_e32 v0, 8, v148
	v_and_b32_e32 v0, 0x3000, v0
	v_lshl_add_u64 v[8:9], v[34:35], 0, v[0:1]
	v_or_b32_e32 v0, 64, v148
	s_waitcnt lgkmcnt(0)
	flat_store_dwordx4 v[8:9], v[2:5] sc1
	v_rcp_f32_e32 v21, v70
	s_nop 0
	v_lshlrev_b32_e32 v2, 4, v0
	v_add_u32_e32 v20, s70, v2
	ds_read_b128 v[2:5], v20
	v_lshlrev_b32_e32 v0, 8, v0
	v_and_b32_e32 v0, 0x7000, v0
	v_lshl_add_u64 v[6:7], v[34:35], 0, v[0:1]
	v_or_b32_e32 v0, 0x80, v148
	s_waitcnt lgkmcnt(0)
	flat_store_dwordx4 v[6:7], v[2:5] sc1
	s_nop 1
	v_lshlrev_b32_e32 v2, 4, v0
	v_add_u32_e32 v19, s70, v2
	ds_read_b128 v[22:25], v19
	v_lshlrev_b32_e32 v0, 8, v0
	v_and_b32_e32 v0, 0xb000, v0
	v_lshl_add_u64 v[2:3], v[34:35], 0, v[0:1]
	v_or_b32_e32 v0, 0xc0, v148
	v_lshlrev_b32_e32 v4, 4, v0
	s_waitcnt lgkmcnt(0)
	flat_store_dwordx4 v[2:3], v[22:25] sc1
	v_add_u32_e32 v18, s70, v4
	ds_read_b128 v[22:25], v18
	v_lshlrev_b32_e32 v0, 8, v0
	v_and_b32_e32 v0, 0xf000, v0
	v_lshl_add_u64 v[4:5], v[34:35], 0, v[0:1]
	v_mul_f32_e32 v0, v58, v21
	s_waitcnt lgkmcnt(0)
	flat_store_dwordx4 v[4:5], v[22:25] sc1
	s_waitcnt lgkmcnt(0)
	s_nop 1
	v_mov_b32_dpp v22, v0 quad_perm:[1,0,3,2] row_mask:0xf bank_mask:0xf bound_ctrl:1
	s_and_saveexec_b64 s[2:3], vcc
	s_cbranch_execz .LBB0_916
	v_cvt_pk_bf16_f32 v0, v0, v22
	ds_write_b32 v78, v0

.LBB0_1379:
	global_load_dwordx2 v[36:37], v34, s[0:1]
	global_load_dwordx2 v[38:39], v34, s[0:1] offset:512
	global_load_dwordx2 v[40:41], v34, s[0:1] offset:1024
	global_load_dwordx2 v[42:43], v34, s[0:1] offset:1536
	global_load_dwordx2 v[44:45], v34, s[0:1] offset:2048
	global_load_dwordx2 v[46:47], v34, s[0:1] offset:2560
	global_load_dwordx2 v[48:49], v34, s[0:1] offset:3072
	global_load_dwordx2 v[50:51], v34, s[0:1] offset:3584
	v_lshl_add_u64 v[52:53], s[4:5], 0, v[32:33]
	v_add_co_u32_e32 v68, vcc, s8, v52
	s_add_i32 s34, s34, s36
	s_nop 0
	v_addc_co_u32_e32 v69, vcc, 0, v53, vcc
	s_add_u32 s0, s0, s2
	s_addc_u32 s1, s1, s3
	s_waitcnt vmcnt(7)
	v_lshlrev_b32_e32 v52, 16, v36
	v_and_b32_e32 v53, 0xffff0000, v36
	v_lshlrev_b32_e32 v36, 16, v37
	v_and_b32_e32 v37, 0xffff0000, v37
	s_waitcnt vmcnt(6)
	v_lshlrev_b32_e32 v54, 16, v38
	v_and_b32_e32 v55, 0xffff0000, v38
	v_lshlrev_b32_e32 v38, 16, v39
	v_and_b32_e32 v39, 0xffff0000, v39
	s_waitcnt vmcnt(5)
	v_lshlrev_b32_e32 v56, 16, v40
	v_and_b32_e32 v57, 0xffff0000, v40
	v_lshlrev_b32_e32 v40, 16, v41
	v_and_b32_e32 v41, 0xffff0000, v41
	v_mul_f32_e32 v70, v53, v53
	v_mul_f32_e32 v71, v37, v37
	v_mul_f32_e32 v72, v55, v55
	v_mul_f32_e32 v73, v39, v39
	s_waitcnt vmcnt(4)
	v_lshlrev_b32_e32 v58, 16, v42
	v_and_b32_e32 v59, 0xffff0000, v42
	v_lshlrev_b32_e32 v42, 16, v43
	v_and_b32_e32 v43, 0xffff0000, v43
	v_mul_f32_e32 v74, v57, v57
	v_mul_f32_e32 v75, v41, v41
	v_fmac_f32_e32 v70, v52, v52
	v_fmac_f32_e32 v71, v36, v36
	v_fmac_f32_e32 v72, v54, v54
	v_fmac_f32_e32 v73, v38, v38
	s_waitcnt vmcnt(3)
	v_lshlrev_b32_e32 v60, 16, v44
	v_and_b32_e32 v61, 0xffff0000, v44
	v_lshlrev_b32_e32 v44, 16, v45
	v_and_b32_e32 v45, 0xffff0000, v45
	v_mul_f32_e32 v76, v59, v59
	v_mul_f32_e32 v77, v43, v43
	v_fmac_f32_e32 v74, v56, v56
	v_fmac_f32_e32 v75, v40, v40
	v_add_f32_e32 v70, v70, v71
	v_add_f32_e32 v71, v72, v73
	s_waitcnt vmcnt(2)
	v_lshlrev_b32_e32 v62, 16, v46
	v_and_b32_e32 v63, 0xffff0000, v46
	v_lshlrev_b32_e32 v46, 16, v47
	v_and_b32_e32 v47, 0xffff0000, v47
	v_mul_f32_e32 v78, v61, v61
	v_mul_f32_e32 v79, v45, v45
	v_fmac_f32_e32 v76, v58, v58
	v_fmac_f32_e32 v77, v42, v42
	v_add_f32_e32 v72, v74, v75
	v_add_f32_e32 v70, v70, v71
	s_waitcnt vmcnt(1)
	v_lshlrev_b32_e32 v64, 16, v48
	v_and_b32_e32 v65, 0xffff0000, v48
	v_lshlrev_b32_e32 v48, 16, v49
	v_and_b32_e32 v49, 0xffff0000, v49
	v_mul_f32_e32 v80, v63, v63
	v_mul_f32_e32 v81, v47, v47
	v_fmac_f32_e32 v78, v60, v60
	v_fmac_f32_e32 v79, v44, v44
	v_add_f32_e32 v73, v76, v77
	v_add_f32_e32 v70, v70, v72
	s_waitcnt vmcnt(0)
	v_lshlrev_b32_e32 v66, 16, v50
	v_and_b32_e32 v67, 0xffff0000, v50
	v_lshlrev_b32_e32 v50, 16, v51
	v_and_b32_e32 v51, 0xffff0000, v51
	v_mul_f32_e32 v82, v65, v65
	v_mul_f32_e32 v83, v49, v49
	v_fmac_f32_e32 v80, v62, v62
	v_fmac_f32_e32 v81, v46, v46
	v_add_f32_e32 v74, v78, v79
	v_add_f32_e32 v70, v70, v73
	v_mul_f32_e32 v84, v67, v67
	v_mul_f32_e32 v85, v51, v51
	v_fmac_f32_e32 v82, v64, v64
	v_fmac_f32_e32 v83, v48, v48
	v_add_f32_e32 v75, v80, v81
	v_add_f32_e32 v70, v70, v74
	v_fmac_f32_e32 v84, v66, v66
	v_fmac_f32_e32 v85, v50, v50
	v_add_f32_e32 v76, v82, v83
	v_add_f32_e32 v70, v70, v75
	v_add_f32_e32 v77, v84, v85
	v_add_f32_e32 v70, v70, v76
	v_add_f32_e32 v70, v70, v77
	s_nop 1
	v_add_f32_dpp v70, v70, v70 quad_perm:[1,0,3,2] row_mask:0xf bank_mask:0xf bound_ctrl:1
	s_nop 1
	v_add_f32_dpp v70, v70, v70 quad_perm:[2,3,0,1] row_mask:0xf bank_mask:0xf bound_ctrl:1
	s_nop 1
	v_add_f32_dpp v70, v70, v70 row_half_mirror row_mask:0xf bank_mask:0xf bound_ctrl:1
	s_nop 1
	v_add_f32_dpp v70, v70, v70 row_mirror row_mask:0xf bank_mask:0xf bound_ctrl:1
	ds_swizzle_b32 v71, v70 offset:swizzle(SWAP,16)
	s_waitcnt lgkmcnt(0)
	v_add_f32_e32 v70, v70, v71
	v_mov_b32_e32 v71, v70
	s_nop 1
	v_permlane32_swap_b32_e32 v70, v71
	v_add_f32_e32 v70, v70, v71
	v_fmamk_f32 v70, v70, 0x3a000000, v35
	v_mul_f32_e32 v71, 0x4b800000, v70
	v_cmp_gt_f32_e32 vcc, s9, v70
	s_nop 1
	v_cndmask_b32_e32 v70, v70, v71, vcc
	v_rsq_f32_e32 v70, v70
	s_nop 0
	v_mul_f32_e32 v71, 0x45800000, v70
	v_cndmask_b32_e32 v70, v70, v71, vcc
	v_pk_mul_f32 v[52:53], v[52:53], v[70:71] op_sel_hi:[1,0]
	v_pk_mul_f32 v[36:37], v[36:37], v[70:71] op_sel_hi:[1,0]
	v_pk_mul_f32 v[54:55], v[54:55], v[70:71] op_sel_hi:[1,0]
	v_pk_mul_f32 v[72:73], v[38:39], v[70:71] op_sel_hi:[1,0]
	v_pk_mul_f32 v[56:57], v[56:57], v[70:71] op_sel_hi:[1,0]
	v_pk_mul_f32 v[74:75], v[40:41], v[70:71] op_sel_hi:[1,0]
	v_pk_mul_f32 v[58:59], v[58:59], v[70:71] op_sel_hi:[1,0]
	v_pk_mul_f32 v[76:77], v[42:43], v[70:71] op_sel_hi:[1,0]
	v_pk_mul_f32 v[60:61], v[60:61], v[70:71] op_sel_hi:[1,0]
	v_pk_mul_f32 v[78:79], v[44:45], v[70:71] op_sel_hi:[1,0]
	v_pk_mul_f32 v[62:63], v[62:63], v[70:71] op_sel_hi:[1,0]
	v_pk_mul_f32 v[80:81], v[46:47], v[70:71] op_sel_hi:[1,0]
	v_pk_mul_f32 v[64:65], v[64:65], v[70:71] op_sel_hi:[1,0]
	v_pk_mul_f32 v[82:83], v[48:49], v[70:71] op_sel_hi:[1,0]
	v_pk_mul_f32 v[38:39], v[2:3], v[36:37]
	v_pk_mul_f32 v[36:37], v[0:1], v[52:53]
	v_pk_mul_f32 v[84:85], v[66:67], v[70:71] op_sel_hi:[1,0]
	v_pk_mul_f32 v[66:67], v[50:51], v[70:71] op_sel_hi:[1,0]
	v_pk_mul_f32 v[42:43], v[6:7], v[72:73]
	v_pk_mul_f32 v[40:41], v[4:5], v[54:55]
	v_pk_mul_f32 v[46:47], v[10:11], v[74:75]
	v_pk_mul_f32 v[44:45], v[8:9], v[56:57]
	v_pk_mul_f32 v[50:51], v[14:15], v[76:77]
	v_pk_mul_f32 v[48:49], v[12:13], v[58:59]
	v_pk_mul_f32 v[54:55], v[18:19], v[78:79]
	v_pk_mul_f32 v[52:53], v[16:17], v[60:61]
	v_pk_mul_f32 v[58:59], v[22:23], v[80:81]
	v_pk_mul_f32 v[56:57], v[20:21], v[62:63]
	v_pk_mul_f32 v[62:63], v[26:27], v[82:83]
	v_pk_mul_f32 v[60:61], v[24:25], v[64:65]
	global_store_dwordx4 v32, v[36:39], s[4:5] sc1
	global_store_dwordx4 v32, v[40:43], s[4:5] offset:1024 sc1
	global_store_dwordx4 v32, v[44:47], s[4:5] offset:2048 sc1
	global_store_dwordx4 v32, v[48:51], s[4:5] offset:3072 sc1
	global_store_dwordx4 v[68:69], v[52:55], off sc1
	global_store_dwordx4 v[68:69], v[56:59], off offset:1024 sc1
	global_store_dwordx4 v[68:69], v[60:63], off offset:2048 sc1
	s_add_u32 s4, s4, s6
	s_addc_u32 s5, s5, s7
	v_pk_mul_f32 v[66:67], v[30:31], v[66:67]
	v_pk_mul_f32 v[64:65], v[28:29], v[84:85]
	s_cmpk_lt_i32 s34, 0x4000
	global_store_dwordx4 v[68:69], v[64:67], off offset:3072 sc1
	s_cbranch_scc1 .LBB0_1379
